# E48: all remaining plain stores in the 7 GEMM phases made write-through (sc1); the XCD leader's buffer_wbl2 dropped at the 7 grid barriers that follow those phases; on E41
# baseline (speedup 1.0000x reference)
.LBB0_167:
	v_lshlrev_b32_e32 v34, 14, v172
	v_lshlrev_b32_e32 v35, 12, v136
	v_add3_u32 v34, v165, v34, v35
	s_barrier
	s_nop 4
	ds_write2st64_b32 v34, v2, v3 offset1:1
	ds_write2st64_b32 v34, v4, v5 offset0:2 offset1:3
	ds_write2st64_b32 v34, v6, v7 offset0:4 offset1:5
	ds_write2st64_b32 v34, v8, v9 offset0:6 offset1:7
	ds_write2st64_b32 v34, v10, v11 offset0:8 offset1:9
	ds_write2st64_b32 v34, v12, v13 offset0:10 offset1:11
	ds_write2st64_b32 v34, v14, v15 offset0:12 offset1:13
	ds_write2st64_b32 v34, v16, v17 offset0:14 offset1:15
	ds_write2st64_b32 v34, v18, v19 offset0:16 offset1:17
	ds_write2st64_b32 v34, v20, v21 offset0:18 offset1:19
	ds_write2st64_b32 v34, v22, v23 offset0:20 offset1:21
	ds_write2st64_b32 v34, v24, v25 offset0:22 offset1:23
	ds_write2st64_b32 v34, v26, v27 offset0:24 offset1:25
	ds_write2st64_b32 v34, v28, v29 offset0:26 offset1:27
	ds_write2st64_b32 v34, v30, v31 offset0:28 offset1:29
	ds_write2st64_b32 v34, v32, v33 offset0:30 offset1:31
	v_lshrrev_b32_e32 v3, 3, v170
	v_lshlrev_b32_e32 v2, 3, v171
	v_and_b32_e32 v3, 0xfffff0, v3
	v_and_or_b32 v2, v2, 8, v3
	v_lshl_add_u32 v32, v2, 8, v165
	s_waitcnt lgkmcnt(0)
	s_barrier
	ds_read2st64_b32 v[2:3], v32 offset1:1
	ds_read2st64_b32 v[4:5], v32 offset0:2 offset1:3
	ds_read2st64_b32 v[6:7], v32 offset0:4 offset1:5
	ds_read2st64_b32 v[8:9], v32 offset0:6 offset1:7
	ds_read2st64_b32 v[10:11], v32 offset0:64 offset1:65
	ds_read2st64_b32 v[12:13], v32 offset0:66 offset1:67
	ds_read2st64_b32 v[14:15], v32 offset0:68 offset1:69
	ds_read2st64_b32 v[16:17], v32 offset0:70 offset1:71
	ds_read2st64_b32 v[18:19], v32 offset0:128 offset1:129
	ds_read2st64_b32 v[20:21], v32 offset0:130 offset1:131
	ds_read2st64_b32 v[22:23], v32 offset0:132 offset1:133
	ds_read2st64_b32 v[24:25], v32 offset0:134 offset1:135
	ds_read2st64_b32 v[26:27], v32 offset0:192 offset1:193
	ds_read2st64_b32 v[28:29], v32 offset0:194 offset1:195
	ds_read2st64_b32 v[30:31], v32 offset0:196 offset1:197
	ds_read2st64_b32 v[32:33], v32 offset0:198 offset1:199
	s_and_b32 s0, s0, 0x1e0
	s_cmp_lt_u32 s90, 16
	s_waitcnt lgkmcnt(14)
	v_pk_add_f32 v[2:3], v[2:3], 0 op_sel_hi:[1,0]
	v_pk_add_f32 v[4:5], v[4:5], 0 op_sel_hi:[1,0]
	s_cselect_b64 s[36:37], -1, 0
	s_waitcnt lgkmcnt(11)
	v_pk_add_f32 v[2:3], v[2:3], v[10:11]
	s_waitcnt lgkmcnt(10)
	v_pk_add_f32 v[4:5], v[4:5], v[12:13]
	v_cndmask_b32_e64 v34, v169, 1.0, s[36:37]
	s_and_b64 s[36:37], s[36:37], exec
	s_waitcnt lgkmcnt(7)
	v_pk_add_f32 v[2:3], v[2:3], v[18:19]
	s_waitcnt lgkmcnt(6)
	v_pk_add_f32 v[4:5], v[4:5], v[20:21]
	v_or_b32_e32 v35, s0, v167
	s_cselect_b32 s37, s17, s19
	s_cselect_b32 s36, s16, s18
	s_waitcnt lgkmcnt(3)
	v_pk_add_f32 v[2:3], v[2:3], v[26:27]
	s_waitcnt lgkmcnt(2)
	v_pk_add_f32 v[4:5], v[4:5], v[28:29]
	v_lshl_add_u64 v[36:37], s[36:37], 0, v[130:131]
	v_pk_mul_f32 v[2:3], v[34:35], v[2:3] op_sel_hi:[0,1]
	v_pk_mul_f32 v[4:5], v[34:35], v[4:5] op_sel_hi:[0,1]
	v_lshlrev_b32_e32 v134, 1, v35
	v_cvt_pk_bf16_f32 v2, v2, v3
	v_cvt_pk_bf16_f32 v3, v4, v5
	v_lshl_add_u64 v[4:5], v[36:37], 0, v[134:135]
	s_waitcnt lgkmcnt(0)
	s_barrier
	global_store_dwordx2 v[4:5], v[2:3], off sc1
	v_pk_add_f32 v[2:3], v[6:7], 0 op_sel_hi:[1,0]
	v_pk_add_f32 v[6:7], v[8:9], 0 op_sel_hi:[1,0]
	v_pk_add_f32 v[2:3], v[2:3], v[14:15]
	v_pk_add_f32 v[6:7], v[6:7], v[16:17]
	v_pk_add_f32 v[2:3], v[2:3], v[22:23]
	v_pk_add_f32 v[6:7], v[6:7], v[24:25]
	v_pk_add_f32 v[2:3], v[2:3], v[30:31]
	v_pk_add_f32 v[6:7], v[6:7], v[32:33]
	v_pk_mul_f32 v[2:3], v[34:35], v[2:3] op_sel_hi:[0,1]
	v_pk_mul_f32 v[6:7], v[34:35], v[6:7] op_sel_hi:[0,1]
	v_cvt_pk_bf16_f32 v2, v2, v3
	v_cvt_pk_bf16_f32 v3, v6, v7
	global_store_dwordx2 v[4:5], v[2:3], off offset:16 sc1

.LBB0_176:
	v_lshlrev_b32_e32 v34, 14, v170
	v_lshlrev_b32_e32 v35, 12, v171
	v_add3_u32 v34, v165, v34, v35
	s_barrier
	s_nop 4
	ds_write2st64_b32 v34, v2, v3 offset1:1
	ds_write2st64_b32 v34, v4, v5 offset0:2 offset1:3
	ds_write2st64_b32 v34, v6, v7 offset0:4 offset1:5
	ds_write2st64_b32 v34, v8, v9 offset0:6 offset1:7
	ds_write2st64_b32 v34, v10, v11 offset0:8 offset1:9
	ds_write2st64_b32 v34, v12, v13 offset0:10 offset1:11
	ds_write2st64_b32 v34, v14, v15 offset0:12 offset1:13
	ds_write2st64_b32 v34, v16, v17 offset0:14 offset1:15
	ds_write2st64_b32 v34, v18, v19 offset0:16 offset1:17
	ds_write2st64_b32 v34, v20, v21 offset0:18 offset1:19
	ds_write2st64_b32 v34, v22, v23 offset0:20 offset1:21
	ds_write2st64_b32 v34, v24, v25 offset0:22 offset1:23
	ds_write2st64_b32 v34, v26, v27 offset0:24 offset1:25
	ds_write2st64_b32 v34, v28, v29 offset0:26 offset1:27
	ds_write2st64_b32 v34, v30, v31 offset0:28 offset1:29
	ds_write2st64_b32 v34, v32, v33 offset0:30 offset1:31
	v_lshrrev_b32_e32 v3, 3, v160
	v_lshlrev_b32_e32 v2, 3, v161
	v_and_b32_e32 v3, 0xfffff0, v3
	v_and_or_b32 v2, v2, 8, v3
	v_lshl_add_u32 v28, v2, 8, v165
	s_waitcnt lgkmcnt(0)
	s_barrier
	ds_read2st64_b32 v[2:3], v28 offset1:1
	ds_read2st64_b32 v[4:5], v28 offset0:64 offset1:65
	ds_read2st64_b32 v[6:7], v28 offset0:128 offset1:129
	ds_read2st64_b32 v[8:9], v28 offset0:192 offset1:193
	ds_read2st64_b32 v[10:11], v28 offset0:2 offset1:3
	ds_read2st64_b32 v[12:13], v28 offset0:4 offset1:5
	ds_read2st64_b32 v[14:15], v28 offset0:6 offset1:7
	s_waitcnt lgkmcnt(6)
	v_pk_add_f32 v[2:3], v[2:3], 0 op_sel_hi:[1,0]
	s_lshl_b32 s38, s65, 2
	s_waitcnt lgkmcnt(5)
	v_pk_add_f32 v[2:3], v[2:3], v[4:5]
	s_and_b32 s38, s38, 0x380
	s_waitcnt lgkmcnt(4)
	v_pk_add_f32 v[2:3], v[2:3], v[6:7]
	ds_read2st64_b32 v[16:17], v28 offset0:66 offset1:67
	ds_read2st64_b32 v[18:19], v28 offset0:68 offset1:69
	ds_read2st64_b32 v[20:21], v28 offset0:70 offset1:71
	s_waitcnt lgkmcnt(6)
	v_pk_add_f32 v[2:3], v[2:3], v[8:9]
	s_waitcnt lgkmcnt(5)
	v_pk_add_f32 v[8:9], v[10:11], 0 op_sel_hi:[1,0]
	v_add_u32_e32 v10, s38, v166
	s_lshl_b64 s[38:39], s[0:1], 21
	s_cmpk_lt_u32 s64, 0x200
	s_mov_b32 s0, 0x81db000
	s_cselect_b32 s0, s0, 0x85db000
	ds_read2st64_b32 v[4:5], v28 offset0:130 offset1:131
	ds_read2st64_b32 v[22:23], v28 offset0:132 offset1:133
	ds_read2st64_b32 v[24:25], v28 offset0:134 offset1:135
	s_add_u32 s0, s80, s0
	ds_read2st64_b32 v[6:7], v28 offset0:194 offset1:195
	ds_read2st64_b32 v[26:27], v28 offset0:196 offset1:197
	ds_read2st64_b32 v[28:29], v28 offset0:198 offset1:199
	s_addc_u32 s65, s81, 0
	s_waitcnt lgkmcnt(8)
	v_pk_add_f32 v[8:9], v[8:9], v[16:17]
	v_ashrrev_i32_e32 v11, 31, v10
	s_add_u32 s38, s0, s38
	s_waitcnt lgkmcnt(5)
	v_pk_add_f32 v[4:5], v[8:9], v[4:5]
	v_pk_add_f32 v[8:9], v[14:15], 0 op_sel_hi:[1,0]
	v_lshlrev_b64 v[10:11], 11, v[10:11]
	s_addc_u32 s39, s65, s39
	v_bitop3_b32 v14, s64, v168, v167 bitop3:0xc8
	s_lshl_b64 s[36:37], s[36:37], 1
	s_waitcnt lgkmcnt(2)
	v_pk_add_f32 v[4:5], v[4:5], v[6:7]
	v_pk_add_f32 v[6:7], v[12:13], 0 op_sel_hi:[1,0]
	v_lshl_add_u64 v[12:13], s[38:39], 0, v[10:11]
	v_lshlrev_b32_e32 v134, 2, v14
	s_add_u32 s36, s41, s36
	v_or_b32_e32 v16, s64, v167
	v_lshl_add_u64 v[14:15], v[12:13], 0, v[134:135]
	s_addc_u32 s37, s42, s37
	s_waitcnt lgkmcnt(0)
	s_barrier
	global_store_dwordx4 v[14:15], v[2:5], off sc1
	v_lshlrev_b32_e32 v134, 1, v16
	s_movk_i32 s0, 0x1fc
	v_cvt_pk_bf16_f32 v2, v2, v3
	v_cvt_pk_bf16_f32 v3, v4, v5
	v_lshl_add_u64 v[4:5], s[36:37], 0, v[10:11]
	v_lshl_add_u64 v[4:5], v[4:5], 0, v[134:135]
	v_pk_add_f32 v[6:7], v[6:7], v[18:19]
	v_pk_add_f32 v[8:9], v[8:9], v[20:21]
	global_store_dwordx2 v[4:5], v[2:3], off sc1
	v_bitop3_b32 v2, v16, s0, 8 bitop3:0xc8
	v_pk_add_f32 v[6:7], v[6:7], v[22:23]
	v_pk_add_f32 v[8:9], v[8:9], v[24:25]
	v_lshlrev_b32_e32 v134, 2, v2
	v_pk_add_f32 v[6:7], v[6:7], v[26:27]
	v_pk_add_f32 v[8:9], v[8:9], v[28:29]
	v_lshl_add_u64 v[2:3], v[12:13], 0, v[134:135]
	global_store_dwordx4 v[2:3], v[6:9], off sc1
	v_cvt_pk_bf16_f32 v2, v6, v7
	v_cvt_pk_bf16_f32 v3, v8, v9
	s_mov_b64 s[36:37], 0
	global_store_dwordx2 v[4:5], v[2:3], off offset:16 sc1

.LBB0_289:
	s_andn2_saveexec_b64 s[16:17], s[16:17]
	s_cbranch_execz .LBB0_309
	s_mov_b64 s[16:17], exec
	s_waitcnt lgkmcnt(0)
	s_waitcnt vmcnt(0)
	v_mbcnt_lo_u32_b32 v3, s16, 0
	v_mbcnt_hi_u32_b32 v3, s17, v3
	v_cmp_eq_u32_e32 vcc, 0, v3
	s_and_saveexec_b64 s[18:19], vcc
	s_cbranch_execz .LBB0_292
	s_bcnt1_i32_b64 s3, s[16:17]
	v_mov_b32_e32 v4, 0x43000
	v_mov_b32_e32 v5, s3
	global_atomic_add v4, v4, v5, s[82:83] offset:1024 sc0

.LBB0_656:
	s_or_b64 exec, exec, s[34:35]
	v_lshl_add_u32 v12, s46, 6, v217
	v_ashrrev_i32_e32 v13, 2, v12
	v_and_or_b32 v24, v13, s43, v212
	v_lshrrev_b32_e32 v13, 2, v12
	v_and_or_b32 v13, v13, 16, s45
	v_or_b32_e32 v16, v13, v168
	v_ashrrev_i32_e32 v25, 31, v24
	v_readlane_b32 s64, v244, 7
	v_ashrrev_i32_e32 v17, 31, v16
	v_lshlrev_b64 v[26:27], 12, v[24:25]
	v_readlane_b32 s66, v244, 9
	v_readlane_b32 s67, v244, 10
	v_lshlrev_b64 v[28:29], 2, v[16:17]
	v_lshl_add_u64 v[30:31], s[52:53], 0, v[28:29]
	v_lshl_add_u64 v[20:21], s[66:67], 0, v[26:27]
	s_waitcnt lgkmcnt(0)
	s_barrier
	global_load_dwordx4 v[16:19], v[30:31], off
	v_lshl_add_u64 v[32:33], v[20:21], 0, v[28:29]
	global_load_dwordx4 v[20:23], v[32:33], off
	v_lshl_add_u32 v15, v24, 2, 0
	v_ashrrev_i32_e32 v24, 4, v13
	ds_read_b32 v13, v15 offset:1536
	v_ashrrev_i32_e32 v34, 7, v12
	v_ashrrev_i32_e32 v35, 31, v34
	v_ashrrev_i32_e32 v25, 31, v24
	v_lshl_add_u64 v[26:27], s[16:17], 0, v[26:27]
	s_waitcnt lgkmcnt(0)
	v_fmamk_f32 v13, v13, 0x3a800000, v170
	v_mul_f32_e32 v15, 0x4f800000, v13
	v_cmp_gt_f32_e32 vcc, s44, v13
	v_lshlrev_b64 v[34:35], 12, v[34:35]
	v_lshlrev_b64 v[24:25], 6, v[24:25]
	v_cndmask_b32_e32 v13, v13, v15, vcc
	v_sqrt_f32_e32 v15, v13
	v_lshl_add_u64 v[26:27], v[26:27], 0, v[28:29]
	v_lshl_add_u64 v[24:25], v[24:25], 0, v[34:35]
	v_or_b32_e32 v24, v24, v212
	v_add_u32_e32 v28, -1, v15
	v_add_u32_e32 v29, 1, v15
	v_fma_f32 v34, -v28, v15, v13
	v_fma_f32 v35, -v29, v15, v13
	v_cmp_ge_f32_e64 s[6:7], 0, v34
	v_lshl_add_u64 v[24:25], v[24:25], 4, v[134:135]
	v_readlane_b32 s65, v244, 8
	v_cndmask_b32_e64 v15, v15, v28, s[6:7]
	v_cmp_lt_f32_e64 s[6:7], 0, v35
	v_readlane_b32 s68, v244, 11
	v_readlane_b32 s69, v244, 12
	v_cndmask_b32_e64 v15, v15, v29, s[6:7]
	v_mul_f32_e32 v28, 0x37800000, v15
	v_cndmask_b32_e32 v15, v15, v28, vcc
	v_cmp_class_f32_e32 vcc, v13, v171
	v_readlane_b32 s70, v244, 13
	v_readlane_b32 s71, v244, 14
	v_cndmask_b32_e32 v13, v15, v13, vcc
	v_div_scale_f32 v15, s[6:7], v13, v13, 1.0
	v_rcp_f32_e32 v28, v15
	v_div_scale_f32 v29, vcc, 1.0, v13, 1.0
	v_readlane_b32 s72, v244, 15
	v_fma_f32 v34, -v15, v28, 1.0
	v_fmac_f32_e32 v28, v34, v28
	v_mul_f32_e32 v34, v29, v28
	v_fma_f32 v35, -v15, v34, v29
	v_fmac_f32_e32 v34, v35, v28
	v_fma_f32 v15, -v15, v34, v29
	v_div_fmas_f32 v15, v15, v28, v34
	v_div_fixup_f32 v28, v15, v13, 1.0
	v_readlane_b32 s73, v244, 16
	v_readlane_b32 s74, v244, 17
	v_readlane_b32 s75, v244, 18
	v_readlane_b32 s76, v244, 19
	v_readlane_b32 s77, v244, 20
	v_readlane_b32 s78, v244, 21
	v_readlane_b32 s79, v244, 22
	s_waitcnt vmcnt(1)
	v_pk_mul_f32 v[10:11], v[10:11], v[18:19]
	v_pk_mul_f32 v[8:9], v[8:9], v[16:17]
	s_waitcnt vmcnt(0)
	v_pk_fma_f32 v[10:11], v[10:11], v[28:29], v[22:23] op_sel_hi:[1,0,1]
	v_pk_fma_f32 v[8:9], v[8:9], v[28:29], v[20:21] op_sel_hi:[1,0,1]
	v_cvt_pk_bf16_f32 v17, v10, v11
	v_cvt_pk_bf16_f32 v16, v8, v9
	global_store_dwordx4 v[26:27], v[8:11], off sc1
	global_store_dwordx2 v[24:25], v[16:17], off sc1
	global_load_dwordx4 v[16:19], v[30:31], off offset:32
	s_nop 0
	global_load_dwordx4 v[20:23], v[32:33], off offset:32
	v_mul_f32_e32 v9, v9, v9
	v_fmac_f32_e32 v9, v8, v8
	v_mul_f32_e32 v8, v11, v11
	v_fmac_f32_e32 v8, v10, v10
	v_add_f32_e32 v8, v9, v8
	s_waitcnt vmcnt(1)
	v_pk_mul_f32 v[6:7], v[6:7], v[18:19]
	v_pk_mul_f32 v[4:5], v[4:5], v[16:17]
	s_waitcnt vmcnt(0)
	v_pk_fma_f32 v[6:7], v[28:29], v[6:7], v[22:23] op_sel_hi:[0,1,1]
	v_pk_fma_f32 v[4:5], v[28:29], v[4:5], v[20:21] op_sel_hi:[0,1,1]
	v_cvt_pk_bf16_f32 v16, v4, v5
	v_cvt_pk_bf16_f32 v17, v6, v7
	global_store_dwordx4 v[26:27], v[4:7], off offset:32 sc1
	global_store_dwordx2 v[24:25], v[16:17], off offset:512 sc1
	s_barrier
	s_getreg_b32 s6, hwreg(HW_REG_HW_ID, 0, 6)
	s_and_b32 s6, s6, 63
	s_lshl_b32 s6, s6, 2
	s_add_i32 s6, s6, 0
	s_add_i32 s6, s6, 0x23e00
	v_mov_b32_e32 v16, s6
	v_mov_b32_e32 v17, s13
	flat_load_dword v13, v[16:17] sc0 sc1
	s_waitcnt vmcnt(0)
	v_mul_f32_e32 v5, v5, v5
	v_fmac_f32_e32 v5, v4, v4
	v_mul_f32_e32 v4, v7, v7
	v_fmac_f32_e32 v4, v6, v6
	v_add_f32_e32 v4, v5, v4
	v_add_f32_e32 v5, v8, v4
	ds_bpermute_b32 v6, v169, v5
	s_waitcnt lgkmcnt(0)
	v_readfirstlane_b32 s6, v13
	s_nop 1
	v_lshl_add_u32 v4, s6, 6, v217
	s_and_saveexec_b64 s[6:7], s[0:1]
	s_cbranch_execz .LBB0_658
	v_add_f32_e32 v5, v5, v6
	v_lshlrev_b32_e32 v6, 3, v4
	v_and_b32_e32 v6, 0x200, v6
	v_add_u32_e32 v6, 0, v6
	v_and_b32_e32 v7, 0xffffff80, v4
	v_add3_u32 v6, v6, v7, v14
	ds_write_b32 v6, v5

.LBB0_660:
	s_or_b64 exec, exec, s[6:7]
	v_cmp_gt_i32_e32 vcc, s42, v12
	s_waitcnt lgkmcnt(0)
	s_barrier
	s_and_saveexec_b64 s[6:7], vcc
	s_cbranch_execz .LBB0_633
	v_lshl_add_u32 v4, v12, 2, 0
	ds_read_b32 v6, v4 offset:1024
	v_lshl_add_u32 v4, v12, 5, s30
	v_ashrrev_i32_e32 v5, 31, v4
	v_lshl_add_u64 v[4:5], v[4:5], 2, s[54:55]
	s_waitcnt lgkmcnt(0)
	global_store_dword v[4:5], v6, off sc1
	s_branch .LBB0_633

.LBB0_713:
	s_or_b64 exec, exec, s[12:13]
	s_lshl_b32 s4, s33, 5
	s_lshl_b32 s5, s6, 8
	s_or_b32 s4, s5, s4
	v_add_u32_e32 v150, s3, v152
	v_and_or_b32 v148, v3, 24, s4
	v_ashrrev_i32_e32 v151, 31, v150
	v_ashrrev_i32_e32 v149, 31, v148
	s_waitcnt lgkmcnt(0)
	v_lshlrev_b64 v[132:133], 10, v[150:151]
	v_readlane_b32 s16, v244, 7
	s_waitcnt vmcnt(0) lgkmcnt(0)
	s_barrier
	v_lshl_add_u64 v[136:137], v[148:149], 2, s[52:53]
	v_lshl_add_u64 v[164:165], v[132:133], 0, v[148:149]
	v_readlane_b32 s17, v244, 8
	global_load_dwordx4 v[140:143], v[136:137], off offset:16
	global_load_dwordx4 v[144:147], v[136:137], off
	v_lshl_add_u64 v[166:167], v[164:165], 2, s[16:17]
	global_load_dwordx4 v[156:159], v[166:167], off nt
	global_load_dwordx4 v[160:163], v[166:167], off offset:16 nt
	v_lshl_add_u32 v3, v152, 2, 0
	ds_read_b32 v168, v3 offset:4096
	v_lshl_add_u64 v[164:165], v[164:165], 1, s[62:63]
	global_load_dwordx4 v[132:135], v[136:137], off offset:528
	s_nop 0
	global_load_dwordx4 v[136:139], v[136:137], off offset:512
	s_lshl_b32 s4, s6, 2
	s_ashr_i32 s5, s4, 31
	s_mov_b32 s11, 0
	v_readlane_b32 s18, v244, 9
	v_readlane_b32 s19, v244, 10
	v_readlane_b32 s20, v244, 11
	v_readlane_b32 s21, v244, 12
	v_readlane_b32 s22, v244, 13
	v_readlane_b32 s23, v244, 14
	v_readlane_b32 s24, v244, 15
	v_readlane_b32 s25, v244, 16
	v_readlane_b32 s26, v244, 17
	v_readlane_b32 s27, v244, 18
	v_readlane_b32 s28, v244, 19
	v_readlane_b32 s29, v244, 20
	v_readlane_b32 s30, v244, 21
	v_readlane_b32 s31, v244, 22
	s_waitcnt vmcnt(0)
	v_pk_mul_f32 v[126:127], v[126:127], v[142:143]
	v_pk_mul_f32 v[130:131], v[130:131], v[146:147]
	v_pk_mul_f32 v[128:129], v[128:129], v[144:145]
	v_pk_mul_f32 v[124:125], v[124:125], v[140:141]
	s_waitcnt lgkmcnt(0)
	v_pk_fma_f32 v[158:159], v[130:131], v[168:169], v[158:159] op_sel_hi:[1,0,1]
	v_pk_fma_f32 v[156:157], v[128:129], v[168:169], v[156:157] op_sel_hi:[1,0,1]
	v_pk_fma_f32 v[162:163], v[126:127], v[168:169], v[162:163] op_sel_hi:[1,0,1]
	v_pk_fma_f32 v[160:161], v[124:125], v[168:169], v[160:161] op_sel_hi:[1,0,1]
	v_cvt_pk_bf16_f32 v124, v156, v157
	v_cvt_pk_bf16_f32 v125, v158, v159
	v_pk_mul_f32 v[122:123], v[122:123], v[138:139]
	v_cvt_pk_bf16_f32 v126, v160, v161
	v_cvt_pk_bf16_f32 v127, v162, v163
	global_store_dwordx4 v[164:165], v[124:127], off sc1
	global_load_dwordx4 v[124:127], v[166:167], off offset:512 nt
	s_nop 0
	global_load_dwordx4 v[128:131], v[166:167], off offset:528 nt
	v_pk_mul_f32 v[120:121], v[120:121], v[136:137]
	v_pk_mul_f32 v[118:119], v[118:119], v[134:135]
	v_pk_mul_f32 v[116:117], v[116:117], v[132:133]
	v_mul_f32_e32 v155, v157, v157
	v_mul_f32_e32 v157, v159, v159
	v_mul_f32_e32 v159, v161, v161
	v_mul_f32_e32 v161, v163, v163
	v_fmac_f32_e32 v155, v156, v156
	v_fmac_f32_e32 v157, v158, v158
	v_fmac_f32_e32 v159, v160, v160
	v_fmac_f32_e32 v161, v162, v162
	v_add_f32_e32 v155, v155, v157
	v_add_f32_e32 v156, v159, v161
	v_add_f32_e32 v155, v155, v156
	s_waitcnt vmcnt(1)
	v_pk_fma_f32 v[122:123], v[122:123], v[168:169], v[126:127] op_sel_hi:[1,0,1]
	v_pk_fma_f32 v[120:121], v[120:121], v[168:169], v[124:125] op_sel_hi:[1,0,1]
	s_waitcnt vmcnt(0)
	v_pk_fma_f32 v[124:125], v[118:119], v[168:169], v[130:131] op_sel_hi:[1,0,1]
	v_pk_fma_f32 v[126:127], v[116:117], v[168:169], v[128:129] op_sel_hi:[1,0,1]
	v_mul_f32_e32 v116, v121, v121
	v_mul_f32_e32 v117, v123, v123
	v_mul_f32_e32 v118, v127, v127
	v_mul_f32_e32 v119, v125, v125
	v_fmac_f32_e32 v116, v120, v120
	v_fmac_f32_e32 v117, v122, v122
	v_fmac_f32_e32 v118, v126, v126
	v_fmac_f32_e32 v119, v124, v124
	v_add_f32_e32 v116, v116, v117
	v_add_f32_e32 v117, v118, v119
	v_add_f32_e32 v116, v116, v117
	v_add_f32_e32 v116, v155, v116
	ds_bpermute_b32 v117, v153, v116
	v_cvt_pk_bf16_f32 v118, v120, v121
	v_cvt_pk_bf16_f32 v119, v122, v123
	v_cvt_pk_bf16_f32 v120, v126, v127
	v_cvt_pk_bf16_f32 v121, v124, v125
	s_waitcnt lgkmcnt(0)
	v_add_f32_e32 v116, v116, v117
	ds_bpermute_b32 v117, v154, v116
	global_store_dwordx4 v[164:165], v[118:121], off offset:256 sc1
	s_and_saveexec_b64 s[6:7], s[0:1]
	s_cbranch_execz .LBB0_715
	s_waitcnt lgkmcnt(0)
	v_add_f32_e32 v118, v116, v117
	v_lshlrev_b64 v[116:117], 6, v[150:151]
	v_lshl_add_u64 v[116:117], s[86:87], 0, v[116:117]
	v_lshl_add_u64 v[116:117], s[4:5], 2, v[116:117]
	v_lshl_add_u64 v[116:117], v[116:117], 0, s[10:11]
	global_store_dword v[116:117], v118, off sc1
.LBB0_715:
	s_or_b64 exec, exec, s[6:7]
	v_add3_u32 v116, s3, v152, 16
	s_waitcnt lgkmcnt(0)
	v_ashrrev_i32_e32 v117, 31, v116
	v_lshlrev_b64 v[118:119], 10, v[116:117]
	v_readlane_b32 s16, v244, 7
	v_lshl_add_u64 v[126:127], v[118:119], 0, v[148:149]
	v_readlane_b32 s17, v244, 8
	v_pk_mul_f32 v[114:115], v[114:115], v[146:147]
	v_pk_mul_f32 v[112:113], v[112:113], v[144:145]
	v_lshl_add_u64 v[128:129], v[126:127], 2, s[16:17]
	global_load_dwordx4 v[118:121], v[128:129], off nt
	global_load_dwordx4 v[122:125], v[128:129], off offset:16 nt
	ds_read_b32 v130, v3 offset:4160
	v_pk_mul_f32 v[110:111], v[110:111], v[142:143]
	v_pk_mul_f32 v[108:109], v[108:109], v[140:141]
	v_lshl_add_u64 v[126:127], v[126:127], 1, s[62:63]
	v_pk_mul_f32 v[106:107], v[106:107], v[138:139]
	v_pk_mul_f32 v[104:105], v[104:105], v[136:137]
	v_pk_mul_f32 v[102:103], v[102:103], v[134:135]
	v_pk_mul_f32 v[100:101], v[100:101], v[132:133]
	v_readlane_b32 s18, v244, 9
	v_readlane_b32 s19, v244, 10
	v_readlane_b32 s20, v244, 11
	v_readlane_b32 s21, v244, 12
	v_readlane_b32 s22, v244, 13
	v_readlane_b32 s23, v244, 14
	v_readlane_b32 s24, v244, 15
	v_readlane_b32 s25, v244, 16
	v_readlane_b32 s26, v244, 17
	v_readlane_b32 s27, v244, 18
	v_readlane_b32 s28, v244, 19
	v_readlane_b32 s29, v244, 20
	v_readlane_b32 s30, v244, 21
	v_readlane_b32 s31, v244, 22
	s_waitcnt vmcnt(1) lgkmcnt(0)
	v_pk_fma_f32 v[120:121], v[114:115], v[130:131], v[120:121] op_sel_hi:[1,0,1]
	v_pk_fma_f32 v[118:119], v[112:113], v[130:131], v[118:119] op_sel_hi:[1,0,1]
	s_waitcnt vmcnt(0)
	v_pk_fma_f32 v[124:125], v[110:111], v[130:131], v[124:125] op_sel_hi:[1,0,1]
	v_pk_fma_f32 v[122:123], v[108:109], v[130:131], v[122:123] op_sel_hi:[1,0,1]
	v_cvt_pk_bf16_f32 v108, v118, v119
	v_cvt_pk_bf16_f32 v109, v120, v121
	v_mul_f32_e32 v119, v119, v119
	v_cvt_pk_bf16_f32 v110, v122, v123
	v_cvt_pk_bf16_f32 v111, v124, v125
	global_store_dwordx4 v[126:127], v[108:111], off sc1
	global_load_dwordx4 v[108:111], v[128:129], off offset:512 nt
	s_nop 0
	global_load_dwordx4 v[112:115], v[128:129], off offset:528 nt
	v_mul_f32_e32 v121, v121, v121
	v_mul_f32_e32 v123, v123, v123
	v_mul_f32_e32 v125, v125, v125
	v_fmac_f32_e32 v119, v118, v118
	v_fmac_f32_e32 v121, v120, v120
	v_fmac_f32_e32 v123, v122, v122
	v_fmac_f32_e32 v125, v124, v124
	v_add_f32_e32 v118, v119, v121
	v_add_f32_e32 v119, v123, v125
	v_add_f32_e32 v118, v118, v119
	s_waitcnt vmcnt(1)
	v_pk_fma_f32 v[106:107], v[106:107], v[130:131], v[110:111] op_sel_hi:[1,0,1]
	v_pk_fma_f32 v[104:105], v[104:105], v[130:131], v[108:109] op_sel_hi:[1,0,1]
	s_waitcnt vmcnt(0)
	v_pk_fma_f32 v[108:109], v[102:103], v[130:131], v[114:115] op_sel_hi:[1,0,1]
	v_pk_fma_f32 v[110:111], v[100:101], v[130:131], v[112:113] op_sel_hi:[1,0,1]
	v_mul_f32_e32 v100, v105, v105
	v_mul_f32_e32 v101, v107, v107
	v_mul_f32_e32 v102, v111, v111
	v_mul_f32_e32 v103, v109, v109
	v_fmac_f32_e32 v100, v104, v104
	v_fmac_f32_e32 v101, v106, v106
	v_fmac_f32_e32 v102, v110, v110
	v_fmac_f32_e32 v103, v108, v108
	v_add_f32_e32 v100, v100, v101
	v_add_f32_e32 v101, v102, v103
	v_add_f32_e32 v100, v100, v101
	v_add_f32_e32 v100, v118, v100
	ds_bpermute_b32 v101, v153, v100
	v_cvt_pk_bf16_f32 v102, v104, v105
	v_cvt_pk_bf16_f32 v103, v106, v107
	v_cvt_pk_bf16_f32 v104, v110, v111
	v_cvt_pk_bf16_f32 v105, v108, v109
	s_waitcnt lgkmcnt(0)
	v_add_f32_e32 v100, v100, v101
	ds_bpermute_b32 v101, v154, v100
	global_store_dwordx4 v[126:127], v[102:105], off offset:256 sc1
	s_and_saveexec_b64 s[6:7], s[0:1]
	s_cbranch_execz .LBB0_717
	s_waitcnt lgkmcnt(0)
	v_add_f32_e32 v102, v100, v101
	v_lshlrev_b64 v[100:101], 6, v[116:117]
	v_lshl_add_u64 v[100:101], s[86:87], 0, v[100:101]
	v_lshl_add_u64 v[100:101], s[4:5], 2, v[100:101]
	v_lshl_add_u64 v[100:101], v[100:101], 0, s[10:11]
	global_store_dword v[100:101], v102, off sc1
.LBB0_717:
	s_or_b64 exec, exec, s[6:7]
	v_add3_u32 v100, s3, v152, 32
	s_waitcnt lgkmcnt(0)
	v_ashrrev_i32_e32 v101, 31, v100
	v_lshlrev_b64 v[102:103], 10, v[100:101]
	v_readlane_b32 s16, v244, 7
	v_lshl_add_u64 v[110:111], v[102:103], 0, v[148:149]
	v_readlane_b32 s17, v244, 8
	v_pk_mul_f32 v[98:99], v[98:99], v[146:147]
	v_pk_mul_f32 v[96:97], v[96:97], v[144:145]
	v_lshl_add_u64 v[112:113], v[110:111], 2, s[16:17]
	global_load_dwordx4 v[102:105], v[112:113], off nt
	global_load_dwordx4 v[106:109], v[112:113], off offset:16 nt
	ds_read_b32 v114, v3 offset:4224
	v_pk_mul_f32 v[94:95], v[94:95], v[142:143]
	v_pk_mul_f32 v[92:93], v[92:93], v[140:141]
	v_lshl_add_u64 v[110:111], v[110:111], 1, s[62:63]
	v_pk_mul_f32 v[90:91], v[90:91], v[138:139]
	v_pk_mul_f32 v[88:89], v[88:89], v[136:137]
	v_pk_mul_f32 v[86:87], v[86:87], v[134:135]
	v_pk_mul_f32 v[84:85], v[84:85], v[132:133]
	v_readlane_b32 s18, v244, 9
	v_readlane_b32 s19, v244, 10
	v_readlane_b32 s20, v244, 11
	v_readlane_b32 s21, v244, 12
	v_readlane_b32 s22, v244, 13
	v_readlane_b32 s23, v244, 14
	v_readlane_b32 s24, v244, 15
	v_readlane_b32 s25, v244, 16
	v_readlane_b32 s26, v244, 17
	v_readlane_b32 s27, v244, 18
	v_readlane_b32 s28, v244, 19
	v_readlane_b32 s29, v244, 20
	v_readlane_b32 s30, v244, 21
	v_readlane_b32 s31, v244, 22
	s_waitcnt vmcnt(1) lgkmcnt(0)
	v_pk_fma_f32 v[104:105], v[98:99], v[114:115], v[104:105] op_sel_hi:[1,0,1]
	v_pk_fma_f32 v[102:103], v[96:97], v[114:115], v[102:103] op_sel_hi:[1,0,1]
	s_waitcnt vmcnt(0)
	v_pk_fma_f32 v[108:109], v[94:95], v[114:115], v[108:109] op_sel_hi:[1,0,1]
	v_pk_fma_f32 v[106:107], v[92:93], v[114:115], v[106:107] op_sel_hi:[1,0,1]
	v_cvt_pk_bf16_f32 v92, v102, v103
	v_cvt_pk_bf16_f32 v93, v104, v105
	v_mul_f32_e32 v103, v103, v103
	v_cvt_pk_bf16_f32 v94, v106, v107
	v_cvt_pk_bf16_f32 v95, v108, v109
	global_store_dwordx4 v[110:111], v[92:95], off sc1
	global_load_dwordx4 v[92:95], v[112:113], off offset:512 nt
	s_nop 0
	global_load_dwordx4 v[96:99], v[112:113], off offset:528 nt
	v_mul_f32_e32 v105, v105, v105
	v_mul_f32_e32 v107, v107, v107
	v_mul_f32_e32 v109, v109, v109
	v_fmac_f32_e32 v103, v102, v102
	v_fmac_f32_e32 v105, v104, v104
	v_fmac_f32_e32 v107, v106, v106
	v_fmac_f32_e32 v109, v108, v108
	v_add_f32_e32 v102, v103, v105
	v_add_f32_e32 v103, v107, v109
	v_add_f32_e32 v102, v102, v103
	s_waitcnt vmcnt(1)
	v_pk_fma_f32 v[90:91], v[90:91], v[114:115], v[94:95] op_sel_hi:[1,0,1]
	v_pk_fma_f32 v[88:89], v[88:89], v[114:115], v[92:93] op_sel_hi:[1,0,1]
	s_waitcnt vmcnt(0)
	v_pk_fma_f32 v[92:93], v[86:87], v[114:115], v[98:99] op_sel_hi:[1,0,1]
	v_pk_fma_f32 v[94:95], v[84:85], v[114:115], v[96:97] op_sel_hi:[1,0,1]
	v_mul_f32_e32 v84, v89, v89
	v_mul_f32_e32 v85, v91, v91
	v_mul_f32_e32 v86, v95, v95
	v_mul_f32_e32 v87, v93, v93
	v_fmac_f32_e32 v84, v88, v88
	v_fmac_f32_e32 v85, v90, v90
	v_fmac_f32_e32 v86, v94, v94
	v_fmac_f32_e32 v87, v92, v92
	v_add_f32_e32 v84, v84, v85
	v_add_f32_e32 v85, v86, v87
	v_add_f32_e32 v84, v84, v85
	v_add_f32_e32 v84, v102, v84
	ds_bpermute_b32 v85, v153, v84
	v_cvt_pk_bf16_f32 v86, v88, v89
	v_cvt_pk_bf16_f32 v87, v90, v91
	v_cvt_pk_bf16_f32 v88, v94, v95
	v_cvt_pk_bf16_f32 v89, v92, v93
	s_waitcnt lgkmcnt(0)
	v_add_f32_e32 v84, v84, v85
	ds_bpermute_b32 v85, v154, v84
	global_store_dwordx4 v[110:111], v[86:89], off offset:256 sc1
	s_and_saveexec_b64 s[6:7], s[0:1]
	s_cbranch_execz .LBB0_719
	s_waitcnt lgkmcnt(0)
	v_add_f32_e32 v86, v84, v85
	v_lshlrev_b64 v[84:85], 6, v[100:101]
	v_lshl_add_u64 v[84:85], s[86:87], 0, v[84:85]
	v_lshl_add_u64 v[84:85], s[4:5], 2, v[84:85]
	v_lshl_add_u64 v[84:85], v[84:85], 0, s[10:11]
	global_store_dword v[84:85], v86, off sc1
.LBB0_719:
	s_or_b64 exec, exec, s[6:7]
	v_add3_u32 v84, s3, v152, 48
	s_waitcnt lgkmcnt(0)
	v_ashrrev_i32_e32 v85, 31, v84
	v_lshlrev_b64 v[86:87], 10, v[84:85]
	v_readlane_b32 s16, v244, 7
	v_lshl_add_u64 v[94:95], v[86:87], 0, v[148:149]
	v_readlane_b32 s17, v244, 8
	v_pk_mul_f32 v[82:83], v[82:83], v[146:147]
	v_pk_mul_f32 v[80:81], v[80:81], v[144:145]
	v_lshl_add_u64 v[96:97], v[94:95], 2, s[16:17]
	global_load_dwordx4 v[86:89], v[96:97], off nt
	global_load_dwordx4 v[90:93], v[96:97], off offset:16 nt
	ds_read_b32 v98, v3 offset:4288
	v_pk_mul_f32 v[78:79], v[78:79], v[142:143]
	v_pk_mul_f32 v[76:77], v[76:77], v[140:141]
	v_lshl_add_u64 v[94:95], v[94:95], 1, s[62:63]
	v_pk_mul_f32 v[74:75], v[74:75], v[138:139]
	v_pk_mul_f32 v[72:73], v[72:73], v[136:137]
	v_pk_mul_f32 v[70:71], v[70:71], v[134:135]
	v_pk_mul_f32 v[68:69], v[68:69], v[132:133]
	v_readlane_b32 s18, v244, 9
	v_readlane_b32 s19, v244, 10
	v_readlane_b32 s20, v244, 11
	v_readlane_b32 s21, v244, 12
	v_readlane_b32 s22, v244, 13
	v_readlane_b32 s23, v244, 14
	v_readlane_b32 s24, v244, 15
	v_readlane_b32 s25, v244, 16
	v_readlane_b32 s26, v244, 17
	v_readlane_b32 s27, v244, 18
	v_readlane_b32 s28, v244, 19
	v_readlane_b32 s29, v244, 20
	v_readlane_b32 s30, v244, 21
	v_readlane_b32 s31, v244, 22
	s_waitcnt vmcnt(1) lgkmcnt(0)
	v_pk_fma_f32 v[88:89], v[82:83], v[98:99], v[88:89] op_sel_hi:[1,0,1]
	v_pk_fma_f32 v[86:87], v[80:81], v[98:99], v[86:87] op_sel_hi:[1,0,1]
	s_waitcnt vmcnt(0)
	v_pk_fma_f32 v[92:93], v[78:79], v[98:99], v[92:93] op_sel_hi:[1,0,1]
	v_pk_fma_f32 v[90:91], v[76:77], v[98:99], v[90:91] op_sel_hi:[1,0,1]
	v_cvt_pk_bf16_f32 v76, v86, v87
	v_cvt_pk_bf16_f32 v77, v88, v89
	v_mul_f32_e32 v87, v87, v87
	v_cvt_pk_bf16_f32 v78, v90, v91
	v_cvt_pk_bf16_f32 v79, v92, v93
	global_store_dwordx4 v[94:95], v[76:79], off sc1
	global_load_dwordx4 v[76:79], v[96:97], off offset:512 nt
	s_nop 0
	global_load_dwordx4 v[80:83], v[96:97], off offset:528 nt
	v_mul_f32_e32 v89, v89, v89
	v_mul_f32_e32 v91, v91, v91
	v_mul_f32_e32 v93, v93, v93
	v_fmac_f32_e32 v87, v86, v86
	v_fmac_f32_e32 v89, v88, v88
	v_fmac_f32_e32 v91, v90, v90
	v_fmac_f32_e32 v93, v92, v92
	v_add_f32_e32 v86, v87, v89
	v_add_f32_e32 v87, v91, v93
	v_add_f32_e32 v86, v86, v87
	s_waitcnt vmcnt(1)
	v_pk_fma_f32 v[74:75], v[74:75], v[98:99], v[78:79] op_sel_hi:[1,0,1]
	v_pk_fma_f32 v[72:73], v[72:73], v[98:99], v[76:77] op_sel_hi:[1,0,1]
	s_waitcnt vmcnt(0)
	v_pk_fma_f32 v[76:77], v[70:71], v[98:99], v[82:83] op_sel_hi:[1,0,1]
	v_pk_fma_f32 v[78:79], v[68:69], v[98:99], v[80:81] op_sel_hi:[1,0,1]
	v_mul_f32_e32 v68, v73, v73
	v_mul_f32_e32 v69, v75, v75
	v_mul_f32_e32 v70, v79, v79
	v_mul_f32_e32 v71, v77, v77
	v_fmac_f32_e32 v68, v72, v72
	v_fmac_f32_e32 v69, v74, v74
	v_fmac_f32_e32 v70, v78, v78
	v_fmac_f32_e32 v71, v76, v76
	v_add_f32_e32 v68, v68, v69
	v_add_f32_e32 v69, v70, v71
	v_add_f32_e32 v68, v68, v69
	v_add_f32_e32 v68, v86, v68
	ds_bpermute_b32 v69, v153, v68
	v_cvt_pk_bf16_f32 v70, v72, v73
	v_cvt_pk_bf16_f32 v71, v74, v75
	v_cvt_pk_bf16_f32 v72, v78, v79
	v_cvt_pk_bf16_f32 v73, v76, v77
	s_waitcnt lgkmcnt(0)
	v_add_f32_e32 v68, v68, v69
	ds_bpermute_b32 v69, v154, v68
	global_store_dwordx4 v[94:95], v[70:73], off offset:256 sc1
	s_and_saveexec_b64 s[6:7], s[0:1]
	s_cbranch_execz .LBB0_721
	s_waitcnt lgkmcnt(0)
	v_add_f32_e32 v70, v68, v69
	v_lshlrev_b64 v[68:69], 6, v[84:85]
	v_lshl_add_u64 v[68:69], s[86:87], 0, v[68:69]
	v_lshl_add_u64 v[68:69], s[4:5], 2, v[68:69]
	v_lshl_add_u64 v[68:69], v[68:69], 0, s[10:11]
	global_store_dword v[68:69], v70, off sc1
.LBB0_721:
	s_or_b64 exec, exec, s[6:7]
	v_add_u32_e32 v68, 0x80, v150
	s_waitcnt lgkmcnt(0)
	v_ashrrev_i32_e32 v69, 31, v68
	v_lshlrev_b64 v[70:71], 10, v[68:69]
	v_readlane_b32 s16, v244, 7
	v_lshl_add_u64 v[78:79], v[70:71], 0, v[148:149]
	v_readlane_b32 s17, v244, 8
	v_pk_mul_f32 v[66:67], v[66:67], v[146:147]
	v_pk_mul_f32 v[64:65], v[64:65], v[144:145]
	v_lshl_add_u64 v[80:81], v[78:79], 2, s[16:17]
	global_load_dwordx4 v[70:73], v[80:81], off nt
	global_load_dwordx4 v[74:77], v[80:81], off offset:16 nt
	ds_read_b32 v82, v3 offset:4608
	v_pk_mul_f32 v[62:63], v[62:63], v[142:143]
	v_pk_mul_f32 v[60:61], v[60:61], v[140:141]
	v_lshl_add_u64 v[78:79], v[78:79], 1, s[62:63]
	v_pk_mul_f32 v[58:59], v[58:59], v[138:139]
	v_pk_mul_f32 v[56:57], v[56:57], v[136:137]
	v_pk_mul_f32 v[54:55], v[54:55], v[134:135]
	v_pk_mul_f32 v[52:53], v[52:53], v[132:133]
	v_readlane_b32 s18, v244, 9
	v_readlane_b32 s19, v244, 10
	v_readlane_b32 s20, v244, 11
	v_readlane_b32 s21, v244, 12
	v_readlane_b32 s22, v244, 13
	v_readlane_b32 s23, v244, 14
	v_readlane_b32 s24, v244, 15
	v_readlane_b32 s25, v244, 16
	v_readlane_b32 s26, v244, 17
	v_readlane_b32 s27, v244, 18
	v_readlane_b32 s28, v244, 19
	v_readlane_b32 s29, v244, 20
	v_readlane_b32 s30, v244, 21
	v_readlane_b32 s31, v244, 22
	s_waitcnt vmcnt(1) lgkmcnt(0)
	v_pk_fma_f32 v[72:73], v[66:67], v[82:83], v[72:73] op_sel_hi:[1,0,1]
	v_pk_fma_f32 v[70:71], v[64:65], v[82:83], v[70:71] op_sel_hi:[1,0,1]
	s_waitcnt vmcnt(0)
	v_pk_fma_f32 v[76:77], v[62:63], v[82:83], v[76:77] op_sel_hi:[1,0,1]
	v_pk_fma_f32 v[74:75], v[60:61], v[82:83], v[74:75] op_sel_hi:[1,0,1]
	v_cvt_pk_bf16_f32 v60, v70, v71
	v_cvt_pk_bf16_f32 v61, v72, v73
	v_mul_f32_e32 v71, v71, v71
	v_cvt_pk_bf16_f32 v62, v74, v75
	v_cvt_pk_bf16_f32 v63, v76, v77
	global_store_dwordx4 v[78:79], v[60:63], off sc1
	global_load_dwordx4 v[60:63], v[80:81], off offset:512 nt
	s_nop 0
	global_load_dwordx4 v[64:67], v[80:81], off offset:528 nt
	v_mul_f32_e32 v73, v73, v73
	v_mul_f32_e32 v75, v75, v75
	v_mul_f32_e32 v77, v77, v77
	v_fmac_f32_e32 v71, v70, v70
	v_fmac_f32_e32 v73, v72, v72
	v_fmac_f32_e32 v75, v74, v74
	v_fmac_f32_e32 v77, v76, v76
	v_add_f32_e32 v70, v71, v73
	v_add_f32_e32 v71, v75, v77
	v_add_f32_e32 v70, v70, v71
	s_waitcnt vmcnt(1)
	v_pk_fma_f32 v[58:59], v[58:59], v[82:83], v[62:63] op_sel_hi:[1,0,1]
	v_pk_fma_f32 v[56:57], v[56:57], v[82:83], v[60:61] op_sel_hi:[1,0,1]
	s_waitcnt vmcnt(0)
	v_pk_fma_f32 v[60:61], v[54:55], v[82:83], v[66:67] op_sel_hi:[1,0,1]
	v_pk_fma_f32 v[62:63], v[52:53], v[82:83], v[64:65] op_sel_hi:[1,0,1]
	v_mul_f32_e32 v52, v57, v57
	v_mul_f32_e32 v53, v59, v59
	v_mul_f32_e32 v54, v63, v63
	v_mul_f32_e32 v55, v61, v61
	v_fmac_f32_e32 v52, v56, v56
	v_fmac_f32_e32 v53, v58, v58
	v_fmac_f32_e32 v54, v62, v62
	v_fmac_f32_e32 v55, v60, v60
	v_add_f32_e32 v52, v52, v53
	v_add_f32_e32 v53, v54, v55
	v_add_f32_e32 v52, v52, v53
	v_add_f32_e32 v52, v70, v52
	ds_bpermute_b32 v53, v153, v52
	v_cvt_pk_bf16_f32 v54, v56, v57
	v_cvt_pk_bf16_f32 v55, v58, v59
	v_cvt_pk_bf16_f32 v56, v62, v63
	v_cvt_pk_bf16_f32 v57, v60, v61
	s_waitcnt lgkmcnt(0)
	v_add_f32_e32 v52, v52, v53
	ds_bpermute_b32 v53, v154, v52
	global_store_dwordx4 v[78:79], v[54:57], off offset:256 sc1
	s_and_saveexec_b64 s[6:7], s[0:1]
	s_cbranch_execz .LBB0_723
	s_waitcnt lgkmcnt(0)
	v_add_f32_e32 v54, v52, v53
	v_lshlrev_b64 v[52:53], 6, v[68:69]
	v_lshl_add_u64 v[52:53], s[86:87], 0, v[52:53]
	v_lshl_add_u64 v[52:53], s[4:5], 2, v[52:53]
	v_lshl_add_u64 v[52:53], v[52:53], 0, s[10:11]
	global_store_dword v[52:53], v54, off sc1
.LBB0_723:
	s_or_b64 exec, exec, s[6:7]
	v_add_u32_e32 v52, 0x90, v150
	s_waitcnt lgkmcnt(0)
	v_ashrrev_i32_e32 v53, 31, v52
	v_lshlrev_b64 v[54:55], 10, v[52:53]
	v_readlane_b32 s16, v244, 7
	v_lshl_add_u64 v[62:63], v[54:55], 0, v[148:149]
	v_readlane_b32 s17, v244, 8
	v_pk_mul_f32 v[50:51], v[50:51], v[146:147]
	v_pk_mul_f32 v[48:49], v[48:49], v[144:145]
	v_lshl_add_u64 v[64:65], v[62:63], 2, s[16:17]
	global_load_dwordx4 v[54:57], v[64:65], off nt
	global_load_dwordx4 v[58:61], v[64:65], off offset:16 nt
	ds_read_b32 v66, v3 offset:4672
	v_pk_mul_f32 v[46:47], v[46:47], v[142:143]
	v_pk_mul_f32 v[44:45], v[44:45], v[140:141]
	v_lshl_add_u64 v[62:63], v[62:63], 1, s[62:63]
	v_pk_mul_f32 v[42:43], v[42:43], v[138:139]
	v_pk_mul_f32 v[40:41], v[40:41], v[136:137]
	v_pk_mul_f32 v[38:39], v[38:39], v[134:135]
	v_pk_mul_f32 v[36:37], v[36:37], v[132:133]
	v_readlane_b32 s18, v244, 9
	v_readlane_b32 s19, v244, 10
	v_readlane_b32 s20, v244, 11
	v_readlane_b32 s21, v244, 12
	v_readlane_b32 s22, v244, 13
	v_readlane_b32 s23, v244, 14
	v_readlane_b32 s24, v244, 15
	v_readlane_b32 s25, v244, 16
	v_readlane_b32 s26, v244, 17
	v_readlane_b32 s27, v244, 18
	v_readlane_b32 s28, v244, 19
	v_readlane_b32 s29, v244, 20
	v_readlane_b32 s30, v244, 21
	v_readlane_b32 s31, v244, 22
	s_waitcnt vmcnt(1) lgkmcnt(0)
	v_pk_fma_f32 v[56:57], v[50:51], v[66:67], v[56:57] op_sel_hi:[1,0,1]
	v_pk_fma_f32 v[54:55], v[48:49], v[66:67], v[54:55] op_sel_hi:[1,0,1]
	s_waitcnt vmcnt(0)
	v_pk_fma_f32 v[60:61], v[46:47], v[66:67], v[60:61] op_sel_hi:[1,0,1]
	v_pk_fma_f32 v[58:59], v[44:45], v[66:67], v[58:59] op_sel_hi:[1,0,1]
	v_cvt_pk_bf16_f32 v44, v54, v55
	v_cvt_pk_bf16_f32 v45, v56, v57
	v_mul_f32_e32 v55, v55, v55
	v_cvt_pk_bf16_f32 v46, v58, v59
	v_cvt_pk_bf16_f32 v47, v60, v61
	global_store_dwordx4 v[62:63], v[44:47], off sc1
	global_load_dwordx4 v[44:47], v[64:65], off offset:512 nt
	s_nop 0
	global_load_dwordx4 v[48:51], v[64:65], off offset:528 nt
	v_mul_f32_e32 v57, v57, v57
	v_mul_f32_e32 v59, v59, v59
	v_mul_f32_e32 v61, v61, v61
	v_fmac_f32_e32 v55, v54, v54
	v_fmac_f32_e32 v57, v56, v56
	v_fmac_f32_e32 v59, v58, v58
	v_fmac_f32_e32 v61, v60, v60
	v_add_f32_e32 v54, v55, v57
	v_add_f32_e32 v55, v59, v61
	v_add_f32_e32 v54, v54, v55
	s_waitcnt vmcnt(1)
	v_pk_fma_f32 v[42:43], v[42:43], v[66:67], v[46:47] op_sel_hi:[1,0,1]
	v_pk_fma_f32 v[40:41], v[40:41], v[66:67], v[44:45] op_sel_hi:[1,0,1]
	s_waitcnt vmcnt(0)
	v_pk_fma_f32 v[44:45], v[38:39], v[66:67], v[50:51] op_sel_hi:[1,0,1]
	v_pk_fma_f32 v[46:47], v[36:37], v[66:67], v[48:49] op_sel_hi:[1,0,1]
	v_mul_f32_e32 v36, v41, v41
	v_mul_f32_e32 v37, v43, v43
	v_mul_f32_e32 v38, v47, v47
	v_mul_f32_e32 v39, v45, v45
	v_fmac_f32_e32 v36, v40, v40
	v_fmac_f32_e32 v37, v42, v42
	v_fmac_f32_e32 v38, v46, v46
	v_fmac_f32_e32 v39, v44, v44
	v_add_f32_e32 v36, v36, v37
	v_add_f32_e32 v37, v38, v39
	v_add_f32_e32 v36, v36, v37
	v_add_f32_e32 v36, v54, v36
	ds_bpermute_b32 v37, v153, v36
	v_cvt_pk_bf16_f32 v38, v40, v41
	v_cvt_pk_bf16_f32 v39, v42, v43
	v_cvt_pk_bf16_f32 v40, v46, v47
	v_cvt_pk_bf16_f32 v41, v44, v45
	s_waitcnt lgkmcnt(0)
	v_add_f32_e32 v36, v36, v37
	ds_bpermute_b32 v37, v154, v36
	global_store_dwordx4 v[62:63], v[38:41], off offset:256 sc1
	s_and_saveexec_b64 s[6:7], s[0:1]
	s_cbranch_execz .LBB0_725
	s_waitcnt lgkmcnt(0)
	v_add_f32_e32 v38, v36, v37
	v_lshlrev_b64 v[36:37], 6, v[52:53]
	v_lshl_add_u64 v[36:37], s[86:87], 0, v[36:37]
	v_lshl_add_u64 v[36:37], s[4:5], 2, v[36:37]
	v_lshl_add_u64 v[36:37], v[36:37], 0, s[10:11]
	global_store_dword v[36:37], v38, off sc1
.LBB0_725:
	s_or_b64 exec, exec, s[6:7]
	v_add_u32_e32 v36, 0xa0, v150
	s_waitcnt lgkmcnt(0)
	v_ashrrev_i32_e32 v37, 31, v36
	v_lshlrev_b64 v[38:39], 10, v[36:37]
	v_readlane_b32 s16, v244, 7
	v_lshl_add_u64 v[46:47], v[38:39], 0, v[148:149]
	v_readlane_b32 s17, v244, 8
	v_pk_mul_f32 v[34:35], v[34:35], v[146:147]
	v_pk_mul_f32 v[32:33], v[32:33], v[144:145]
	v_lshl_add_u64 v[48:49], v[46:47], 2, s[16:17]
	global_load_dwordx4 v[38:41], v[48:49], off nt
	global_load_dwordx4 v[42:45], v[48:49], off offset:16 nt
	ds_read_b32 v50, v3 offset:4736
	v_pk_mul_f32 v[30:31], v[30:31], v[142:143]
	v_pk_mul_f32 v[28:29], v[28:29], v[140:141]
	v_lshl_add_u64 v[46:47], v[46:47], 1, s[62:63]
	v_pk_mul_f32 v[26:27], v[26:27], v[138:139]
	v_pk_mul_f32 v[24:25], v[24:25], v[136:137]
	v_pk_mul_f32 v[22:23], v[22:23], v[134:135]
	v_pk_mul_f32 v[20:21], v[20:21], v[132:133]
	v_readlane_b32 s18, v244, 9
	v_readlane_b32 s19, v244, 10
	v_readlane_b32 s20, v244, 11
	v_readlane_b32 s21, v244, 12
	v_readlane_b32 s22, v244, 13
	v_readlane_b32 s23, v244, 14
	v_readlane_b32 s24, v244, 15
	v_readlane_b32 s25, v244, 16
	v_readlane_b32 s26, v244, 17
	v_readlane_b32 s27, v244, 18
	v_readlane_b32 s28, v244, 19
	v_readlane_b32 s29, v244, 20
	v_readlane_b32 s30, v244, 21
	v_readlane_b32 s31, v244, 22
	s_waitcnt vmcnt(1) lgkmcnt(0)
	v_pk_fma_f32 v[40:41], v[34:35], v[50:51], v[40:41] op_sel_hi:[1,0,1]
	v_pk_fma_f32 v[38:39], v[32:33], v[50:51], v[38:39] op_sel_hi:[1,0,1]
	s_waitcnt vmcnt(0)
	v_pk_fma_f32 v[44:45], v[30:31], v[50:51], v[44:45] op_sel_hi:[1,0,1]
	v_pk_fma_f32 v[42:43], v[28:29], v[50:51], v[42:43] op_sel_hi:[1,0,1]
	v_cvt_pk_bf16_f32 v28, v38, v39
	v_cvt_pk_bf16_f32 v29, v40, v41
	v_mul_f32_e32 v39, v39, v39
	v_cvt_pk_bf16_f32 v30, v42, v43
	v_cvt_pk_bf16_f32 v31, v44, v45
	global_store_dwordx4 v[46:47], v[28:31], off sc1
	global_load_dwordx4 v[28:31], v[48:49], off offset:512 nt
	s_nop 0
	global_load_dwordx4 v[32:35], v[48:49], off offset:528 nt
	v_mul_f32_e32 v41, v41, v41
	v_mul_f32_e32 v43, v43, v43
	v_mul_f32_e32 v45, v45, v45
	v_fmac_f32_e32 v39, v38, v38
	v_fmac_f32_e32 v41, v40, v40
	v_fmac_f32_e32 v43, v42, v42
	v_fmac_f32_e32 v45, v44, v44
	v_add_f32_e32 v38, v39, v41
	v_add_f32_e32 v39, v43, v45
	v_add_f32_e32 v38, v38, v39
	s_waitcnt vmcnt(1)
	v_pk_fma_f32 v[26:27], v[26:27], v[50:51], v[30:31] op_sel_hi:[1,0,1]
	v_pk_fma_f32 v[24:25], v[24:25], v[50:51], v[28:29] op_sel_hi:[1,0,1]
	s_waitcnt vmcnt(0)
	v_pk_fma_f32 v[28:29], v[22:23], v[50:51], v[34:35] op_sel_hi:[1,0,1]
	v_pk_fma_f32 v[30:31], v[20:21], v[50:51], v[32:33] op_sel_hi:[1,0,1]
	v_mul_f32_e32 v20, v25, v25
	v_mul_f32_e32 v21, v27, v27
	v_mul_f32_e32 v22, v31, v31
	v_mul_f32_e32 v23, v29, v29
	v_fmac_f32_e32 v20, v24, v24
	v_fmac_f32_e32 v21, v26, v26
	v_fmac_f32_e32 v22, v30, v30
	v_fmac_f32_e32 v23, v28, v28
	v_add_f32_e32 v20, v20, v21
	v_add_f32_e32 v21, v22, v23
	v_add_f32_e32 v20, v20, v21
	v_add_f32_e32 v20, v38, v20
	ds_bpermute_b32 v21, v153, v20
	v_cvt_pk_bf16_f32 v22, v24, v25
	v_cvt_pk_bf16_f32 v23, v26, v27
	v_cvt_pk_bf16_f32 v24, v30, v31
	v_cvt_pk_bf16_f32 v25, v28, v29
	s_waitcnt lgkmcnt(0)
	v_add_f32_e32 v20, v20, v21
	ds_bpermute_b32 v21, v154, v20
	global_store_dwordx4 v[46:47], v[22:25], off offset:256 sc1
	s_and_saveexec_b64 s[6:7], s[0:1]
	s_cbranch_execz .LBB0_727
	s_waitcnt lgkmcnt(0)
	v_add_f32_e32 v22, v20, v21
	v_lshlrev_b64 v[20:21], 6, v[36:37]
	v_lshl_add_u64 v[20:21], s[86:87], 0, v[20:21]
	v_lshl_add_u64 v[20:21], s[4:5], 2, v[20:21]
	v_lshl_add_u64 v[20:21], v[20:21], 0, s[10:11]
	global_store_dword v[20:21], v22, off sc1
.LBB0_727:
	s_or_b64 exec, exec, s[6:7]
	v_add_u32_e32 v20, 0xb0, v150
	s_waitcnt lgkmcnt(0)
	v_ashrrev_i32_e32 v21, 31, v20
	v_lshlrev_b64 v[22:23], 10, v[20:21]
	v_readlane_b32 s16, v244, 7
	v_lshl_add_u64 v[30:31], v[22:23], 0, v[148:149]
	v_readlane_b32 s17, v244, 8
	v_pk_mul_f32 v[18:19], v[18:19], v[146:147]
	v_pk_mul_f32 v[16:17], v[16:17], v[144:145]
	v_lshl_add_u64 v[32:33], v[30:31], 2, s[16:17]
	global_load_dwordx4 v[22:25], v[32:33], off nt
	global_load_dwordx4 v[26:29], v[32:33], off offset:16 nt
	ds_read_b32 v34, v3 offset:4800
	v_pk_mul_f32 v[14:15], v[14:15], v[142:143]
	v_pk_mul_f32 v[12:13], v[12:13], v[140:141]
	v_lshl_add_u64 v[30:31], v[30:31], 1, s[62:63]
	v_pk_mul_f32 v[10:11], v[10:11], v[138:139]
	v_pk_mul_f32 v[8:9], v[8:9], v[136:137]
	v_pk_mul_f32 v[6:7], v[6:7], v[134:135]
	v_pk_mul_f32 v[4:5], v[4:5], v[132:133]
	v_readlane_b32 s18, v244, 9
	v_readlane_b32 s19, v244, 10
	v_readlane_b32 s20, v244, 11
	v_readlane_b32 s21, v244, 12
	v_readlane_b32 s22, v244, 13
	v_readlane_b32 s23, v244, 14
	v_readlane_b32 s24, v244, 15
	v_readlane_b32 s25, v244, 16
	v_readlane_b32 s26, v244, 17
	v_readlane_b32 s27, v244, 18
	v_readlane_b32 s28, v244, 19
	v_readlane_b32 s29, v244, 20
	v_readlane_b32 s30, v244, 21
	v_readlane_b32 s31, v244, 22
	s_waitcnt vmcnt(1) lgkmcnt(0)
	v_pk_fma_f32 v[24:25], v[18:19], v[34:35], v[24:25] op_sel_hi:[1,0,1]
	v_pk_fma_f32 v[22:23], v[16:17], v[34:35], v[22:23] op_sel_hi:[1,0,1]
	s_waitcnt vmcnt(0)
	v_pk_fma_f32 v[28:29], v[14:15], v[34:35], v[28:29] op_sel_hi:[1,0,1]
	v_pk_fma_f32 v[26:27], v[12:13], v[34:35], v[26:27] op_sel_hi:[1,0,1]
	v_cvt_pk_bf16_f32 v12, v22, v23
	v_cvt_pk_bf16_f32 v13, v24, v25
	v_mul_f32_e32 v3, v23, v23
	v_cvt_pk_bf16_f32 v14, v26, v27
	v_cvt_pk_bf16_f32 v15, v28, v29
	global_store_dwordx4 v[30:31], v[12:15], off sc1
	global_load_dwordx4 v[12:15], v[32:33], off offset:512 nt
	s_nop 0
	global_load_dwordx4 v[16:19], v[32:33], off offset:528 nt
	v_mul_f32_e32 v23, v25, v25
	v_mul_f32_e32 v25, v27, v27
	v_mul_f32_e32 v27, v29, v29
	v_fmac_f32_e32 v3, v22, v22
	v_fmac_f32_e32 v23, v24, v24
	v_fmac_f32_e32 v25, v26, v26
	v_fmac_f32_e32 v27, v28, v28
	v_add_f32_e32 v3, v3, v23
	v_add_f32_e32 v22, v25, v27
	v_add_f32_e32 v3, v3, v22
	s_waitcnt vmcnt(1)
	v_pk_fma_f32 v[10:11], v[10:11], v[34:35], v[14:15] op_sel_hi:[1,0,1]
	v_pk_fma_f32 v[8:9], v[8:9], v[34:35], v[12:13] op_sel_hi:[1,0,1]
	s_waitcnt vmcnt(0)
	v_pk_fma_f32 v[12:13], v[6:7], v[34:35], v[18:19] op_sel_hi:[1,0,1]
	v_pk_fma_f32 v[14:15], v[4:5], v[34:35], v[16:17] op_sel_hi:[1,0,1]
	v_mul_f32_e32 v4, v9, v9
	v_mul_f32_e32 v5, v11, v11
	v_mul_f32_e32 v6, v15, v15
	v_mul_f32_e32 v7, v13, v13
	v_fmac_f32_e32 v4, v8, v8
	v_fmac_f32_e32 v5, v10, v10
	v_fmac_f32_e32 v6, v14, v14
	v_fmac_f32_e32 v7, v12, v12
	v_add_f32_e32 v4, v4, v5
	v_add_f32_e32 v5, v6, v7
	v_add_f32_e32 v4, v4, v5
	v_add_f32_e32 v3, v3, v4
	ds_bpermute_b32 v4, v153, v3
	v_cvt_pk_bf16_f32 v6, v8, v9
	v_cvt_pk_bf16_f32 v7, v10, v11
	v_cvt_pk_bf16_f32 v8, v14, v15
	v_cvt_pk_bf16_f32 v9, v12, v13
	s_waitcnt lgkmcnt(0)
	v_add_f32_e32 v3, v3, v4
	ds_bpermute_b32 v4, v154, v3
	global_store_dwordx4 v[30:31], v[6:9], off offset:256 sc1
	s_and_saveexec_b64 s[6:7], s[0:1]
	s_cbranch_execz .LBB0_729
	s_waitcnt lgkmcnt(0)
	v_add_f32_e32 v3, v3, v4
	v_lshlrev_b64 v[4:5], 6, v[20:21]
	v_lshl_add_u64 v[4:5], s[86:87], 0, v[4:5]
	v_lshl_add_u64 v[4:5], s[4:5], 2, v[4:5]
	v_lshl_add_u64 v[4:5], v[4:5], 0, s[10:11]
	global_store_dword v[4:5], v3, off sc1

.LBB0_763:
	s_andn2_saveexec_b64 s[8:9], s[8:9]
	s_cbranch_execz .LBB0_783
	s_mov_b64 s[8:9], exec
	s_waitcnt lgkmcnt(0)
	s_waitcnt vmcnt(0)
	v_mbcnt_lo_u32_b32 v4, s8, 0
	v_mbcnt_hi_u32_b32 v4, s9, v4
	v_cmp_eq_u32_e32 vcc, 0, v4
	s_and_saveexec_b64 s[10:11], vcc
	s_cbranch_execz .LBB0_766
	s_bcnt1_i32_b64 s3, s[8:9]
	v_mov_b32_e32 v5, 0x43000
	v_mov_b32_e32 v6, s3
	global_atomic_add v5, v5, v6, s[82:83] offset:1024 sc0

.LBB0_787:
	v_lshlrev_b32_e32 v36, 14, v174
	v_lshlrev_b32_e32 v37, 12, v142
	v_add3_u32 v36, v169, v36, v37
	s_barrier
	s_nop 4
	ds_write2st64_b32 v36, v4, v5 offset1:1
	ds_write2st64_b32 v36, v6, v7 offset0:2 offset1:3
	ds_write2st64_b32 v36, v8, v9 offset0:4 offset1:5
	ds_write2st64_b32 v36, v10, v11 offset0:6 offset1:7
	ds_write2st64_b32 v36, v12, v13 offset0:8 offset1:9
	ds_write2st64_b32 v36, v14, v15 offset0:10 offset1:11
	ds_write2st64_b32 v36, v16, v17 offset0:12 offset1:13
	ds_write2st64_b32 v36, v18, v19 offset0:14 offset1:15
	ds_write2st64_b32 v36, v20, v21 offset0:16 offset1:17
	ds_write2st64_b32 v36, v22, v23 offset0:18 offset1:19
	ds_write2st64_b32 v36, v24, v25 offset0:20 offset1:21
	ds_write2st64_b32 v36, v26, v27 offset0:22 offset1:23
	ds_write2st64_b32 v36, v28, v29 offset0:24 offset1:25
	ds_write2st64_b32 v36, v30, v31 offset0:26 offset1:27
	ds_write2st64_b32 v36, v32, v33 offset0:28 offset1:29
	ds_write2st64_b32 v36, v34, v35 offset0:30 offset1:31
	v_lshrrev_b32_e32 v5, 3, v140
	v_lshlrev_b32_e32 v4, 3, v173
	v_and_b32_e32 v5, 0xfffff0, v5
	v_and_or_b32 v4, v4, 8, v5
	v_lshl_add_u32 v4, v4, 8, v169
	s_waitcnt lgkmcnt(0)
	s_barrier
	ds_read2st64_b32 v[36:37], v4 offset1:1
	ds_read2st64_b32 v[38:39], v4 offset0:2 offset1:3
	ds_read2st64_b32 v[40:41], v4 offset0:4 offset1:5
	ds_read2st64_b32 v[42:43], v4 offset0:6 offset1:7
	ds_read2st64_b32 v[44:45], v4 offset0:64 offset1:65
	ds_read2st64_b32 v[46:47], v4 offset0:66 offset1:67
	ds_read2st64_b32 v[48:49], v4 offset0:68 offset1:69
	ds_read2st64_b32 v[50:51], v4 offset0:70 offset1:71
	ds_read2st64_b32 v[52:53], v4 offset0:128 offset1:129
	ds_read2st64_b32 v[54:55], v4 offset0:130 offset1:131
	ds_read2st64_b32 v[56:57], v4 offset0:132 offset1:133
	ds_read2st64_b32 v[58:59], v4 offset0:134 offset1:135
	ds_read2st64_b32 v[60:61], v4 offset0:192 offset1:193
	ds_read2st64_b32 v[62:63], v4 offset0:194 offset1:195
	ds_read2st64_b32 v[64:65], v4 offset0:196 offset1:197
	ds_read2st64_b32 v[66:67], v4 offset0:198 offset1:199
	s_waitcnt lgkmcnt(0)
	s_barrier
	global_load_dwordx4 v[4:7], v[132:133], off
	global_load_dwordx4 v[8:11], v[132:133], off offset:16
	global_load_dwordx4 v[12:15], v[132:133], off offset:32
	global_load_dwordx4 v[16:19], v[132:133], off offset:48
	global_load_dwordx4 v[20:23], v[132:133], off offset:64
	global_load_dwordx4 v[24:27], v[132:133], off offset:80
	global_load_dwordx4 v[28:31], v[132:133], off offset:96
	global_load_dwordx4 v[32:35], v[132:133], off offset:112
	s_add_i32 s25, s25, s88
	s_add_i32 s18, s18, s19
	s_cmpk_gt_i32 s25, 0x7f
	s_waitcnt vmcnt(7)
	v_mov_b32_e32 v68, v4
	s_waitcnt vmcnt(6)
	v_mov_b32_e32 v69, v8
	v_mov_b32_e32 v8, v5
	v_mov_b32_e32 v4, v6
	v_mov_b32_e32 v5, v10
	v_mov_b32_e32 v10, v7
	s_waitcnt vmcnt(5)
	v_mov_b32_e32 v6, v13
	v_mov_b32_e32 v7, v14
	v_mov_b32_e32 v13, v15
	v_pk_add_f32 v[8:9], v[68:69], v[8:9]
	v_pk_add_f32 v[4:5], v[4:5], v[10:11]
	v_pk_add_f32 v[6:7], v[6:7], v[12:13]
	v_pk_add_f32 v[4:5], v[8:9], v[4:5]
	v_pk_add_f32 v[6:7], v[6:7], v[6:7] op_sel:[0,1] op_sel_hi:[1,0]
	v_add_f32_e32 v4, 0, v4
	s_waitcnt vmcnt(4)
	v_add_f32_e32 v14, v16, v17
	v_add_f32_e32 v16, v18, v19
	s_waitcnt vmcnt(3)
	v_mov_b32_e32 v19, v20
	v_mov_b32_e32 v15, v22
	v_mov_b32_e32 v17, v23
	v_mov_b32_e32 v7, v21
	v_add_f32_e32 v18, v4, v5
	s_waitcnt vmcnt(2)
	v_mov_b32_e32 v22, v25
	v_mov_b32_e32 v23, v26
	v_mov_b32_e32 v25, v27
	v_pk_add_f32 v[10:11], v[14:15], v[16:17]
	v_pk_add_f32 v[4:5], v[18:19], v[6:7]
	v_pk_add_f32 v[12:13], v[22:23], v[24:25]
	v_pk_add_f32 v[4:5], v[4:5], v[10:11]
	v_pk_add_f32 v[8:9], v[12:13], v[12:13] op_sel:[0,1] op_sel_hi:[1,0]
	v_pk_add_f32 v[4:5], v[4:5], v[4:5] op_sel:[0,1] op_sel_hi:[1,0]
	s_waitcnt vmcnt(1)
	v_add_f32_e32 v26, v28, v29
	v_add_f32_e32 v20, v30, v31
	s_waitcnt vmcnt(0)
	v_mov_b32_e32 v27, v34
	v_mov_b32_e32 v9, v33
	v_mov_b32_e32 v5, v32
	v_mov_b32_e32 v21, v35
	v_pk_add_f32 v[4:5], v[4:5], v[8:9]
	v_pk_add_f32 v[6:7], v[26:27], v[20:21]
	v_pk_add_f32 v[10:11], v[38:39], 0 op_sel_hi:[1,0]
	v_pk_add_f32 v[4:5], v[4:5], v[6:7]
	v_pk_add_f32 v[10:11], v[10:11], v[46:47]
	v_add_f32_e32 v4, v4, v5
	v_fmamk_f32 v4, v4, 0x3a800000, v171
	v_mul_f32_e32 v5, 0x4f800000, v4
	v_cmp_gt_f32_e32 vcc, s24, v4
	v_pk_add_f32 v[10:11], v[10:11], v[54:55]
	s_nop 0
	v_cndmask_b32_e32 v4, v4, v5, vcc
	v_sqrt_f32_e32 v5, v4
	v_pk_add_f32 v[10:11], v[10:11], v[62:63]
	v_add_u32_e32 v6, -1, v5
	v_fma_f32 v7, -v6, v5, v4
	v_cmp_ge_f32_e64 s[0:1], 0, v7
	v_add_u32_e32 v7, 1, v5
	v_max_f32_e32 v11, 0, v11
	v_cndmask_b32_e64 v6, v5, v6, s[0:1]
	v_fma_f32 v5, -v7, v5, v4
	v_cmp_lt_f32_e64 s[0:1], 0, v5
	v_max_f32_e32 v10, 0, v10
	s_nop 0
	v_cndmask_b32_e64 v5, v6, v7, s[0:1]
	v_mul_f32_e32 v6, 0x37800000, v5
	v_cndmask_b32_e32 v5, v5, v6, vcc
	v_cmp_class_f32_e32 vcc, v4, v172
	s_nop 1
	v_cndmask_b32_e32 v4, v5, v4, vcc
	v_div_scale_f32 v5, s[0:1], v4, v4, 1.0
	v_rcp_f32_e32 v6, v5
	s_nop 0
	v_fma_f32 v7, -v5, v6, 1.0
	v_fmac_f32_e32 v6, v7, v6
	v_div_scale_f32 v7, vcc, 1.0, v4, 1.0
	v_mul_f32_e32 v8, v7, v6
	v_fma_f32 v9, -v5, v8, v7
	v_fmac_f32_e32 v8, v9, v6
	v_fma_f32 v5, -v5, v8, v7
	v_div_fmas_f32 v5, v5, v6, v8
	v_pk_add_f32 v[8:9], v[36:37], 0 op_sel_hi:[1,0]
	v_div_fixup_f32 v4, v5, v4, 1.0
	v_pk_add_f32 v[8:9], v[8:9], v[44:45]
	v_or_b32_e32 v5, s26, v170
	v_pk_add_f32 v[8:9], v[8:9], v[52:53]
	v_ashrrev_i32_e32 v6, 4, v5
	v_pk_add_f32 v[8:9], v[8:9], v[60:61]
	v_ashrrev_i32_e32 v7, 31, v6
	v_max_f32_e32 v9, 0, v9
	v_max_f32_e32 v8, 0, v8
	v_pk_mul_f32 v[8:9], v[8:9], v[4:5] op_sel_hi:[1,0]
	v_pk_mul_f32 v[10:11], v[10:11], v[4:5] op_sel_hi:[1,0]
	v_pk_mul_f32 v[8:9], v[8:9], v[8:9]
	v_pk_mul_f32 v[10:11], v[10:11], v[10:11]
	v_lshlrev_b64 v[6:7], 10, v[6:7]
	v_cvt_pk_bf16_f32 v8, v8, v9
	v_cvt_pk_bf16_f32 v9, v10, v11
	v_lshl_add_u64 v[6:7], v[136:137], 0, v[6:7]
	global_store_dwordx2 v[6:7], v[8:9], off sc1
	v_pk_add_f32 v[8:9], v[40:41], 0 op_sel_hi:[1,0]
	v_pk_add_f32 v[10:11], v[42:43], 0 op_sel_hi:[1,0]
	v_pk_add_f32 v[8:9], v[8:9], v[48:49]
	v_pk_add_f32 v[10:11], v[10:11], v[50:51]
	v_pk_add_f32 v[8:9], v[8:9], v[56:57]
	v_pk_add_f32 v[10:11], v[10:11], v[58:59]
	v_pk_add_f32 v[8:9], v[8:9], v[64:65]
	v_pk_add_f32 v[10:11], v[10:11], v[66:67]
	v_max_f32_e32 v9, 0, v9
	v_max_f32_e32 v8, 0, v8
	v_max_f32_e32 v11, 0, v11
	v_max_f32_e32 v10, 0, v10
	v_pk_mul_f32 v[8:9], v[8:9], v[4:5] op_sel_hi:[1,0]
	v_pk_mul_f32 v[4:5], v[10:11], v[4:5] op_sel_hi:[1,0]
	v_pk_mul_f32 v[8:9], v[8:9], v[8:9]
	v_pk_mul_f32 v[4:5], v[4:5], v[4:5]
	v_cvt_pk_bf16_f32 v8, v8, v9
	v_cvt_pk_bf16_f32 v9, v4, v5
	global_store_dwordx2 v[6:7], v[8:9], off offset:512 sc1
	s_cbranch_scc1 .LBB0_793

.LBB0_909:
	s_or_b64 exec, exec, s[34:35]
	v_lshl_add_u32 v12, s46, 6, v217
	v_ashrrev_i32_e32 v13, 2, v12
	v_and_or_b32 v24, v13, s43, v212
	v_lshrrev_b32_e32 v13, 2, v12
	v_and_or_b32 v13, v13, 16, s45
	v_or_b32_e32 v16, v13, v168
	v_ashrrev_i32_e32 v25, 31, v24
	v_ashrrev_i32_e32 v17, 31, v16
	v_lshlrev_b64 v[18:19], 12, v[24:25]
	v_lshlrev_b64 v[22:23], 2, v[16:17]
	v_lshl_add_u64 v[20:21], s[16:17], 0, v[18:19]
	v_lshl_add_u64 v[26:27], s[56:57], 0, v[22:23]
	s_waitcnt lgkmcnt(0)
	s_barrier
	global_load_dwordx4 v[16:19], v[26:27], off
	v_lshl_add_u64 v[28:29], v[20:21], 0, v[22:23]
	global_load_dwordx4 v[20:23], v[28:29], off
	v_lshl_add_u32 v15, v24, 2, 0
	ds_read_b32 v15, v15 offset:1536
	v_ashrrev_i32_e32 v24, 4, v13
	v_ashrrev_i32_e32 v30, 7, v12
	v_ashrrev_i32_e32 v31, 31, v30
	v_ashrrev_i32_e32 v25, 31, v24
	s_waitcnt lgkmcnt(0)
	v_fmamk_f32 v13, v15, 0x3a800000, v170
	v_mul_f32_e32 v15, 0x4f800000, v13
	v_cmp_gt_f32_e32 vcc, s44, v13
	v_lshlrev_b64 v[30:31], 12, v[30:31]
	v_lshlrev_b64 v[24:25], 6, v[24:25]
	v_cndmask_b32_e32 v13, v13, v15, vcc
	v_sqrt_f32_e32 v15, v13
	v_lshl_add_u64 v[24:25], v[24:25], 0, v[30:31]
	v_or_b32_e32 v24, v24, v212
	v_lshl_add_u64 v[24:25], v[24:25], 4, v[134:135]
	v_add_u32_e32 v30, -1, v15
	v_add_u32_e32 v31, 1, v15
	v_fma_f32 v32, -v30, v15, v13
	v_fma_f32 v33, -v31, v15, v13
	v_cmp_ge_f32_e64 s[6:7], 0, v32
	s_waitcnt vmcnt(1)
	v_pk_mul_f32 v[10:11], v[10:11], v[18:19]
	v_cndmask_b32_e64 v15, v15, v30, s[6:7]
	v_cmp_lt_f32_e64 s[6:7], 0, v33
	v_pk_mul_f32 v[8:9], v[8:9], v[16:17]
	s_nop 0
	v_cndmask_b32_e64 v15, v15, v31, s[6:7]
	v_mul_f32_e32 v30, 0x37800000, v15
	v_cndmask_b32_e32 v15, v15, v30, vcc
	v_cmp_class_f32_e32 vcc, v13, v171
	s_nop 1
	v_cndmask_b32_e32 v13, v15, v13, vcc
	v_div_scale_f32 v15, s[6:7], v13, v13, 1.0
	v_rcp_f32_e32 v30, v15
	v_div_scale_f32 v31, vcc, 1.0, v13, 1.0
	v_fma_f32 v32, -v15, v30, 1.0
	v_fmac_f32_e32 v30, v32, v30
	v_mul_f32_e32 v32, v31, v30
	v_fma_f32 v33, -v15, v32, v31
	v_fmac_f32_e32 v32, v33, v30
	v_fma_f32 v15, -v15, v32, v31
	v_div_fmas_f32 v15, v15, v30, v32
	v_div_fixup_f32 v30, v15, v13, 1.0
	s_waitcnt vmcnt(0)
	v_pk_fma_f32 v[10:11], v[10:11], v[30:31], v[22:23] op_sel_hi:[1,0,1]
	v_pk_fma_f32 v[8:9], v[8:9], v[30:31], v[20:21] op_sel_hi:[1,0,1]
	v_cvt_pk_bf16_f32 v17, v10, v11
	v_cvt_pk_bf16_f32 v16, v8, v9
	global_store_dwordx4 v[28:29], v[8:11], off sc1
	global_store_dwordx2 v[24:25], v[16:17], off sc1
	global_load_dwordx4 v[16:19], v[26:27], off offset:32
	s_nop 0
	global_load_dwordx4 v[20:23], v[28:29], off offset:32
	v_mul_f32_e32 v9, v9, v9
	v_fmac_f32_e32 v9, v8, v8
	v_mul_f32_e32 v8, v11, v11
	v_fmac_f32_e32 v8, v10, v10
	v_add_f32_e32 v8, v9, v8
	s_waitcnt vmcnt(1)
	v_pk_mul_f32 v[6:7], v[6:7], v[18:19]
	v_pk_mul_f32 v[4:5], v[4:5], v[16:17]
	s_waitcnt vmcnt(0)
	v_pk_fma_f32 v[6:7], v[30:31], v[6:7], v[22:23] op_sel_hi:[0,1,1]
	v_pk_fma_f32 v[4:5], v[30:31], v[4:5], v[20:21] op_sel_hi:[0,1,1]
	v_cvt_pk_bf16_f32 v16, v4, v5
	v_cvt_pk_bf16_f32 v17, v6, v7
	global_store_dwordx4 v[28:29], v[4:7], off offset:32 sc1
	global_store_dwordx2 v[24:25], v[16:17], off offset:512 sc1
	s_barrier
	s_getreg_b32 s6, hwreg(HW_REG_HW_ID, 0, 6)
	s_and_b32 s6, s6, 63
	s_lshl_b32 s6, s6, 2
	s_add_i32 s6, s6, 0
	s_add_i32 s6, s6, 0x23e00
	v_mov_b32_e32 v16, s6
	v_mov_b32_e32 v17, s13
	flat_load_dword v13, v[16:17] sc0 sc1
	s_waitcnt vmcnt(0)
	v_mul_f32_e32 v5, v5, v5
	v_fmac_f32_e32 v5, v4, v4
	v_mul_f32_e32 v4, v7, v7
	v_fmac_f32_e32 v4, v6, v6
	v_add_f32_e32 v4, v5, v4
	v_add_f32_e32 v5, v8, v4
	ds_bpermute_b32 v6, v169, v5
	s_waitcnt lgkmcnt(0)
	v_readfirstlane_b32 s6, v13
	s_nop 1
	v_lshl_add_u32 v4, s6, 6, v217
	s_and_saveexec_b64 s[6:7], s[0:1]
	s_cbranch_execz .LBB0_911
	v_add_f32_e32 v5, v5, v6
	v_lshlrev_b32_e32 v6, 3, v4
	v_and_b32_e32 v6, 0x200, v6
	v_add_u32_e32 v6, 0, v6
	v_and_b32_e32 v7, 0xffffff80, v4
	v_add3_u32 v6, v6, v7, v14
	ds_write_b32 v6, v5

.LBB0_970:
	s_or_b64 exec, exec, s[16:17]
	s_waitcnt vmcnt(0) lgkmcnt(0)
	s_barrier
	v_lshl_add_u64 v[164:165], v[218:219], 2, s[56:57]
	global_load_dwordx4 v[180:183], v[164:165], off
	global_load_dwordx4 v[176:179], v[164:165], off offset:16
	global_load_dwordx4 v[168:171], v[164:165], off offset:512
	s_nop 0
	global_load_dwordx4 v[164:167], v[164:165], off offset:528
	v_lshl_add_u32 v227, v215, 2, 0
	ds_read_b32 v236, v227 offset:4096
	s_waitcnt vmcnt(0)
	v_lshlrev_b32_e32 v228, 16, v208
	v_and_b32_e32 v229, 0xffff0000, v208
	v_lshlrev_b32_e32 v208, 16, v209
	v_and_b32_e32 v209, 0xffff0000, v209
	v_lshlrev_b32_e32 v230, 16, v210
	v_and_b32_e32 v231, 0xffff0000, v210
	v_lshlrev_b32_e32 v210, 16, v211
	v_and_b32_e32 v211, 0xffff0000, v211
	v_lshlrev_b32_e32 v232, 16, v204
	v_and_b32_e32 v233, 0xffff0000, v204
	v_lshlrev_b32_e32 v204, 16, v205
	v_and_b32_e32 v205, 0xffff0000, v205
	v_lshlrev_b32_e32 v234, 16, v206
	v_and_b32_e32 v235, 0xffff0000, v206
	v_lshlrev_b32_e32 v206, 16, v207
	v_and_b32_e32 v207, 0xffff0000, v207
	v_add_u32_e32 v220, s20, v215
	v_ashrrev_i32_e32 v221, 31, v220
	v_lshlrev_b64 v[238:239], 11, v[220:221]
	s_lshl_b32 s4, s12, 2
	s_mov_b32 s7, 0
	s_ashr_i32 s5, s4, 31
	v_pk_mul_f32 v[150:151], v[150:151], v[182:183]
	v_pk_mul_f32 v[148:149], v[148:149], v[180:181]
	v_pk_mul_f32 v[146:147], v[146:147], v[178:179]
	v_pk_mul_f32 v[144:145], v[144:145], v[176:177]
	v_pk_mul_f32 v[142:143], v[142:143], v[170:171]
	v_pk_mul_f32 v[140:141], v[140:141], v[168:169]
	v_pk_mul_f32 v[138:139], v[138:139], v[166:167]
	v_pk_mul_f32 v[136:137], v[136:137], v[164:165]
	s_waitcnt lgkmcnt(0)
	v_pk_fma_f32 v[148:149], v[148:149], v[236:237], v[228:229] op_sel_hi:[1,0,1]
	v_pk_fma_f32 v[150:151], v[150:151], v[236:237], v[208:209] op_sel_hi:[1,0,1]
	v_pk_fma_f32 v[144:145], v[144:145], v[236:237], v[230:231] op_sel_hi:[1,0,1]
	v_pk_fma_f32 v[146:147], v[146:147], v[236:237], v[210:211] op_sel_hi:[1,0,1]
	v_pk_fma_f32 v[140:141], v[140:141], v[236:237], v[232:233] op_sel_hi:[1,0,1]
	v_pk_fma_f32 v[142:143], v[142:143], v[236:237], v[204:205] op_sel_hi:[1,0,1]
	v_pk_fma_f32 v[204:205], v[136:137], v[236:237], v[234:235] op_sel_hi:[1,0,1]
	v_pk_fma_f32 v[206:207], v[138:139], v[236:237], v[206:207] op_sel_hi:[1,0,1]
	v_mul_f32_e32 v208, v149, v149
	v_mul_f32_e32 v209, v151, v151
	v_mul_f32_e32 v210, v145, v145
	v_mul_f32_e32 v211, v147, v147
	v_cvt_pk_bf16_f32 v136, v148, v149
	v_cvt_pk_bf16_f32 v137, v150, v151
	v_cvt_pk_bf16_f32 v138, v144, v145
	v_cvt_pk_bf16_f32 v139, v146, v147
	v_mul_f32_e32 v145, v141, v141
	v_mul_f32_e32 v147, v143, v143
	v_mul_f32_e32 v149, v205, v205
	v_mul_f32_e32 v151, v207, v207
	v_fmac_f32_e32 v208, v148, v148
	v_fmac_f32_e32 v209, v150, v150
	v_fmac_f32_e32 v210, v144, v144
	v_fmac_f32_e32 v211, v146, v146
	v_fmac_f32_e32 v145, v140, v140
	v_fmac_f32_e32 v147, v142, v142
	v_fmac_f32_e32 v149, v204, v204
	v_fmac_f32_e32 v151, v206, v206
	v_add_f32_e32 v144, v208, v209
	v_add_f32_e32 v146, v210, v211
	v_add_f32_e32 v145, v145, v147
	v_add_f32_e32 v147, v149, v151
	v_add_f32_e32 v144, v144, v146
	v_add_f32_e32 v145, v145, v147
	v_add_f32_e32 v146, v144, v145
	ds_bpermute_b32 v147, v3, v146
	v_lshl_add_u64 v[144:145], s[62:63], 0, v[238:239]
	v_lshl_add_u64 v[144:145], v[218:219], 1, v[144:145]
	global_store_dwordx4 v[144:145], v[136:139], off sc1
	s_waitcnt lgkmcnt(0)
	s_nop 0
	v_add_f32_e32 v136, v146, v147
	ds_bpermute_b32 v137, v226, v136
	v_cvt_pk_bf16_f32 v138, v140, v141
	v_cvt_pk_bf16_f32 v139, v142, v143
	v_cvt_pk_bf16_f32 v140, v204, v205
	v_cvt_pk_bf16_f32 v141, v206, v207
	global_store_dwordx4 v[144:145], v[138:141], off offset:256 sc1
	s_and_saveexec_b64 s[10:11], s[0:1]
	s_cbranch_execz .LBB0_972
	s_waitcnt lgkmcnt(0)
	v_add_f32_e32 v138, v136, v137
	v_lshlrev_b64 v[136:137], 6, v[220:221]
	v_lshl_add_u64 v[136:137], s[86:87], 0, v[136:137]
	v_lshl_add_u64 v[136:137], s[4:5], 2, v[136:137]
	v_lshl_add_u64 v[136:137], v[136:137], 0, s[6:7]
	global_store_dword v[136:137], v138, off sc1
.LBB0_972:
	s_or_b64 exec, exec, s[10:11]
	ds_read_b32 v138, v227 offset:4160
	v_lshlrev_b32_e32 v142, 16, v200
	v_and_b32_e32 v143, 0xffff0000, v200
	v_lshlrev_b32_e32 v144, 16, v201
	v_and_b32_e32 v145, 0xffff0000, v201
	v_pk_mul_f32 v[130:131], v[130:131], v[182:183]
	v_pk_mul_f32 v[128:129], v[128:129], v[180:181]
	v_lshlrev_b32_e32 v146, 16, v202
	v_and_b32_e32 v147, 0xffff0000, v202
	v_lshlrev_b32_e32 v148, 16, v203
	v_and_b32_e32 v149, 0xffff0000, v203
	s_waitcnt lgkmcnt(0)
	v_pk_fma_f32 v[130:131], v[130:131], v[138:139], v[144:145] op_sel_hi:[1,0,1]
	v_pk_fma_f32 v[128:129], v[128:129], v[138:139], v[142:143] op_sel_hi:[1,0,1]
	v_pk_mul_f32 v[126:127], v[126:127], v[178:179]
	v_pk_mul_f32 v[124:125], v[124:125], v[176:177]
	v_pk_fma_f32 v[142:143], v[126:127], v[138:139], v[148:149] op_sel_hi:[1,0,1]
	v_pk_fma_f32 v[126:127], v[124:125], v[138:139], v[146:147] op_sel_hi:[1,0,1]
	v_mul_f32_e32 v124, v129, v129
	v_mul_f32_e32 v125, v131, v131
	v_fmac_f32_e32 v124, v128, v128
	v_fmac_f32_e32 v125, v130, v130
	v_add_f32_e32 v124, v124, v125
	v_mul_f32_e32 v125, v127, v127
	v_mul_f32_e32 v139, v143, v143
	v_fmac_f32_e32 v125, v126, v126
	v_fmac_f32_e32 v139, v142, v142
	v_add_f32_e32 v125, v125, v139
	v_add_f32_e32 v139, v124, v125
	v_cvt_pk_bf16_f32 v124, v128, v129
	v_cvt_pk_bf16_f32 v125, v130, v131
	v_lshlrev_b32_e32 v128, 16, v196
	v_and_b32_e32 v129, 0xffff0000, v196
	v_lshlrev_b32_e32 v130, 16, v197
	v_and_b32_e32 v131, 0xffff0000, v197
	v_pk_mul_f32 v[118:119], v[118:119], v[170:171]
	v_pk_mul_f32 v[116:117], v[116:117], v[168:169]
	v_cvt_pk_bf16_f32 v126, v126, v127
	v_cvt_pk_bf16_f32 v127, v142, v143
	v_lshlrev_b32_e32 v142, 16, v198
	v_and_b32_e32 v143, 0xffff0000, v198
	v_pk_fma_f32 v[118:119], v[118:119], v[138:139], v[130:131] op_sel_hi:[1,0,1]
	v_pk_fma_f32 v[116:117], v[116:117], v[138:139], v[128:129] op_sel_hi:[1,0,1]
	v_pk_mul_f32 v[108:109], v[108:109], v[164:165]
	v_lshlrev_b32_e32 v144, 16, v199
	v_and_b32_e32 v145, 0xffff0000, v199
	v_pk_mul_f32 v[110:111], v[110:111], v[166:167]
	v_pk_fma_f32 v[128:129], v[108:109], v[138:139], v[142:143] op_sel_hi:[1,0,1]
	v_mul_f32_e32 v108, v117, v117
	v_mul_f32_e32 v109, v119, v119
	v_pk_fma_f32 v[110:111], v[110:111], v[138:139], v[144:145] op_sel_hi:[1,0,1]
	v_fmac_f32_e32 v108, v116, v116
	v_fmac_f32_e32 v109, v118, v118
	v_add_f32_e32 v108, v108, v109
	v_mul_f32_e32 v109, v129, v129
	v_mul_f32_e32 v130, v111, v111
	v_fmac_f32_e32 v109, v128, v128
	v_fmac_f32_e32 v130, v110, v110
	v_add_f32_e32 v109, v109, v130
	v_add_f32_e32 v108, v108, v109
	v_add_f32_e32 v138, v139, v108
	ds_bpermute_b32 v139, v3, v138
	v_add3_u32 v136, s20, v215, 16
	v_ashrrev_i32_e32 v137, 31, v136
	v_lshlrev_b64 v[140:141], 11, v[136:137]
	v_lshl_add_u64 v[108:109], s[62:63], 0, v[140:141]
	v_lshl_add_u64 v[130:131], v[218:219], 1, v[108:109]
	s_waitcnt lgkmcnt(0)
	v_add_f32_e32 v108, v138, v139
	ds_bpermute_b32 v109, v226, v108
	global_store_dwordx4 v[130:131], v[124:127], off sc1
	v_cvt_pk_bf16_f32 v116, v116, v117
	v_cvt_pk_bf16_f32 v117, v118, v119
	v_cvt_pk_bf16_f32 v118, v128, v129
	v_cvt_pk_bf16_f32 v119, v110, v111
	global_store_dwordx4 v[130:131], v[116:119], off offset:256 sc1
	s_and_saveexec_b64 s[10:11], s[0:1]
	s_cbranch_execz .LBB0_974
	s_waitcnt lgkmcnt(0)
	v_add_f32_e32 v110, v108, v109
	v_lshlrev_b64 v[108:109], 6, v[136:137]
	v_lshl_add_u64 v[108:109], s[86:87], 0, v[108:109]
	v_lshl_add_u64 v[108:109], s[4:5], 2, v[108:109]
	v_lshl_add_u64 v[108:109], v[108:109], 0, s[6:7]
	global_store_dword v[108:109], v110, off sc1
.LBB0_974:
	s_or_b64 exec, exec, s[10:11]
	ds_read_b32 v110, v227 offset:4224
	v_lshlrev_b32_e32 v118, 16, v192
	v_and_b32_e32 v119, 0xffff0000, v192
	v_lshlrev_b32_e32 v124, 16, v193
	v_and_b32_e32 v125, 0xffff0000, v193
	v_pk_mul_f32 v[106:107], v[106:107], v[182:183]
	v_pk_mul_f32 v[104:105], v[104:105], v[180:181]
	v_lshlrev_b32_e32 v126, 16, v194
	v_and_b32_e32 v127, 0xffff0000, v194
	v_lshlrev_b32_e32 v128, 16, v195
	v_and_b32_e32 v129, 0xffff0000, v195
	s_waitcnt lgkmcnt(0)
	v_pk_fma_f32 v[106:107], v[106:107], v[110:111], v[124:125] op_sel_hi:[1,0,1]
	v_pk_fma_f32 v[104:105], v[104:105], v[110:111], v[118:119] op_sel_hi:[1,0,1]
	v_pk_mul_f32 v[98:99], v[98:99], v[178:179]
	v_pk_mul_f32 v[96:97], v[96:97], v[176:177]
	v_pk_fma_f32 v[118:119], v[98:99], v[110:111], v[128:129] op_sel_hi:[1,0,1]
	v_pk_fma_f32 v[98:99], v[96:97], v[110:111], v[126:127] op_sel_hi:[1,0,1]
	v_mul_f32_e32 v96, v105, v105
	v_mul_f32_e32 v97, v107, v107
	v_fmac_f32_e32 v96, v104, v104
	v_fmac_f32_e32 v97, v106, v106
	v_add_f32_e32 v96, v96, v97
	v_mul_f32_e32 v97, v99, v99
	v_mul_f32_e32 v111, v119, v119
	v_fmac_f32_e32 v97, v98, v98
	v_fmac_f32_e32 v111, v118, v118
	v_add_f32_e32 v97, v97, v111
	v_add_f32_e32 v111, v96, v97
	v_cvt_pk_bf16_f32 v96, v104, v105
	v_cvt_pk_bf16_f32 v97, v106, v107
	v_lshlrev_b32_e32 v104, 16, v188
	v_and_b32_e32 v105, 0xffff0000, v188
	v_lshlrev_b32_e32 v106, 16, v189
	v_and_b32_e32 v107, 0xffff0000, v189
	v_pk_mul_f32 v[90:91], v[90:91], v[170:171]
	v_pk_mul_f32 v[88:89], v[88:89], v[168:169]
	v_cvt_pk_bf16_f32 v98, v98, v99
	v_cvt_pk_bf16_f32 v99, v118, v119
	v_lshlrev_b32_e32 v118, 16, v190
	v_and_b32_e32 v119, 0xffff0000, v190
	v_pk_fma_f32 v[90:91], v[90:91], v[110:111], v[106:107] op_sel_hi:[1,0,1]
	v_pk_fma_f32 v[88:89], v[88:89], v[110:111], v[104:105] op_sel_hi:[1,0,1]
	v_pk_mul_f32 v[84:85], v[84:85], v[164:165]
	v_lshlrev_b32_e32 v124, 16, v191
	v_and_b32_e32 v125, 0xffff0000, v191
	v_pk_mul_f32 v[86:87], v[86:87], v[166:167]
	v_pk_fma_f32 v[106:107], v[84:85], v[110:111], v[118:119] op_sel_hi:[1,0,1]
	v_mul_f32_e32 v84, v89, v89
	v_mul_f32_e32 v85, v91, v91
	v_pk_fma_f32 v[104:105], v[86:87], v[110:111], v[124:125] op_sel_hi:[1,0,1]
	v_fmac_f32_e32 v84, v88, v88
	v_fmac_f32_e32 v85, v90, v90
	v_add_f32_e32 v84, v84, v85
	v_mul_f32_e32 v85, v107, v107
	v_mul_f32_e32 v86, v105, v105
	v_fmac_f32_e32 v85, v106, v106
	v_fmac_f32_e32 v86, v104, v104
	v_add_f32_e32 v85, v85, v86
	v_add_f32_e32 v84, v84, v85
	v_add_f32_e32 v87, v111, v84
	ds_bpermute_b32 v118, v3, v87
	v_add3_u32 v108, s20, v215, 32
	v_ashrrev_i32_e32 v109, 31, v108
	v_lshlrev_b64 v[116:117], 11, v[108:109]
	v_lshl_add_u64 v[84:85], s[62:63], 0, v[116:117]
	v_lshl_add_u64 v[110:111], v[218:219], 1, v[84:85]
	s_waitcnt lgkmcnt(0)
	v_add_f32_e32 v84, v87, v118
	ds_bpermute_b32 v85, v226, v84
	global_store_dwordx4 v[110:111], v[96:99], off sc1
	v_cvt_pk_bf16_f32 v86, v88, v89
	v_cvt_pk_bf16_f32 v87, v90, v91
	v_cvt_pk_bf16_f32 v88, v106, v107
	v_cvt_pk_bf16_f32 v89, v104, v105
	global_store_dwordx4 v[110:111], v[86:89], off offset:256 sc1
	s_and_saveexec_b64 s[10:11], s[0:1]
	s_cbranch_execz .LBB0_976
	s_waitcnt lgkmcnt(0)
	v_add_f32_e32 v86, v84, v85
	v_lshlrev_b64 v[84:85], 6, v[108:109]
	v_lshl_add_u64 v[84:85], s[86:87], 0, v[84:85]
	v_lshl_add_u64 v[84:85], s[4:5], 2, v[84:85]
	v_lshl_add_u64 v[84:85], v[84:85], 0, s[6:7]
	global_store_dword v[84:85], v86, off sc1
.LBB0_976:
	s_or_b64 exec, exec, s[10:11]
	ds_read_b32 v86, v227 offset:4288
	v_lshlrev_b32_e32 v90, 16, v184
	v_and_b32_e32 v91, 0xffff0000, v184
	v_lshlrev_b32_e32 v96, 16, v185
	v_and_b32_e32 v97, 0xffff0000, v185
	v_pk_mul_f32 v[82:83], v[82:83], v[182:183]
	v_pk_mul_f32 v[80:81], v[80:81], v[180:181]
	v_lshlrev_b32_e32 v98, 16, v186
	v_and_b32_e32 v99, 0xffff0000, v186
	v_lshlrev_b32_e32 v104, 16, v187
	v_and_b32_e32 v105, 0xffff0000, v187
	s_waitcnt lgkmcnt(0)
	v_pk_fma_f32 v[82:83], v[82:83], v[86:87], v[96:97] op_sel_hi:[1,0,1]
	v_pk_fma_f32 v[80:81], v[80:81], v[86:87], v[90:91] op_sel_hi:[1,0,1]
	v_pk_mul_f32 v[78:79], v[78:79], v[178:179]
	v_pk_mul_f32 v[76:77], v[76:77], v[176:177]
	v_pk_fma_f32 v[90:91], v[78:79], v[86:87], v[104:105] op_sel_hi:[1,0,1]
	v_pk_fma_f32 v[78:79], v[76:77], v[86:87], v[98:99] op_sel_hi:[1,0,1]
	v_mul_f32_e32 v76, v81, v81
	v_mul_f32_e32 v77, v83, v83
	v_fmac_f32_e32 v76, v80, v80
	v_fmac_f32_e32 v77, v82, v82
	v_add_f32_e32 v76, v76, v77
	v_mul_f32_e32 v77, v79, v79
	v_mul_f32_e32 v87, v91, v91
	v_fmac_f32_e32 v77, v78, v78
	v_fmac_f32_e32 v87, v90, v90
	v_add_f32_e32 v77, v77, v87
	v_add_f32_e32 v87, v76, v77
	v_cvt_pk_bf16_f32 v76, v80, v81
	v_cvt_pk_bf16_f32 v77, v82, v83
	v_lshlrev_b32_e32 v80, 16, v172
	v_and_b32_e32 v81, 0xffff0000, v172
	v_lshlrev_b32_e32 v82, 16, v173
	v_and_b32_e32 v83, 0xffff0000, v173
	v_pk_mul_f32 v[74:75], v[74:75], v[170:171]
	v_pk_mul_f32 v[72:73], v[72:73], v[168:169]
	v_cvt_pk_bf16_f32 v78, v78, v79
	v_cvt_pk_bf16_f32 v79, v90, v91
	v_lshlrev_b32_e32 v90, 16, v174
	v_and_b32_e32 v91, 0xffff0000, v174
	v_pk_fma_f32 v[74:75], v[74:75], v[86:87], v[82:83] op_sel_hi:[1,0,1]
	v_pk_fma_f32 v[72:73], v[72:73], v[86:87], v[80:81] op_sel_hi:[1,0,1]
	v_pk_mul_f32 v[68:69], v[68:69], v[164:165]
	v_lshlrev_b32_e32 v96, 16, v175
	v_and_b32_e32 v97, 0xffff0000, v175
	v_pk_mul_f32 v[70:71], v[70:71], v[166:167]
	v_pk_fma_f32 v[82:83], v[68:69], v[86:87], v[90:91] op_sel_hi:[1,0,1]
	v_mul_f32_e32 v68, v73, v73
	v_mul_f32_e32 v69, v75, v75
	v_pk_fma_f32 v[80:81], v[70:71], v[86:87], v[96:97] op_sel_hi:[1,0,1]
	v_fmac_f32_e32 v68, v72, v72
	v_fmac_f32_e32 v69, v74, v74
	v_add_f32_e32 v68, v68, v69
	v_mul_f32_e32 v69, v83, v83
	v_mul_f32_e32 v70, v81, v81
	v_fmac_f32_e32 v69, v82, v82
	v_fmac_f32_e32 v70, v80, v80
	v_add_f32_e32 v69, v69, v70
	v_add_f32_e32 v68, v68, v69
	v_add_f32_e32 v71, v87, v68
	ds_bpermute_b32 v90, v3, v71
	v_add3_u32 v84, s20, v215, 48
	v_ashrrev_i32_e32 v85, 31, v84
	v_lshlrev_b64 v[88:89], 11, v[84:85]
	v_lshl_add_u64 v[68:69], s[62:63], 0, v[88:89]
	v_lshl_add_u64 v[86:87], v[218:219], 1, v[68:69]
	s_waitcnt lgkmcnt(0)
	v_add_f32_e32 v68, v71, v90
	ds_bpermute_b32 v69, v226, v68
	global_store_dwordx4 v[86:87], v[76:79], off sc1
	v_cvt_pk_bf16_f32 v70, v72, v73
	v_cvt_pk_bf16_f32 v71, v74, v75
	v_cvt_pk_bf16_f32 v72, v82, v83
	v_cvt_pk_bf16_f32 v73, v80, v81
	global_store_dwordx4 v[86:87], v[70:73], off offset:256 sc1
	s_and_saveexec_b64 s[10:11], s[0:1]
	s_cbranch_execz .LBB0_978
	s_waitcnt lgkmcnt(0)
	v_add_f32_e32 v70, v68, v69
	v_lshlrev_b64 v[68:69], 6, v[84:85]
	v_lshl_add_u64 v[68:69], s[86:87], 0, v[68:69]
	v_lshl_add_u64 v[68:69], s[4:5], 2, v[68:69]
	v_lshl_add_u64 v[68:69], v[68:69], 0, s[6:7]
	global_store_dword v[68:69], v70, off sc1
.LBB0_978:
	s_or_b64 exec, exec, s[10:11]
	ds_read_b32 v70, v227 offset:4608
	v_lshlrev_b32_e32 v74, 16, v160
	v_and_b32_e32 v75, 0xffff0000, v160
	v_lshlrev_b32_e32 v76, 16, v161
	v_and_b32_e32 v77, 0xffff0000, v161
	v_pk_mul_f32 v[66:67], v[66:67], v[182:183]
	v_pk_mul_f32 v[64:65], v[64:65], v[180:181]
	v_lshlrev_b32_e32 v78, 16, v162
	v_and_b32_e32 v79, 0xffff0000, v162
	v_lshlrev_b32_e32 v80, 16, v163
	v_and_b32_e32 v81, 0xffff0000, v163
	s_waitcnt lgkmcnt(0)
	v_pk_fma_f32 v[66:67], v[66:67], v[70:71], v[76:77] op_sel_hi:[1,0,1]
	v_pk_fma_f32 v[64:65], v[64:65], v[70:71], v[74:75] op_sel_hi:[1,0,1]
	v_pk_mul_f32 v[62:63], v[62:63], v[178:179]
	v_pk_mul_f32 v[60:61], v[60:61], v[176:177]
	v_pk_fma_f32 v[74:75], v[62:63], v[70:71], v[80:81] op_sel_hi:[1,0,1]
	v_pk_fma_f32 v[62:63], v[60:61], v[70:71], v[78:79] op_sel_hi:[1,0,1]
	v_mul_f32_e32 v60, v65, v65
	v_mul_f32_e32 v61, v67, v67
	v_fmac_f32_e32 v60, v64, v64
	v_fmac_f32_e32 v61, v66, v66
	v_add_f32_e32 v60, v60, v61
	v_mul_f32_e32 v61, v63, v63
	v_mul_f32_e32 v71, v75, v75
	v_fmac_f32_e32 v61, v62, v62
	v_fmac_f32_e32 v71, v74, v74
	v_add_f32_e32 v61, v61, v71
	v_add_f32_e32 v71, v60, v61
	v_cvt_pk_bf16_f32 v60, v64, v65
	v_cvt_pk_bf16_f32 v61, v66, v67
	v_lshlrev_b32_e32 v64, 16, v156
	v_and_b32_e32 v65, 0xffff0000, v156
	v_lshlrev_b32_e32 v66, 16, v157
	v_and_b32_e32 v67, 0xffff0000, v157
	v_pk_mul_f32 v[58:59], v[58:59], v[170:171]
	v_pk_mul_f32 v[56:57], v[56:57], v[168:169]
	v_cvt_pk_bf16_f32 v62, v62, v63
	v_cvt_pk_bf16_f32 v63, v74, v75
	v_lshlrev_b32_e32 v74, 16, v158
	v_and_b32_e32 v75, 0xffff0000, v158
	v_pk_fma_f32 v[58:59], v[58:59], v[70:71], v[66:67] op_sel_hi:[1,0,1]
	v_pk_fma_f32 v[56:57], v[56:57], v[70:71], v[64:65] op_sel_hi:[1,0,1]
	v_pk_mul_f32 v[52:53], v[52:53], v[164:165]
	v_lshlrev_b32_e32 v76, 16, v159
	v_and_b32_e32 v77, 0xffff0000, v159
	v_pk_mul_f32 v[54:55], v[54:55], v[166:167]
	v_pk_fma_f32 v[66:67], v[52:53], v[70:71], v[74:75] op_sel_hi:[1,0,1]
	v_mul_f32_e32 v52, v57, v57
	v_mul_f32_e32 v53, v59, v59
	v_pk_fma_f32 v[64:65], v[54:55], v[70:71], v[76:77] op_sel_hi:[1,0,1]
	v_fmac_f32_e32 v52, v56, v56
	v_fmac_f32_e32 v53, v58, v58
	v_add_f32_e32 v52, v52, v53
	v_mul_f32_e32 v53, v67, v67
	v_mul_f32_e32 v54, v65, v65
	v_fmac_f32_e32 v53, v66, v66
	v_fmac_f32_e32 v54, v64, v64
	v_add_f32_e32 v53, v53, v54
	v_add_f32_e32 v52, v52, v53
	v_add_f32_e32 v55, v71, v52
	ds_bpermute_b32 v74, v3, v55
	v_add_u32_e32 v68, 0x80, v220
	v_ashrrev_i32_e32 v69, 31, v68
	v_lshlrev_b64 v[72:73], 11, v[68:69]
	v_lshl_add_u64 v[52:53], s[62:63], 0, v[72:73]
	v_lshl_add_u64 v[70:71], v[218:219], 1, v[52:53]
	s_waitcnt lgkmcnt(0)
	v_add_f32_e32 v52, v55, v74
	ds_bpermute_b32 v53, v226, v52
	global_store_dwordx4 v[70:71], v[60:63], off sc1
	v_cvt_pk_bf16_f32 v54, v56, v57
	v_cvt_pk_bf16_f32 v55, v58, v59
	v_cvt_pk_bf16_f32 v56, v66, v67
	v_cvt_pk_bf16_f32 v57, v64, v65
	global_store_dwordx4 v[70:71], v[54:57], off offset:256 sc1
	s_and_saveexec_b64 s[10:11], s[0:1]
	s_cbranch_execz .LBB0_980
	s_waitcnt lgkmcnt(0)
	v_add_f32_e32 v54, v52, v53
	v_lshlrev_b64 v[52:53], 6, v[68:69]
	v_lshl_add_u64 v[52:53], s[86:87], 0, v[52:53]
	v_lshl_add_u64 v[52:53], s[4:5], 2, v[52:53]
	v_lshl_add_u64 v[52:53], v[52:53], 0, s[6:7]
	global_store_dword v[52:53], v54, off sc1
.LBB0_980:
	s_or_b64 exec, exec, s[10:11]
	ds_read_b32 v54, v227 offset:4672
	v_lshlrev_b32_e32 v58, 16, v152
	v_and_b32_e32 v59, 0xffff0000, v152
	v_lshlrev_b32_e32 v60, 16, v153
	v_and_b32_e32 v61, 0xffff0000, v153
	v_pk_mul_f32 v[50:51], v[50:51], v[182:183]
	v_pk_mul_f32 v[48:49], v[48:49], v[180:181]
	v_lshlrev_b32_e32 v62, 16, v154
	v_and_b32_e32 v63, 0xffff0000, v154
	v_lshlrev_b32_e32 v64, 16, v155
	v_and_b32_e32 v65, 0xffff0000, v155
	s_waitcnt lgkmcnt(0)
	v_pk_fma_f32 v[50:51], v[50:51], v[54:55], v[60:61] op_sel_hi:[1,0,1]
	v_pk_fma_f32 v[48:49], v[48:49], v[54:55], v[58:59] op_sel_hi:[1,0,1]
	v_pk_mul_f32 v[46:47], v[46:47], v[178:179]
	v_pk_mul_f32 v[44:45], v[44:45], v[176:177]
	v_pk_fma_f32 v[58:59], v[46:47], v[54:55], v[64:65] op_sel_hi:[1,0,1]
	v_pk_fma_f32 v[46:47], v[44:45], v[54:55], v[62:63] op_sel_hi:[1,0,1]
	v_mul_f32_e32 v44, v49, v49
	v_mul_f32_e32 v45, v51, v51
	v_fmac_f32_e32 v44, v48, v48
	v_fmac_f32_e32 v45, v50, v50
	v_add_f32_e32 v44, v44, v45
	v_mul_f32_e32 v45, v47, v47
	v_mul_f32_e32 v55, v59, v59
	v_fmac_f32_e32 v45, v46, v46
	v_fmac_f32_e32 v55, v58, v58
	v_add_f32_e32 v45, v45, v55
	v_add_f32_e32 v55, v44, v45
	v_cvt_pk_bf16_f32 v44, v48, v49
	v_cvt_pk_bf16_f32 v45, v50, v51
	v_lshlrev_b32_e32 v48, 16, v132
	v_and_b32_e32 v49, 0xffff0000, v132
	v_lshlrev_b32_e32 v50, 16, v133
	v_and_b32_e32 v51, 0xffff0000, v133
	v_pk_mul_f32 v[42:43], v[42:43], v[170:171]
	v_pk_mul_f32 v[40:41], v[40:41], v[168:169]
	v_cvt_pk_bf16_f32 v46, v46, v47
	v_cvt_pk_bf16_f32 v47, v58, v59
	v_lshlrev_b32_e32 v58, 16, v134
	v_and_b32_e32 v59, 0xffff0000, v134
	v_pk_fma_f32 v[42:43], v[42:43], v[54:55], v[50:51] op_sel_hi:[1,0,1]
	v_pk_fma_f32 v[40:41], v[40:41], v[54:55], v[48:49] op_sel_hi:[1,0,1]
	v_pk_mul_f32 v[36:37], v[36:37], v[164:165]
	v_lshlrev_b32_e32 v60, 16, v135
	v_and_b32_e32 v61, 0xffff0000, v135
	v_pk_mul_f32 v[38:39], v[38:39], v[166:167]
	v_pk_fma_f32 v[50:51], v[36:37], v[54:55], v[58:59] op_sel_hi:[1,0,1]
	v_mul_f32_e32 v36, v41, v41
	v_mul_f32_e32 v37, v43, v43
	v_pk_fma_f32 v[48:49], v[38:39], v[54:55], v[60:61] op_sel_hi:[1,0,1]
	v_fmac_f32_e32 v36, v40, v40
	v_fmac_f32_e32 v37, v42, v42
	v_add_f32_e32 v36, v36, v37
	v_mul_f32_e32 v37, v51, v51
	v_mul_f32_e32 v38, v49, v49
	v_fmac_f32_e32 v37, v50, v50
	v_fmac_f32_e32 v38, v48, v48
	v_add_f32_e32 v37, v37, v38
	v_add_f32_e32 v36, v36, v37
	v_add_f32_e32 v39, v55, v36
	ds_bpermute_b32 v58, v3, v39
	v_add_u32_e32 v52, 0x90, v220
	v_ashrrev_i32_e32 v53, 31, v52
	v_lshlrev_b64 v[56:57], 11, v[52:53]
	v_lshl_add_u64 v[36:37], s[62:63], 0, v[56:57]
	v_lshl_add_u64 v[54:55], v[218:219], 1, v[36:37]
	s_waitcnt lgkmcnt(0)
	v_add_f32_e32 v36, v39, v58
	ds_bpermute_b32 v37, v226, v36
	global_store_dwordx4 v[54:55], v[44:47], off sc1
	v_cvt_pk_bf16_f32 v38, v40, v41
	v_cvt_pk_bf16_f32 v39, v42, v43
	v_cvt_pk_bf16_f32 v40, v50, v51
	v_cvt_pk_bf16_f32 v41, v48, v49
	global_store_dwordx4 v[54:55], v[38:41], off offset:256 sc1
	s_and_saveexec_b64 s[10:11], s[0:1]
	s_cbranch_execz .LBB0_982
	s_waitcnt lgkmcnt(0)
	v_add_f32_e32 v38, v36, v37
	v_lshlrev_b64 v[36:37], 6, v[52:53]
	v_lshl_add_u64 v[36:37], s[86:87], 0, v[36:37]
	v_lshl_add_u64 v[36:37], s[4:5], 2, v[36:37]
	v_lshl_add_u64 v[36:37], v[36:37], 0, s[6:7]
	global_store_dword v[36:37], v38, off sc1
.LBB0_982:
	s_or_b64 exec, exec, s[10:11]
	ds_read_b32 v38, v227 offset:4736
	v_lshlrev_b32_e32 v42, 16, v120
	v_and_b32_e32 v43, 0xffff0000, v120
	v_lshlrev_b32_e32 v44, 16, v121
	v_and_b32_e32 v45, 0xffff0000, v121
	v_pk_mul_f32 v[34:35], v[34:35], v[182:183]
	v_pk_mul_f32 v[32:33], v[32:33], v[180:181]
	v_lshlrev_b32_e32 v46, 16, v122
	v_and_b32_e32 v47, 0xffff0000, v122
	v_lshlrev_b32_e32 v48, 16, v123
	v_and_b32_e32 v49, 0xffff0000, v123
	s_waitcnt lgkmcnt(0)
	v_pk_fma_f32 v[34:35], v[34:35], v[38:39], v[44:45] op_sel_hi:[1,0,1]
	v_pk_fma_f32 v[32:33], v[32:33], v[38:39], v[42:43] op_sel_hi:[1,0,1]
	v_pk_mul_f32 v[30:31], v[30:31], v[178:179]
	v_pk_mul_f32 v[28:29], v[28:29], v[176:177]
	v_pk_fma_f32 v[42:43], v[30:31], v[38:39], v[48:49] op_sel_hi:[1,0,1]
	v_pk_fma_f32 v[30:31], v[28:29], v[38:39], v[46:47] op_sel_hi:[1,0,1]
	v_mul_f32_e32 v28, v33, v33
	v_mul_f32_e32 v29, v35, v35
	v_fmac_f32_e32 v28, v32, v32
	v_fmac_f32_e32 v29, v34, v34
	v_add_f32_e32 v28, v28, v29
	v_mul_f32_e32 v29, v31, v31
	v_mul_f32_e32 v39, v43, v43
	v_fmac_f32_e32 v29, v30, v30
	v_fmac_f32_e32 v39, v42, v42
	v_add_f32_e32 v29, v29, v39
	v_add_f32_e32 v39, v28, v29
	v_cvt_pk_bf16_f32 v28, v32, v33
	v_cvt_pk_bf16_f32 v29, v34, v35
	v_lshlrev_b32_e32 v32, 16, v112
	v_and_b32_e32 v33, 0xffff0000, v112
	v_lshlrev_b32_e32 v34, 16, v113
	v_and_b32_e32 v35, 0xffff0000, v113
	v_pk_mul_f32 v[26:27], v[26:27], v[170:171]
	v_pk_mul_f32 v[24:25], v[24:25], v[168:169]
	v_cvt_pk_bf16_f32 v30, v30, v31
	v_cvt_pk_bf16_f32 v31, v42, v43
	v_lshlrev_b32_e32 v42, 16, v114
	v_and_b32_e32 v43, 0xffff0000, v114
	v_pk_fma_f32 v[26:27], v[26:27], v[38:39], v[34:35] op_sel_hi:[1,0,1]
	v_pk_fma_f32 v[24:25], v[24:25], v[38:39], v[32:33] op_sel_hi:[1,0,1]
	v_pk_mul_f32 v[20:21], v[20:21], v[164:165]
	v_lshlrev_b32_e32 v44, 16, v115
	v_and_b32_e32 v45, 0xffff0000, v115
	v_pk_mul_f32 v[22:23], v[22:23], v[166:167]
	v_pk_fma_f32 v[34:35], v[20:21], v[38:39], v[42:43] op_sel_hi:[1,0,1]
	v_mul_f32_e32 v20, v25, v25
	v_mul_f32_e32 v21, v27, v27
	v_pk_fma_f32 v[32:33], v[22:23], v[38:39], v[44:45] op_sel_hi:[1,0,1]
	v_fmac_f32_e32 v20, v24, v24
	v_fmac_f32_e32 v21, v26, v26
	v_add_f32_e32 v20, v20, v21
	v_mul_f32_e32 v21, v35, v35
	v_mul_f32_e32 v22, v33, v33
	v_fmac_f32_e32 v21, v34, v34
	v_fmac_f32_e32 v22, v32, v32
	v_add_f32_e32 v21, v21, v22
	v_add_f32_e32 v20, v20, v21
	v_add_f32_e32 v23, v39, v20
	ds_bpermute_b32 v42, v3, v23
	v_add_u32_e32 v36, 0xa0, v220
	v_ashrrev_i32_e32 v37, 31, v36
	v_lshlrev_b64 v[40:41], 11, v[36:37]
	v_lshl_add_u64 v[20:21], s[62:63], 0, v[40:41]
	v_lshl_add_u64 v[38:39], v[218:219], 1, v[20:21]
	s_waitcnt lgkmcnt(0)
	v_add_f32_e32 v20, v23, v42
	ds_bpermute_b32 v21, v226, v20
	global_store_dwordx4 v[38:39], v[28:31], off sc1
	v_cvt_pk_bf16_f32 v22, v24, v25
	v_cvt_pk_bf16_f32 v23, v26, v27
	v_cvt_pk_bf16_f32 v24, v34, v35
	v_cvt_pk_bf16_f32 v25, v32, v33
	global_store_dwordx4 v[38:39], v[22:25], off offset:256 sc1
	s_and_saveexec_b64 s[10:11], s[0:1]
	s_cbranch_execz .LBB0_984
	s_waitcnt lgkmcnt(0)
	v_add_f32_e32 v22, v20, v21
	v_lshlrev_b64 v[20:21], 6, v[36:37]
	v_lshl_add_u64 v[20:21], s[86:87], 0, v[20:21]
	v_lshl_add_u64 v[20:21], s[4:5], 2, v[20:21]
	v_lshl_add_u64 v[20:21], v[20:21], 0, s[6:7]
	global_store_dword v[20:21], v22, off sc1
.LBB0_984:
	s_or_b64 exec, exec, s[10:11]
	ds_read_b32 v22, v227 offset:4800
	v_lshlrev_b32_e32 v26, 16, v100
	v_and_b32_e32 v27, 0xffff0000, v100
	v_lshlrev_b32_e32 v28, 16, v101
	v_and_b32_e32 v29, 0xffff0000, v101
	v_pk_mul_f32 v[18:19], v[18:19], v[182:183]
	v_pk_mul_f32 v[16:17], v[16:17], v[180:181]
	v_lshlrev_b32_e32 v30, 16, v102
	v_and_b32_e32 v31, 0xffff0000, v102
	v_lshlrev_b32_e32 v32, 16, v103
	v_and_b32_e32 v33, 0xffff0000, v103
	s_waitcnt lgkmcnt(0)
	v_pk_fma_f32 v[18:19], v[18:19], v[22:23], v[28:29] op_sel_hi:[1,0,1]
	v_pk_fma_f32 v[16:17], v[16:17], v[22:23], v[26:27] op_sel_hi:[1,0,1]
	v_pk_mul_f32 v[14:15], v[14:15], v[178:179]
	v_pk_mul_f32 v[12:13], v[12:13], v[176:177]
	v_pk_fma_f32 v[26:27], v[14:15], v[22:23], v[32:33] op_sel_hi:[1,0,1]
	v_pk_fma_f32 v[14:15], v[12:13], v[22:23], v[30:31] op_sel_hi:[1,0,1]
	v_mul_f32_e32 v12, v17, v17
	v_mul_f32_e32 v13, v19, v19
	v_fmac_f32_e32 v12, v16, v16
	v_fmac_f32_e32 v13, v18, v18
	v_add_f32_e32 v12, v12, v13
	v_mul_f32_e32 v13, v15, v15
	v_mul_f32_e32 v23, v27, v27
	v_fmac_f32_e32 v13, v14, v14
	v_fmac_f32_e32 v23, v26, v26
	v_add_f32_e32 v13, v13, v23
	v_add_f32_e32 v23, v12, v13
	v_cvt_pk_bf16_f32 v12, v16, v17
	v_cvt_pk_bf16_f32 v13, v18, v19
	v_lshlrev_b32_e32 v16, 16, v92
	v_and_b32_e32 v17, 0xffff0000, v92
	v_lshlrev_b32_e32 v18, 16, v93
	v_and_b32_e32 v19, 0xffff0000, v93
	v_pk_mul_f32 v[10:11], v[10:11], v[170:171]
	v_pk_mul_f32 v[8:9], v[8:9], v[168:169]
	v_cvt_pk_bf16_f32 v14, v14, v15
	v_cvt_pk_bf16_f32 v15, v26, v27
	v_lshlrev_b32_e32 v26, 16, v94
	v_and_b32_e32 v27, 0xffff0000, v94
	v_pk_fma_f32 v[10:11], v[10:11], v[22:23], v[18:19] op_sel_hi:[1,0,1]
	v_pk_fma_f32 v[8:9], v[8:9], v[22:23], v[16:17] op_sel_hi:[1,0,1]
	v_pk_mul_f32 v[4:5], v[4:5], v[164:165]
	v_lshlrev_b32_e32 v28, 16, v95
	v_and_b32_e32 v29, 0xffff0000, v95
	v_pk_mul_f32 v[6:7], v[6:7], v[166:167]
	v_pk_fma_f32 v[18:19], v[4:5], v[22:23], v[26:27] op_sel_hi:[1,0,1]
	v_mul_f32_e32 v4, v9, v9
	v_mul_f32_e32 v5, v11, v11
	v_pk_fma_f32 v[16:17], v[6:7], v[22:23], v[28:29] op_sel_hi:[1,0,1]
	v_fmac_f32_e32 v4, v8, v8
	v_fmac_f32_e32 v5, v10, v10
	v_add_f32_e32 v4, v4, v5
	v_mul_f32_e32 v5, v19, v19
	v_mul_f32_e32 v6, v17, v17
	v_fmac_f32_e32 v5, v18, v18
	v_fmac_f32_e32 v6, v16, v16
	v_add_f32_e32 v5, v5, v6
	v_add_f32_e32 v4, v4, v5
	v_add_f32_e32 v7, v23, v4
	ds_bpermute_b32 v3, v3, v7
	v_add_u32_e32 v20, 0xb0, v220
	v_ashrrev_i32_e32 v21, 31, v20
	v_lshlrev_b64 v[24:25], 11, v[20:21]
	v_lshl_add_u64 v[4:5], s[62:63], 0, v[24:25]
	s_waitcnt lgkmcnt(0)
	v_add_f32_e32 v3, v7, v3
	v_lshl_add_u64 v[22:23], v[218:219], 1, v[4:5]
	ds_bpermute_b32 v4, v226, v3
	global_store_dwordx4 v[22:23], v[12:15], off sc1
	v_cvt_pk_bf16_f32 v6, v8, v9
	v_cvt_pk_bf16_f32 v7, v10, v11
	v_cvt_pk_bf16_f32 v8, v18, v19
	v_cvt_pk_bf16_f32 v9, v16, v17
	global_store_dwordx4 v[22:23], v[6:9], off offset:256 sc1
	s_and_saveexec_b64 s[10:11], s[0:1]
	s_cbranch_execz .LBB0_986
	s_waitcnt lgkmcnt(0)
	v_add_f32_e32 v3, v3, v4
	v_lshlrev_b64 v[4:5], 6, v[20:21]
	v_lshl_add_u64 v[4:5], s[86:87], 0, v[4:5]
	v_lshl_add_u64 v[4:5], s[4:5], 2, v[4:5]
	v_lshl_add_u64 v[4:5], v[4:5], 0, s[6:7]
	global_store_dword v[4:5], v3, off sc1

.LBB0_1067:
	global_load_dwordx4 v[14:17], v[8:9], off
	s_nop 0
	global_load_dwordx4 v[8:11], v[148:149], off
	s_waitcnt vmcnt(1)
	v_mov_b32_e32 v18, v15
	v_mov_b32_e32 v19, v16
	v_mov_b32_e32 v15, v17
	v_pk_add_f32 v[14:15], v[18:19], v[14:15]
	s_nop 0
	v_add_f32_e32 v14, v14, v15
	v_add_f32_e32 v13, v13, v14
	v_fmamk_f32 v13, v13, 0x3a800000, v185
	v_mul_f32_e32 v14, 0x4f800000, v13
	v_cmp_gt_f32_e32 vcc, s50, v13
	s_nop 1
	v_cndmask_b32_e32 v13, v13, v14, vcc
	v_sqrt_f32_e32 v14, v13
	s_nop 0
	v_add_u32_e32 v15, -1, v14
	v_add_u32_e32 v16, 1, v14
	v_fma_f32 v17, -v15, v14, v13
	v_fma_f32 v18, -v16, v14, v13
	v_cmp_ge_f32_e64 s[6:7], 0, v17
	s_nop 1
	v_cndmask_b32_e64 v14, v14, v15, s[6:7]
	v_cmp_lt_f32_e64 s[6:7], 0, v18
	s_nop 1
	v_cndmask_b32_e64 v14, v14, v16, s[6:7]
	v_mul_f32_e32 v15, 0x37800000, v14
	v_cndmask_b32_e32 v14, v14, v15, vcc
	v_cmp_class_f32_e32 vcc, v13, v186
	s_nop 1
	v_cndmask_b32_e32 v13, v14, v13, vcc
	v_div_scale_f32 v16, s[6:7], v13, v13, 1.0
	v_rcp_f32_e32 v17, v16
	v_div_scale_f32 v18, vcc, 1.0, v13, 1.0
	v_mov_b64_e32 v[14:15], s[30:31]
	v_fma_f32 v19, -v16, v17, 1.0
	v_fmac_f32_e32 v17, v19, v17
	v_mul_f32_e32 v19, v18, v17
	v_fma_f32 v20, -v16, v19, v18
	v_fmac_f32_e32 v19, v20, v17
	v_fma_f32 v16, -v16, v19, v18
	v_div_fmas_f32 v16, v16, v17, v19
	v_div_fixup_f32 v13, v16, v13, 1.0
	s_waitcnt vmcnt(0)
	v_fma_f32 v8, v4, v13, v8
	v_fma_f32 v9, v5, v13, v9
	v_mul_f32_e64 v4, |v8|, s51
	v_mul_f32_e64 v5, |v9|, s51
	v_fma_f32 v16, |v8|, s51, -v4
	v_rndne_f32_e32 v17, v4
	v_fma_f32 v18, |v9|, s51, -v5
	v_rndne_f32_e32 v19, v5
	v_fma_f32 v16, |v8|, s58, v16
	v_sub_f32_e32 v4, v4, v17
	v_fma_f32 v18, |v9|, s58, v18
	v_sub_f32_e32 v5, v5, v19
	v_add_f32_e32 v4, v4, v16
	v_cvt_i32_f32_e32 v17, v17
	v_add_f32_e32 v5, v5, v18
	v_exp_f32_e32 v16, v4
	v_cvt_i32_f32_e32 v19, v19
	v_exp_f32_e32 v18, v5
	v_cmp_ngt_f32_e64 vcc, |v8|, s59
	v_ldexp_f32 v16, v16, v17
	v_min_f32_e32 v4, 0, v8
	v_ldexp_f32 v17, v18, v19
	v_cndmask_b32_e32 v16, 0, v16, vcc
	v_cmp_ngt_f32_e64 vcc, |v9|, s59
	v_min_f32_e32 v5, 0, v9
	v_fma_f32 v10, v6, v13, v10
	v_cndmask_b32_e32 v17, 0, v17, vcc
	v_cmp_nlt_f32_e64 vcc, |v8|, s60
	v_mul_f32_e64 v6, |v10|, s51
	v_fmac_f32_e32 v11, v7, v13
	v_cndmask_b32_e32 v42, v188, v16, vcc
	v_cmp_nlt_f32_e64 vcc, |v9|, s60
	v_add_f32_e32 v18, 1.0, v42
	v_add_f32_e32 v20, -1.0, v18
	v_cndmask_b32_e32 v43, v188, v17, vcc
	v_add_f32_e32 v19, 1.0, v43
	v_frexp_mant_f32_e32 v23, v19
	v_cvt_f64_f32_e32 v[16:17], v19
	v_frexp_exp_i32_f64_e32 v16, v[16:17]
	v_cmp_gt_f32_e32 vcc, s64, v23
	v_frexp_mant_f32_e32 v21, v18
	v_cvt_f64_f32_e32 v[8:9], v18
	v_add_f32_e32 v22, -1.0, v19
	v_subbrev_co_u32_e32 v16, vcc, 0, v16, vcc
	v_sub_f32_e32 v24, v20, v18
	v_frexp_exp_i32_f64_e32 v8, v[8:9]
	v_sub_f32_e32 v9, v22, v19
	v_cmp_gt_f32_e32 vcc, s64, v21
	v_sub_f32_e32 v20, v42, v20
	v_sub_f32_e32 v22, v43, v22
	v_add_f32_e32 v17, 1.0, v24
	v_add_f32_e32 v9, 1.0, v9
	v_subbrev_co_u32_e32 v8, vcc, 0, v8, vcc
	v_add_f32_e32 v17, v20, v17
	v_add_f32_e32 v20, v22, v9
	v_sub_u32_e32 v21, 0, v8
	v_sub_u32_e32 v22, 0, v16
	v_cvt_f32_i32_e32 v9, v16
	v_cvt_f32_i32_e32 v8, v8
	v_ldexp_f32 v16, v18, v21
	v_ldexp_f32 v18, v17, v21
	v_ldexp_f32 v17, v19, v22
	v_ldexp_f32 v19, v20, v22
	v_pk_add_f32 v[20:21], v[16:17], 1.0 op_sel_hi:[1,0]
	v_pk_add_f32 v[22:23], v[16:17], -1.0 op_sel_hi:[1,0]
	v_pk_add_f32 v[24:25], v[20:21], -1.0 op_sel_hi:[1,0]
	v_pk_add_f32 v[26:27], v[22:23], 1.0 op_sel_hi:[1,0]
	v_pk_add_f32 v[24:25], v[16:17], v[24:25] neg_lo:[0,1] neg_hi:[0,1]
	v_pk_add_f32 v[16:17], v[16:17], v[26:27] neg_lo:[0,1] neg_hi:[0,1]
	v_pk_mul_f32 v[26:27], v[8:9], s[38:39] op_sel_hi:[1,0]
	v_pk_add_f32 v[24:25], v[18:19], v[24:25]
	v_pk_add_f32 v[16:17], v[18:19], v[16:17]
	v_pk_fma_f32 v[18:19], v[8:9], s[38:39], v[26:27] op_sel_hi:[1,0,1] neg_lo:[0,0,1] neg_hi:[0,0,1]
	v_pk_add_f32 v[28:29], v[20:21], v[24:25]
	v_pk_fma_f32 v[8:9], v[8:9], s[40:41], v[18:19] op_sel_hi:[1,0,1]
	v_rcp_f32_e32 v18, v28
	v_rcp_f32_e32 v19, v29
	v_pk_add_f32 v[30:31], v[22:23], v[16:17]
	v_pk_add_f32 v[20:21], v[20:21], v[28:29] neg_lo:[0,1] neg_hi:[0,1]
	v_pk_add_f32 v[22:23], v[22:23], v[30:31] neg_lo:[0,1] neg_hi:[0,1]
	v_pk_add_f32 v[20:21], v[24:25], v[20:21]
	v_pk_add_f32 v[16:17], v[16:17], v[22:23]
	v_pk_mul_f32 v[22:23], v[30:31], v[18:19]
	v_pk_add_f32 v[32:33], v[26:27], v[8:9]
	v_pk_mul_f32 v[24:25], v[28:29], v[22:23]
	v_mov_b32_e32 v41, v33
	v_pk_fma_f32 v[34:35], v[22:23], v[28:29], v[24:25] neg_lo:[0,0,1] neg_hi:[0,0,1]
	v_cmp_neq_f32_e32 vcc, s61, v42
	v_pk_fma_f32 v[34:35], v[22:23], v[20:21], v[34:35]
	v_mul_f32_e64 v7, |v11|, s51
	v_pk_add_f32 v[36:37], v[24:25], v[34:35]
	s_nop 0
	v_pk_add_f32 v[38:39], v[30:31], v[36:37] neg_lo:[0,1] neg_hi:[0,1]
	v_pk_add_f32 v[24:25], v[36:37], v[24:25] neg_lo:[0,1] neg_hi:[0,1]
	v_pk_add_f32 v[30:31], v[30:31], v[38:39] neg_lo:[0,1] neg_hi:[0,1]
	v_pk_add_f32 v[24:25], v[24:25], v[34:35] neg_lo:[0,1] neg_hi:[0,1]
	v_pk_add_f32 v[30:31], v[30:31], v[36:37] neg_lo:[0,1] neg_hi:[0,1]
	s_nop 0
	v_pk_add_f32 v[16:17], v[16:17], v[30:31]
	s_nop 0
	v_pk_add_f32 v[16:17], v[24:25], v[16:17]
	s_nop 0
	v_pk_add_f32 v[24:25], v[38:39], v[16:17]
	s_nop 0
	v_pk_mul_f32 v[30:31], v[18:19], v[24:25]
	v_pk_add_f32 v[34:35], v[38:39], v[24:25] neg_lo:[0,1] neg_hi:[0,1]
	v_pk_mul_f32 v[36:37], v[28:29], v[30:31]
	v_pk_add_f32 v[16:17], v[16:17], v[34:35]
	v_pk_fma_f32 v[28:29], v[30:31], v[28:29], v[36:37] neg_lo:[0,0,1] neg_hi:[0,0,1]
	v_pk_add_f32 v[34:35], v[22:23], v[30:31]
	v_pk_fma_f32 v[20:21], v[30:31], v[20:21], v[28:29]
	v_pk_add_f32 v[22:23], v[34:35], v[22:23] neg_lo:[0,1] neg_hi:[0,1]
	v_pk_add_f32 v[28:29], v[36:37], v[20:21]
	v_pk_add_f32 v[22:23], v[30:31], v[22:23] neg_lo:[0,1] neg_hi:[0,1]
	v_pk_add_f32 v[30:31], v[28:29], v[36:37] neg_lo:[0,1] neg_hi:[0,1]
	v_pk_add_f32 v[36:37], v[24:25], v[28:29] neg_lo:[0,1] neg_hi:[0,1]
	v_pk_add_f32 v[20:21], v[30:31], v[20:21] neg_lo:[0,1] neg_hi:[0,1]
	v_pk_add_f32 v[24:25], v[24:25], v[36:37] neg_lo:[0,1] neg_hi:[0,1]
	v_mov_b32_e32 v30, v32
	v_pk_add_f32 v[24:25], v[24:25], v[28:29] neg_lo:[0,1] neg_hi:[0,1]
	v_mov_b32_e32 v28, v8
	v_pk_add_f32 v[16:17], v[16:17], v[24:25]
	v_mov_b32_e32 v31, v27
	v_pk_add_f32 v[16:17], v[20:21], v[16:17]
	s_nop 0
	v_pk_add_f32 v[16:17], v[36:37], v[16:17]
	s_nop 0
	v_pk_mul_f32 v[16:17], v[18:19], v[16:17]
	s_nop 0
	v_pk_add_f32 v[16:17], v[22:23], v[16:17]
	s_nop 0
	v_pk_add_f32 v[18:19], v[34:35], v[16:17]
	s_nop 0
	v_pk_add_f32 v[20:21], v[18:19], v[34:35] neg_lo:[0,1] neg_hi:[0,1]
	v_pk_mul_f32 v[24:25], v[18:19], v[18:19]
	v_pk_add_f32 v[16:17], v[16:17], v[20:21] neg_lo:[0,1] neg_hi:[0,1]
	v_pk_fma_f32 v[20:21], v[24:25], s[34:35], v[14:15] op_sel_hi:[1,0,0]
	v_ldexp_f32 v22, v18, 1
	v_ldexp_f32 v23, v19, 1
	v_pk_mul_f32 v[18:19], v[18:19], v[24:25]
	v_pk_fma_f32 v[20:21], v[24:25], v[20:21], s[36:37] op_sel_hi:[1,1,0]
	v_mov_b32_e32 v29, v23
	v_pk_mul_f32 v[18:19], v[18:19], v[20:21]
	v_ldexp_f32 v16, v16, 1
	v_pk_add_f32 v[20:21], v[22:23], v[18:19]
	v_ldexp_f32 v17, v17, 1
	v_pk_add_f32 v[22:23], v[20:21], v[22:23] neg_lo:[0,1] neg_hi:[0,1]
	v_mov_b32_e32 v25, v19
	v_pk_add_f32 v[18:19], v[18:19], v[22:23] neg_lo:[0,1] neg_hi:[0,1]
	v_mov_b32_e32 v24, v26
	v_pk_add_f32 v[22:23], v[16:17], v[18:19]
	v_mov_b32_e32 v18, v26
	v_mov_b32_e32 v16, v8
	v_pk_add_f32 v[24:25], v[24:25], v[28:29]
	v_pk_add_f32 v[28:29], v[18:19], v[16:17]
	v_mov_b32_e32 v16, v20
	v_mov_b32_e32 v18, v22
	v_pk_add_f32 v[16:17], v[16:17], v[18:19]
	v_pk_add_f32 v[18:19], v[20:21], v[22:23]
	v_mov_b32_e32 v35, v9
	v_mov_b32_e32 v34, v18
	v_pk_add_f32 v[16:17], v[24:25], v[16:17]
	v_pk_add_f32 v[24:25], v[32:33], v[18:19]
	v_pk_add_f32 v[36:37], v[30:31], v[34:35]
	v_mov_b32_e32 v38, v18
	v_mov_b32_e32 v39, v25
	v_mov_b32_e32 v40, v20
	v_pk_add_f32 v[30:31], v[36:37], v[30:31] neg_lo:[0,1] neg_hi:[0,1]
	v_pk_add_f32 v[38:39], v[38:39], v[40:41] neg_lo:[0,1] neg_hi:[0,1]
	v_pk_add_f32 v[36:37], v[32:33], v[26:27] neg_lo:[0,1] neg_hi:[0,1]
	v_pk_add_f32 v[34:35], v[34:35], v[30:31] neg_lo:[0,1] neg_hi:[0,1]
	v_mov_b32_e32 v40, v32
	v_mov_b32_e32 v41, v25
	v_mov_b32_e32 v27, v39
	v_mov_b32_e32 v31, v21
	v_pk_add_f32 v[20:21], v[18:19], v[20:21] neg_lo:[0,1] neg_hi:[0,1]
	v_pk_add_f32 v[26:27], v[40:41], v[26:27] neg_lo:[0,1] neg_hi:[0,1]
	v_pk_add_f32 v[36:37], v[8:9], v[36:37] neg_lo:[0,1] neg_hi:[0,1]
	v_pk_add_f32 v[16:17], v[16:17], v[30:31] neg_lo:[0,1] neg_hi:[0,1]
	v_pk_add_f32 v[20:21], v[22:23], v[20:21] neg_lo:[0,1] neg_hi:[0,1]
	v_mov_b32_e32 v9, v33
	v_mov_b32_e32 v23, v19
	v_pk_add_f32 v[16:17], v[28:29], v[16:17] neg_lo:[0,1] neg_hi:[0,1]
	v_pk_add_f32 v[8:9], v[8:9], v[26:27] neg_lo:[0,1] neg_hi:[0,1]
	v_pk_add_f32 v[18:19], v[22:23], v[38:39] neg_lo:[0,1] neg_hi:[0,1]
	v_pk_add_f32 v[26:27], v[34:35], v[16:17]
	v_pk_add_f32 v[22:23], v[18:19], v[8:9]
	v_mov_b32_e32 v19, v17
	v_pk_add_f32 v[16:17], v[36:37], v[18:19]
	v_mov_b32_e32 v9, v35
	v_pk_add_f32 v[16:17], v[16:17], v[8:9] neg_lo:[0,1] neg_hi:[0,1]
	v_mov_b32_e32 v18, v22
	v_mov_b32_e32 v19, v27
	v_pk_add_f32 v[18:19], v[18:19], v[16:17] neg_lo:[0,1] neg_hi:[0,1]
	v_pk_add_f32 v[16:17], v[20:21], v[16:17] neg_lo:[0,1] neg_hi:[0,1]
	v_pk_add_f32 v[8:9], v[8:9], v[18:19] neg_lo:[0,1] neg_hi:[0,1]
	s_nop 0
	v_pk_add_f32 v[8:9], v[16:17], v[8:9]
	v_pk_add_f32 v[16:17], v[26:27], v[22:23]
	s_nop 0
	v_pk_add_f32 v[18:19], v[24:25], v[16:17]
	s_nop 0
	v_pk_add_f32 v[20:21], v[18:19], v[24:25] neg_lo:[0,1] neg_hi:[0,1]
	s_nop 0
	v_pk_add_f32 v[16:17], v[16:17], v[20:21] neg_lo:[0,1] neg_hi:[0,1]
	s_nop 0
	v_pk_add_f32 v[8:9], v[8:9], v[16:17]
	v_fma_f32 v16, |v10|, s51, -v6
	v_rndne_f32_e32 v17, v6
	v_fma_f32 v16, |v10|, s58, v16
	v_sub_f32_e32 v6, v6, v17
	v_pk_add_f32 v[8:9], v[18:19], v[8:9]
	v_add_f32_e32 v6, v6, v16
	v_cndmask_b32_e32 v8, v188, v8, vcc
	v_cmp_neq_f32_e32 vcc, s61, v43
	v_exp_f32_e32 v16, v6
	v_cvt_i32_f32_e32 v17, v17
	v_cndmask_b32_e32 v9, v188, v9, vcc
	v_cmp_lt_f32_e64 vcc, |v43|, s65
	v_min_f32_e32 v6, 0, v10
	s_nop 0
	v_cndmask_b32_e32 v9, v9, v43, vcc
	v_cmp_lt_f32_e64 vcc, |v42|, s65
	s_nop 1
	v_cndmask_b32_e32 v8, v8, v42, vcc
	v_pk_add_f32 v[4:5], v[4:5], v[8:9] neg_lo:[0,1] neg_hi:[0,1]
	v_ldexp_f32 v8, v16, v17
	v_cmp_ngt_f32_e64 vcc, |v10|, s59
	s_nop 1
	v_cndmask_b32_e32 v8, 0, v8, vcc
	v_cmp_nlt_f32_e64 vcc, |v10|, s60
	s_nop 1
	v_cndmask_b32_e32 v38, v188, v8, vcc
	v_add_f32_e32 v10, 1.0, v38
	v_add_f32_e32 v8, -1.0, v10
	v_sub_f32_e32 v9, v8, v10
	v_add_f32_e32 v9, 1.0, v9
	v_sub_f32_e32 v8, v38, v8
	v_add_f32_e32 v16, v8, v9
	v_fma_f32 v8, |v11|, s51, -v7
	v_rndne_f32_e32 v9, v7
	v_fma_f32 v8, |v11|, s58, v8
	v_sub_f32_e32 v7, v7, v9
	v_add_f32_e32 v7, v7, v8
	v_exp_f32_e32 v13, v7
	v_cvt_i32_f32_e32 v18, v9
	v_cvt_f64_f32_e32 v[8:9], v10
	v_frexp_exp_i32_f64_e32 v19, v[8:9]
	v_cmp_ngt_f32_e64 vcc, |v11|, s59
	v_ldexp_f32 v8, v13, v18
	v_min_f32_e32 v7, 0, v11
	v_cndmask_b32_e32 v8, 0, v8, vcc
	v_cmp_nlt_f32_e64 vcc, |v11|, s60
	v_frexp_mant_f32_e32 v17, v10
	s_nop 0
	v_cndmask_b32_e32 v13, v188, v8, vcc
	v_add_f32_e32 v11, 1.0, v13
	v_add_f32_e32 v8, -1.0, v11
	v_sub_f32_e32 v9, v8, v11
	v_add_f32_e32 v9, 1.0, v9
	v_sub_f32_e32 v8, v13, v8
	v_add_f32_e32 v18, v8, v9
	v_frexp_mant_f32_e32 v20, v11
	v_cvt_f64_f32_e32 v[8:9], v11
	v_frexp_exp_i32_f64_e32 v8, v[8:9]
	v_cmp_gt_f32_e32 vcc, s64, v20
	s_nop 1
	v_subbrev_co_u32_e32 v32, vcc, 0, v8, vcc
	v_cmp_gt_f32_e32 vcc, s64, v17
	s_nop 1
	v_subbrev_co_u32_e32 v33, vcc, 0, v19, vcc
	v_sub_u32_e32 v9, 0, v33
	v_ldexp_f32 v8, v10, v9
	v_ldexp_f32 v10, v16, v9
	v_sub_u32_e32 v16, 0, v32
	v_ldexp_f32 v9, v11, v16
	v_ldexp_f32 v11, v18, v16
	v_pk_add_f32 v[16:17], v[8:9], 1.0 op_sel_hi:[1,0]
	v_pk_add_f32 v[24:25], v[8:9], -1.0 op_sel_hi:[1,0]
	v_pk_add_f32 v[18:19], v[16:17], -1.0 op_sel_hi:[1,0]
	v_pk_add_f32 v[26:27], v[24:25], 1.0 op_sel_hi:[1,0]
	v_pk_add_f32 v[18:19], v[8:9], v[18:19] neg_lo:[0,1] neg_hi:[0,1]
	v_pk_add_f32 v[8:9], v[8:9], v[26:27] neg_lo:[0,1] neg_hi:[0,1]
	v_pk_add_f32 v[18:19], v[10:11], v[18:19]
	v_pk_add_f32 v[8:9], v[10:11], v[8:9]
	v_pk_add_f32 v[20:21], v[16:17], v[18:19]
	v_pk_add_f32 v[10:11], v[24:25], v[8:9]
	v_rcp_f32_e32 v22, v20
	v_rcp_f32_e32 v23, v21
	v_pk_add_f32 v[16:17], v[16:17], v[20:21] neg_lo:[0,1] neg_hi:[0,1]
	v_pk_add_f32 v[24:25], v[24:25], v[10:11] neg_lo:[0,1] neg_hi:[0,1]
	v_pk_add_f32 v[16:17], v[18:19], v[16:17]
	v_pk_mul_f32 v[18:19], v[10:11], v[22:23]
	v_pk_add_f32 v[8:9], v[8:9], v[24:25]
	v_pk_mul_f32 v[24:25], v[20:21], v[18:19]
	v_cmp_neq_f32_e32 vcc, s61, v38
	v_pk_fma_f32 v[26:27], v[18:19], v[20:21], v[24:25] neg_lo:[0,0,1] neg_hi:[0,0,1]
	s_nop 0
	v_pk_fma_f32 v[26:27], v[18:19], v[16:17], v[26:27]
	s_nop 0
	v_pk_add_f32 v[28:29], v[24:25], v[26:27]
	s_nop 0
	v_pk_add_f32 v[30:31], v[10:11], v[28:29] neg_lo:[0,1] neg_hi:[0,1]
	v_pk_add_f32 v[24:25], v[28:29], v[24:25] neg_lo:[0,1] neg_hi:[0,1]
	v_pk_add_f32 v[10:11], v[10:11], v[30:31] neg_lo:[0,1] neg_hi:[0,1]
	s_nop 0
	v_pk_add_f32 v[10:11], v[10:11], v[28:29] neg_lo:[0,1] neg_hi:[0,1]
	s_nop 0
	v_pk_add_f32 v[8:9], v[8:9], v[10:11]
	v_pk_add_f32 v[10:11], v[24:25], v[26:27] neg_lo:[0,1] neg_hi:[0,1]
	s_nop 0
	v_pk_add_f32 v[8:9], v[10:11], v[8:9]
	s_nop 0
	v_pk_add_f32 v[10:11], v[30:31], v[8:9]
	s_nop 0
	v_pk_mul_f32 v[24:25], v[22:23], v[10:11]
	s_nop 0
	v_pk_mul_f32 v[26:27], v[20:21], v[24:25]
	s_nop 0
	v_pk_fma_f32 v[20:21], v[24:25], v[20:21], v[26:27] neg_lo:[0,0,1] neg_hi:[0,0,1]
	s_nop 0
	v_pk_fma_f32 v[16:17], v[24:25], v[16:17], v[20:21]
	v_pk_add_f32 v[20:21], v[30:31], v[10:11] neg_lo:[0,1] neg_hi:[0,1]
	s_nop 0
	v_pk_add_f32 v[8:9], v[8:9], v[20:21]
	v_pk_add_f32 v[20:21], v[26:27], v[16:17]
	s_nop 0
	v_pk_add_f32 v[28:29], v[10:11], v[20:21] neg_lo:[0,1] neg_hi:[0,1]
	v_pk_add_f32 v[26:27], v[20:21], v[26:27] neg_lo:[0,1] neg_hi:[0,1]
	v_pk_add_f32 v[10:11], v[10:11], v[28:29] neg_lo:[0,1] neg_hi:[0,1]
	s_nop 0
	v_pk_add_f32 v[10:11], v[10:11], v[20:21] neg_lo:[0,1] neg_hi:[0,1]
	s_nop 0
	v_pk_add_f32 v[8:9], v[8:9], v[10:11]
	v_pk_add_f32 v[10:11], v[26:27], v[16:17] neg_lo:[0,1] neg_hi:[0,1]
	s_nop 0
	v_pk_add_f32 v[8:9], v[10:11], v[8:9]
	v_pk_add_f32 v[10:11], v[18:19], v[24:25]
	v_pk_add_f32 v[8:9], v[28:29], v[8:9]
	v_pk_add_f32 v[16:17], v[10:11], v[18:19] neg_lo:[0,1] neg_hi:[0,1]
	v_pk_mul_f32 v[8:9], v[22:23], v[8:9]
	v_pk_add_f32 v[16:17], v[24:25], v[16:17] neg_lo:[0,1] neg_hi:[0,1]
	v_cvt_f32_i32_e32 v19, v32
	v_pk_add_f32 v[8:9], v[16:17], v[8:9]
	v_cvt_f32_i32_e32 v18, v33
	v_pk_add_f32 v[16:17], v[10:11], v[8:9]
	v_pk_mul_f32 v[22:23], v[18:19], s[38:39] op_sel_hi:[1,0]
	v_pk_mul_f32 v[20:21], v[16:17], v[16:17]
	v_pk_add_f32 v[10:11], v[16:17], v[10:11] neg_lo:[0,1] neg_hi:[0,1]
	v_pk_fma_f32 v[14:15], v[20:21], s[34:35], v[14:15] op_sel_hi:[1,0,0]
	v_pk_add_f32 v[8:9], v[8:9], v[10:11] neg_lo:[0,1] neg_hi:[0,1]
	v_ldexp_f32 v10, v16, 1
	v_pk_fma_f32 v[14:15], v[20:21], v[14:15], s[36:37] op_sel_hi:[1,1,0]
	v_ldexp_f32 v11, v17, 1
	v_pk_mul_f32 v[16:17], v[16:17], v[20:21]
	v_pk_fma_f32 v[24:25], v[18:19], s[38:39], v[22:23] op_sel_hi:[1,0,1] neg_lo:[0,0,1] neg_hi:[0,0,1]
	v_pk_mul_f32 v[14:15], v[16:17], v[14:15]
	v_mov_b32_e32 v27, v11
	v_pk_add_f32 v[16:17], v[10:11], v[14:15]
	v_ldexp_f32 v8, v8, 1
	v_pk_add_f32 v[10:11], v[16:17], v[10:11] neg_lo:[0,1] neg_hi:[0,1]
	v_pk_fma_f32 v[18:19], v[18:19], s[40:41], v[24:25] op_sel_hi:[1,0,1]
	v_ldexp_f32 v9, v9, 1
	v_pk_add_f32 v[10:11], v[14:15], v[10:11] neg_lo:[0,1] neg_hi:[0,1]
	v_mov_b32_e32 v20, v22
	v_mov_b32_e32 v21, v15
	v_mov_b32_e32 v26, v18
	v_pk_add_f32 v[14:15], v[8:9], v[10:11]
	v_mov_b32_e32 v10, v22
	v_mov_b32_e32 v8, v18
	v_pk_add_f32 v[20:21], v[20:21], v[26:27]
	v_pk_add_f32 v[26:27], v[10:11], v[8:9]
	v_mov_b32_e32 v8, v16
	v_mov_b32_e32 v10, v14
	v_pk_add_f32 v[24:25], v[22:23], v[18:19]
	v_pk_add_f32 v[8:9], v[8:9], v[10:11]
	v_pk_add_f32 v[10:11], v[16:17], v[14:15]
	v_mov_b32_e32 v28, v24
	v_mov_b32_e32 v29, v23
	v_mov_b32_e32 v30, v10
	v_mov_b32_e32 v31, v19
	v_pk_add_f32 v[8:9], v[20:21], v[8:9]
	v_pk_add_f32 v[20:21], v[24:25], v[10:11]
	v_pk_add_f32 v[32:33], v[28:29], v[30:31]
	v_mov_b32_e32 v34, v10
	v_mov_b32_e32 v35, v21
	v_mov_b32_e32 v36, v16
	v_mov_b32_e32 v37, v25
	v_pk_add_f32 v[28:29], v[32:33], v[28:29] neg_lo:[0,1] neg_hi:[0,1]
	v_pk_add_f32 v[34:35], v[34:35], v[36:37] neg_lo:[0,1] neg_hi:[0,1]
	v_pk_add_f32 v[32:33], v[24:25], v[22:23] neg_lo:[0,1] neg_hi:[0,1]
	v_pk_add_f32 v[30:31], v[30:31], v[28:29] neg_lo:[0,1] neg_hi:[0,1]
	v_mov_b32_e32 v36, v24
	v_mov_b32_e32 v37, v21
	v_mov_b32_e32 v23, v35
	v_mov_b32_e32 v29, v17
	v_pk_add_f32 v[16:17], v[10:11], v[16:17] neg_lo:[0,1] neg_hi:[0,1]
	v_pk_add_f32 v[22:23], v[36:37], v[22:23] neg_lo:[0,1] neg_hi:[0,1]
	v_pk_add_f32 v[32:33], v[18:19], v[32:33] neg_lo:[0,1] neg_hi:[0,1]
	v_pk_add_f32 v[8:9], v[8:9], v[28:29] neg_lo:[0,1] neg_hi:[0,1]
	v_pk_add_f32 v[16:17], v[14:15], v[16:17] neg_lo:[0,1] neg_hi:[0,1]
	v_mov_b32_e32 v19, v25
	v_mov_b32_e32 v15, v11
	v_pk_add_f32 v[8:9], v[26:27], v[8:9] neg_lo:[0,1] neg_hi:[0,1]
	v_pk_add_f32 v[18:19], v[18:19], v[22:23] neg_lo:[0,1] neg_hi:[0,1]
	v_pk_add_f32 v[10:11], v[14:15], v[34:35] neg_lo:[0,1] neg_hi:[0,1]
	v_pk_add_f32 v[22:23], v[30:31], v[8:9]
	v_pk_add_f32 v[14:15], v[10:11], v[18:19]
	v_mov_b32_e32 v11, v9
	v_pk_add_f32 v[8:9], v[32:33], v[10:11]
	v_mov_b32_e32 v19, v31
	v_pk_add_f32 v[8:9], v[8:9], v[18:19] neg_lo:[0,1] neg_hi:[0,1]
	v_mov_b32_e32 v10, v14
	v_mov_b32_e32 v11, v23
	v_pk_add_f32 v[10:11], v[10:11], v[8:9] neg_lo:[0,1] neg_hi:[0,1]
	v_pk_add_f32 v[8:9], v[16:17], v[8:9] neg_lo:[0,1] neg_hi:[0,1]
	v_pk_add_f32 v[10:11], v[18:19], v[10:11] neg_lo:[0,1] neg_hi:[0,1]
	s_nop 0
	v_pk_add_f32 v[8:9], v[8:9], v[10:11]
	v_pk_add_f32 v[10:11], v[22:23], v[14:15]
	s_nop 0
	v_pk_add_f32 v[14:15], v[20:21], v[10:11]
	s_nop 0
	v_pk_add_f32 v[16:17], v[14:15], v[20:21] neg_lo:[0,1] neg_hi:[0,1]
	s_nop 0
	v_pk_add_f32 v[10:11], v[10:11], v[16:17] neg_lo:[0,1] neg_hi:[0,1]
	s_nop 0
	v_pk_add_f32 v[8:9], v[8:9], v[10:11]
	s_nop 0
	v_pk_add_f32 v[8:9], v[14:15], v[8:9]
	s_nop 0
	v_cndmask_b32_e32 v8, v188, v8, vcc
	v_cmp_neq_f32_e32 vcc, s61, v13
	s_nop 1
	v_cndmask_b32_e32 v9, v188, v9, vcc
	v_cmp_lt_f32_e64 vcc, |v13|, s65
	s_nop 1
	v_cndmask_b32_e32 v9, v9, v13, vcc
	v_cmp_lt_f32_e64 vcc, |v38|, s65
	s_nop 1
	v_cndmask_b32_e32 v8, v8, v38, vcc
	v_pk_add_f32 v[6:7], v[6:7], v[8:9] neg_lo:[0,1] neg_hi:[0,1]
	s_and_saveexec_b64 s[6:7], s[4:5]
	s_xor_b64 s[4:5], exec, s[6:7]
	s_cbranch_execz .LBB0_1069
	v_add_u32_e32 v144, 0xffffc000, v12
	v_lshlrev_b64 v[8:9], 5, v[144:145]
	v_lshl_add_u64 v[8:9], v[150:151], 0, v[8:9]
	global_store_dwordx4 v[8:9], v[4:7], off sc1
.LBB0_1069:
	s_andn2_saveexec_b64 s[4:5], s[4:5]
	s_cbranch_execz .LBB0_1071
	v_ashrrev_i32_e32 v13, 31, v12
	v_lshlrev_b64 v[8:9], 5, v[12:13]
	v_lshl_add_u64 v[8:9], v[152:153], 0, v[8:9]
	global_store_dwordx4 v[8:9], v[4:7], off sc1

.LBB0_1079:
	v_lshlrev_b32_e32 v36, 14, v193
	v_lshlrev_b32_e32 v37, 12, v158
	v_add3_u32 v36, v184, v36, v37
	s_barrier
	s_nop 4
	ds_write2st64_b32 v36, v4, v5 offset1:1
	ds_write2st64_b32 v36, v6, v7 offset0:2 offset1:3
	ds_write2st64_b32 v36, v8, v9 offset0:4 offset1:5
	ds_write2st64_b32 v36, v10, v11 offset0:6 offset1:7
	ds_write2st64_b32 v36, v12, v13 offset0:8 offset1:9
	ds_write2st64_b32 v36, v14, v15 offset0:10 offset1:11
	ds_write2st64_b32 v36, v16, v17 offset0:12 offset1:13
	ds_write2st64_b32 v36, v18, v19 offset0:14 offset1:15
	ds_write2st64_b32 v36, v20, v21 offset0:16 offset1:17
	ds_write2st64_b32 v36, v22, v23 offset0:18 offset1:19
	ds_write2st64_b32 v36, v24, v25 offset0:20 offset1:21
	ds_write2st64_b32 v36, v26, v27 offset0:22 offset1:23
	ds_write2st64_b32 v36, v28, v29 offset0:24 offset1:25
	ds_write2st64_b32 v36, v30, v31 offset0:26 offset1:27
	ds_write2st64_b32 v36, v32, v33 offset0:28 offset1:29
	ds_write2st64_b32 v36, v34, v35 offset0:30 offset1:31
	v_lshrrev_b32_e32 v5, 3, v191
	v_lshlrev_b32_e32 v4, 3, v192
	v_and_b32_e32 v5, 0xfffff0, v5
	v_and_or_b32 v4, v4, 8, v5
	v_lshl_add_u32 v4, v4, 8, v184
	s_waitcnt lgkmcnt(0)
	s_barrier
	ds_read2st64_b32 v[52:53], v4 offset1:1
	ds_read2st64_b32 v[54:55], v4 offset0:2 offset1:3
	ds_read2st64_b32 v[8:9], v4 offset0:4 offset1:5
	ds_read2st64_b32 v[22:23], v4 offset0:6 offset1:7
	ds_read2st64_b32 v[56:57], v4 offset0:64 offset1:65
	ds_read2st64_b32 v[58:59], v4 offset0:66 offset1:67
	ds_read2st64_b32 v[18:19], v4 offset0:68 offset1:69
	ds_read2st64_b32 v[16:17], v4 offset0:70 offset1:71
	ds_read2st64_b32 v[60:61], v4 offset0:128 offset1:129
	ds_read2st64_b32 v[62:63], v4 offset0:130 offset1:131
	ds_read2st64_b32 v[10:11], v4 offset0:132 offset1:133
	ds_read2st64_b32 v[20:21], v4 offset0:134 offset1:135
	ds_read2st64_b32 v[64:65], v4 offset0:192 offset1:193
	ds_read2st64_b32 v[66:67], v4 offset0:194 offset1:195
	ds_read2st64_b32 v[14:15], v4 offset0:196 offset1:197
	ds_read2st64_b32 v[12:13], v4 offset0:198 offset1:199
	s_waitcnt lgkmcnt(0)
	s_barrier
	global_load_dwordx4 v[4:7], v[136:137], off
	global_load_dwordx4 v[24:27], v[136:137], off offset:16
	global_load_dwordx4 v[28:31], v[136:137], off offset:32
	global_load_dwordx4 v[32:35], v[136:137], off offset:48
	global_load_dwordx4 v[36:39], v[136:137], off offset:64
	global_load_dwordx4 v[40:43], v[136:137], off offset:80
	global_load_dwordx4 v[44:47], v[136:137], off offset:96
	global_load_dwordx4 v[48:51], v[136:137], off offset:112
	s_mov_b64 s[46:47], -1
	s_waitcnt vmcnt(7)
	v_mov_b32_e32 v68, v4
	s_waitcnt vmcnt(6)
	v_mov_b32_e32 v69, v24
	v_mov_b32_e32 v24, v5
	v_mov_b32_e32 v4, v6
	v_mov_b32_e32 v5, v26
	v_mov_b32_e32 v26, v7
	s_waitcnt vmcnt(5)
	v_mov_b32_e32 v6, v29
	v_mov_b32_e32 v7, v30
	v_mov_b32_e32 v29, v31
	v_pk_add_f32 v[24:25], v[68:69], v[24:25]
	v_pk_add_f32 v[4:5], v[4:5], v[26:27]
	v_pk_add_f32 v[6:7], v[6:7], v[28:29]
	v_pk_add_f32 v[4:5], v[24:25], v[4:5]
	v_pk_add_f32 v[6:7], v[6:7], v[6:7] op_sel:[0,1] op_sel_hi:[1,0]
	v_add_f32_e32 v4, 0, v4
	s_waitcnt vmcnt(4)
	v_add_f32_e32 v30, v32, v33
	v_add_f32_e32 v32, v34, v35
	s_waitcnt vmcnt(3)
	v_mov_b32_e32 v35, v36
	v_mov_b32_e32 v31, v38
	v_mov_b32_e32 v33, v39
	v_mov_b32_e32 v7, v37
	v_add_f32_e32 v34, v4, v5
	s_waitcnt vmcnt(2)
	v_mov_b32_e32 v38, v41
	v_mov_b32_e32 v39, v42
	v_mov_b32_e32 v41, v43
	v_pk_add_f32 v[26:27], v[30:31], v[32:33]
	v_pk_add_f32 v[4:5], v[34:35], v[6:7]
	v_pk_add_f32 v[28:29], v[38:39], v[40:41]
	v_pk_add_f32 v[4:5], v[4:5], v[26:27]
	v_pk_add_f32 v[24:25], v[28:29], v[28:29] op_sel:[0,1] op_sel_hi:[1,0]
	v_pk_add_f32 v[4:5], v[4:5], v[4:5] op_sel:[0,1] op_sel_hi:[1,0]
	s_waitcnt vmcnt(1)
	v_add_f32_e32 v42, v44, v45
	v_add_f32_e32 v36, v46, v47
	s_waitcnt vmcnt(0)
	v_mov_b32_e32 v43, v50
	v_mov_b32_e32 v25, v49
	v_mov_b32_e32 v5, v48
	v_mov_b32_e32 v37, v51
	v_pk_add_f32 v[4:5], v[4:5], v[24:25]
	v_pk_add_f32 v[6:7], v[42:43], v[36:37]
	s_nop 0
	v_pk_add_f32 v[4:5], v[4:5], v[6:7]
	s_nop 0
	v_add_f32_e32 v4, v4, v5
	v_fmamk_f32 v4, v4, 0x3a800000, v185
	v_mul_f32_e32 v5, 0x4f800000, v4
	v_cmp_gt_f32_e32 vcc, s50, v4
	s_nop 1
	v_cndmask_b32_e32 v4, v4, v5, vcc
	v_sqrt_f32_e32 v5, v4
	s_nop 0
	v_add_u32_e32 v6, -1, v5
	v_fma_f32 v7, -v6, v5, v4
	v_cmp_ge_f32_e64 s[4:5], 0, v7
	v_add_u32_e32 v7, 1, v5
	s_nop 0
	v_cndmask_b32_e64 v6, v5, v6, s[4:5]
	v_fma_f32 v5, -v7, v5, v4
	v_cmp_lt_f32_e64 s[4:5], 0, v5
	s_nop 1
	v_cndmask_b32_e64 v5, v6, v7, s[4:5]
	v_mul_f32_e32 v6, 0x37800000, v5
	v_cndmask_b32_e32 v5, v5, v6, vcc
	v_cmp_class_f32_e32 vcc, v4, v186
	s_nop 1
	v_cndmask_b32_e32 v4, v5, v4, vcc
	v_div_scale_f32 v5, s[4:5], v4, v4, 1.0
	v_rcp_f32_e32 v6, v5
	s_ashr_i32 s4, s68, 4
	s_and_b32 s5, s6, 0x1e0
	s_cmp_gt_i32 s4, 1
	v_fma_f32 v7, -v5, v6, 1.0
	v_fmac_f32_e32 v6, v7, v6
	v_div_scale_f32 v7, vcc, 1.0, v4, 1.0
	v_mul_f32_e32 v24, v7, v6
	v_fma_f32 v25, -v5, v24, v7
	v_fmac_f32_e32 v24, v25, v6
	v_fma_f32 v5, -v5, v24, v7
	v_div_fmas_f32 v5, v5, v6, v24
	v_div_fixup_f32 v24, v5, v4, 1.0
	s_cselect_b64 s[6:7], -1, 0
	s_cmp_eq_u32 s4, 2
	v_pk_add_f32 v[4:5], v[54:55], 0 op_sel_hi:[1,0]
	v_pk_add_f32 v[6:7], v[52:53], 0 op_sel_hi:[1,0]
	s_cselect_b32 s69, s66, 0x2066800
	s_cselect_b32 s16, s67, 0xda00000
	s_cmp_lt_u32 s68, 16
	v_pk_add_f32 v[6:7], v[6:7], v[56:57]
	v_pk_add_f32 v[4:5], v[4:5], v[58:59]
	v_or_b32_e32 v25, s5, v133
	s_cselect_b64 s[4:5], -1, 0
	v_pk_add_f32 v[4:5], v[4:5], v[62:63]
	v_pk_add_f32 v[6:7], v[6:7], v[60:61]
	s_and_b64 s[44:45], s[4:5], exec
	v_pk_add_f32 v[26:27], v[6:7], v[64:65]
	v_pk_add_f32 v[4:5], v[4:5], v[66:67]
	s_cselect_b32 s45, s11, s13
	s_cselect_b32 s44, s10, s12
	v_pk_mul_f32 v[6:7], v[4:5], v[24:25] op_sel_hi:[1,0]
	v_pk_mul_f32 v[4:5], v[26:27], v[24:25] op_sel_hi:[1,0]
	s_and_b64 vcc, exec, s[6:7]
	v_lshlrev_b32_e32 v28, 2, v25
	v_lshl_add_u64 v[26:27], v[146:147], 0, s[16:17]
	v_lshlrev_b32_e32 v144, 1, v25
	s_cbranch_vccz .LBB0_1081
	s_lshl_b32 s16, s69, 2
	v_lshl_add_u64 v[30:31], v[142:143], 0, s[16:17]
	v_mov_b32_e32 v29, v145
	v_lshl_add_u64 v[30:31], v[30:31], 0, v[28:29]
	global_store_dwordx4 v[30:31], v[4:7], off sc1
	v_cvt_pk_bf16_f32 v30, v4, v5
	v_cvt_pk_bf16_f32 v31, v6, v7
	v_lshl_add_u64 v[32:33], v[26:27], 0, v[144:145]
	global_store_dwordx2 v[32:33], v[30:31], off sc1
	s_mov_b64 s[46:47], 0
.LBB0_1081:
	v_cndmask_b32_e64 v30, v189, v190, s[4:5]
	s_andn2_b64 vcc, exec, s[46:47]
	v_lshl_add_u64 v[32:33], s[44:45], 0, v[140:141]
	s_cbranch_vccnz .LBB0_1083
	v_pk_mul_f32 v[4:5], v[30:31], v[4:5] op_sel_hi:[0,1]
	v_pk_mul_f32 v[6:7], v[30:31], v[6:7] op_sel_hi:[0,1]
	v_cvt_pk_bf16_f32 v4, v4, v5
	v_cvt_pk_bf16_f32 v5, v6, v7
	v_lshl_add_u64 v[6:7], v[32:33], 0, v[144:145]
	global_store_dwordx2 v[6:7], v[4:5], off sc1
.LBB0_1083:
	v_pk_add_f32 v[4:5], v[22:23], 0 op_sel_hi:[1,0]
	v_pk_add_f32 v[6:7], v[8:9], 0 op_sel_hi:[1,0]
	v_pk_add_f32 v[4:5], v[4:5], v[16:17]
	v_pk_add_f32 v[6:7], v[6:7], v[18:19]
	v_pk_add_f32 v[4:5], v[4:5], v[20:21]
	v_pk_add_f32 v[6:7], v[6:7], v[10:11]
	v_mov_b32_e32 v25, v24
	v_pk_add_f32 v[8:9], v[6:7], v[14:15]
	v_pk_add_f32 v[4:5], v[4:5], v[12:13]
	v_mov_b32_e32 v6, v24
	v_mov_b32_e32 v7, v24
	v_pk_mul_f32 v[6:7], v[4:5], v[6:7]
	v_pk_mul_f32 v[4:5], v[8:9], v[24:25]
	s_andn2_b64 vcc, exec, s[6:7]
	s_mov_b64 s[4:5], -1
	s_cbranch_vccnz .LBB0_1085
	s_lshl_b32 s16, s69, 2
	v_lshl_add_u64 v[8:9], v[142:143], 0, s[16:17]
	v_mov_b32_e32 v29, v145
	v_lshl_add_u64 v[8:9], v[8:9], 0, v[28:29]
	global_store_dwordx4 v[8:9], v[4:7], off offset:32 sc1
	v_cvt_pk_bf16_f32 v8, v4, v5
	v_cvt_pk_bf16_f32 v9, v6, v7
	v_lshl_add_u64 v[10:11], v[26:27], 0, v[144:145]
	s_mov_b64 s[4:5], 0
	global_store_dwordx2 v[10:11], v[8:9], off offset:16 sc1
.LBB0_1085:
	s_andn2_b64 vcc, exec, s[4:5]
	s_cbranch_vccnz .LBB0_1044
	v_pk_mul_f32 v[4:5], v[30:31], v[4:5] op_sel_hi:[0,1]
	v_pk_mul_f32 v[6:7], v[30:31], v[6:7] op_sel_hi:[0,1]
	v_cvt_pk_bf16_f32 v4, v4, v5
	v_cvt_pk_bf16_f32 v5, v6, v7
	v_lshl_add_u64 v[6:7], v[32:33], 0, v[144:145]
	global_store_dwordx2 v[6:7], v[4:5], off offset:16 sc1
	s_branch .LBB0_1044

.LBB0_1589:
	s_or_b64 exec, exec, s[34:35]
	v_lshl_add_u32 v10, s46, 6, v217
	v_ashrrev_i32_e32 v11, 2, v10
	v_and_or_b32 v22, v11, s43, v212
	v_lshrrev_b32_e32 v11, 2, v10
	v_and_or_b32 v11, v11, 16, s45
	v_or_b32_e32 v24, v11, v167
	v_ashrrev_i32_e32 v23, 31, v22
	v_ashrrev_i32_e32 v25, 31, v24
	v_lshlrev_b64 v[14:15], 12, v[22:23]
	v_lshlrev_b64 v[20:21], 2, v[24:25]
	v_lshl_add_u64 v[18:19], s[14:15], 0, v[14:15]
	v_lshl_add_u64 v[14:15], s[20:21], 0, v[20:21]
	s_waitcnt lgkmcnt(0)
	s_barrier
	global_load_dwordx4 v[14:17], v[14:15], off
	v_lshl_add_u64 v[26:27], v[18:19], 0, v[20:21]
	global_load_dwordx4 v[18:21], v[26:27], off
	v_lshl_add_u32 v13, v22, 2, 0
	v_ashrrev_i32_e32 v22, 4, v11
	ds_read_b32 v11, v13 offset:1536
	v_ashrrev_i32_e32 v28, 7, v10
	v_ashrrev_i32_e32 v29, 31, v28
	v_ashrrev_i32_e32 v23, 31, v22
	v_lshlrev_b64 v[28:29], 12, v[28:29]
	s_waitcnt lgkmcnt(0)
	v_fmamk_f32 v11, v11, 0x3a800000, v169
	v_mul_f32_e32 v13, 0x4f800000, v11
	v_cmp_gt_f32_e32 vcc, s44, v11
	v_lshlrev_b64 v[22:23], 6, v[22:23]
	v_lshl_add_u64 v[22:23], v[22:23], 0, v[28:29]
	v_cndmask_b32_e32 v11, v11, v13, vcc
	v_sqrt_f32_e32 v13, v11
	v_or_b32_e32 v24, 8, v24
	v_or_b32_e32 v22, v22, v212
	v_ashrrev_i32_e32 v25, 31, v24
	v_add_u32_e32 v28, -1, v13
	v_add_u32_e32 v29, 1, v13
	v_fma_f32 v30, -v28, v13, v11
	v_fma_f32 v31, -v29, v13, v11
	v_cmp_ge_f32_e64 s[6:7], 0, v30
	v_lshl_add_u64 v[22:23], v[22:23], 4, v[132:133]
	v_lshl_add_u64 v[24:25], v[24:25], 2, s[20:21]
	v_cndmask_b32_e64 v13, v13, v28, s[6:7]
	v_cmp_lt_f32_e64 s[6:7], 0, v31
	s_waitcnt vmcnt(1)
	v_pk_mul_f32 v[8:9], v[8:9], v[16:17]
	v_cndmask_b32_e64 v13, v13, v29, s[6:7]
	v_mul_f32_e32 v28, 0x37800000, v13
	v_cndmask_b32_e32 v13, v13, v28, vcc
	v_cmp_class_f32_e32 vcc, v11, v170
	v_pk_mul_f32 v[6:7], v[6:7], v[14:15]
	s_nop 0
	v_cndmask_b32_e32 v11, v13, v11, vcc
	v_div_scale_f32 v13, s[6:7], v11, v11, 1.0
	v_rcp_f32_e32 v28, v13
	v_div_scale_f32 v29, vcc, 1.0, v11, 1.0
	v_fma_f32 v30, -v13, v28, 1.0
	v_fmac_f32_e32 v28, v30, v28
	v_mul_f32_e32 v30, v29, v28
	v_fma_f32 v31, -v13, v30, v29
	v_fmac_f32_e32 v30, v31, v28
	v_fma_f32 v13, -v13, v30, v29
	v_div_fmas_f32 v13, v13, v28, v30
	v_div_fixup_f32 v28, v13, v11, 1.0
	s_waitcnt vmcnt(0)
	v_pk_fma_f32 v[8:9], v[8:9], v[28:29], v[20:21] op_sel_hi:[1,0,1]
	v_pk_fma_f32 v[6:7], v[6:7], v[28:29], v[18:19] op_sel_hi:[1,0,1]
	v_cvt_pk_bf16_f32 v15, v8, v9
	v_cvt_pk_bf16_f32 v14, v6, v7
	global_store_dwordx4 v[26:27], v[6:9], off sc1
	global_store_dwordx2 v[22:23], v[14:15], off sc1
	global_load_dwordx4 v[14:17], v[24:25], off
	s_nop 0
	global_load_dwordx4 v[18:21], v[26:27], off offset:32
	v_mul_f32_e32 v7, v7, v7
	v_fmac_f32_e32 v7, v6, v6
	v_mul_f32_e32 v6, v9, v9
	v_fmac_f32_e32 v6, v8, v8
	v_add_f32_e32 v6, v7, v6
	s_waitcnt vmcnt(1)
	v_pk_mul_f32 v[4:5], v[4:5], v[16:17]
	v_pk_mul_f32 v[2:3], v[2:3], v[14:15]
	s_waitcnt vmcnt(0)
	v_pk_fma_f32 v[4:5], v[28:29], v[4:5], v[20:21] op_sel_hi:[0,1,1]
	v_pk_fma_f32 v[2:3], v[28:29], v[2:3], v[18:19] op_sel_hi:[0,1,1]
	v_cvt_pk_bf16_f32 v14, v2, v3
	v_cvt_pk_bf16_f32 v15, v4, v5
	global_store_dwordx4 v[26:27], v[2:5], off offset:32 sc1
	global_store_dwordx2 v[22:23], v[14:15], off offset:512 sc1
	s_barrier
	s_getreg_b32 s6, hwreg(HW_REG_HW_ID, 0, 6)
	s_and_b32 s6, s6, 63
	s_lshl_b32 s6, s6, 2
	s_add_i32 s6, s6, 0
	s_add_i32 s6, s6, 0x23e00
	v_mov_b32_e32 v14, s6
	v_mov_b32_e32 v15, s13
	flat_load_dword v11, v[14:15] sc0 sc1
	s_waitcnt vmcnt(0)
	v_mul_f32_e32 v3, v3, v3
	v_fmac_f32_e32 v3, v2, v2
	v_mul_f32_e32 v2, v5, v5
	v_fmac_f32_e32 v2, v4, v4
	v_add_f32_e32 v2, v3, v2
	v_add_f32_e32 v3, v6, v2
	ds_bpermute_b32 v4, v168, v3
	s_waitcnt lgkmcnt(0)
	v_readfirstlane_b32 s6, v11
	s_nop 1
	v_lshl_add_u32 v2, s6, 6, v217
	s_and_saveexec_b64 s[6:7], s[0:1]
	s_cbranch_execz .LBB0_1591
	v_add_f32_e32 v3, v3, v4
	v_lshlrev_b32_e32 v4, 3, v2
	v_and_b32_e32 v4, 0x200, v4
	v_add_u32_e32 v4, 0, v4
	v_and_b32_e32 v5, 0xffffff80, v2
	v_add3_u32 v4, v4, v5, v12
	ds_write_b32 v4, v3

.LBB0_1593:
	s_or_b64 exec, exec, s[6:7]
	v_cmp_gt_i32_e32 vcc, s42, v10
	s_waitcnt lgkmcnt(0)
	s_barrier
	s_and_saveexec_b64 s[6:7], vcc
	s_cbranch_execz .LBB0_1566
	v_lshl_add_u32 v2, v10, 2, 0
	ds_read_b32 v4, v2 offset:1024
	v_lshl_add_u32 v2, v10, 5, s30
	v_ashrrev_i32_e32 v3, 31, v2
	v_lshl_add_u64 v[2:3], v[2:3], 2, s[54:55]
	s_waitcnt lgkmcnt(0)
	global_store_dword v[2:3], v4, off sc1
	s_branch .LBB0_1566

.LBB0_1646:
	s_or_b64 exec, exec, s[12:13]
	v_lshl_add_u64 v[162:163], v[210:211], 2, s[52:53]
	s_mov_b64 s[4:5], 0x1000
	v_lshl_add_u64 v[164:165], v[162:163], 0, s[4:5]
	v_add_co_u32_e32 v162, vcc, 0x1000, v162
	s_waitcnt vmcnt(0) lgkmcnt(0)
	s_barrier
	s_nop 0
	v_addc_co_u32_e32 v163, vcc, 0, v163, vcc
	global_load_dwordx4 v[174:177], v[164:165], off offset:16
	global_load_dwordx4 v[166:169], v[164:165], off offset:512
	global_load_dwordx4 v[178:181], v[162:163], off
	s_nop 0
	global_load_dwordx4 v[162:165], v[164:165], off offset:528
	v_lshl_add_u32 v225, v216, 2, 0
	ds_read_b32 v234, v225 offset:4096
	s_waitcnt vmcnt(0)
	v_lshlrev_b32_e32 v226, 16, v206
	v_and_b32_e32 v227, 0xffff0000, v206
	v_lshlrev_b32_e32 v206, 16, v207
	v_and_b32_e32 v207, 0xffff0000, v207
	v_lshlrev_b32_e32 v228, 16, v208
	v_and_b32_e32 v229, 0xffff0000, v208
	v_lshlrev_b32_e32 v208, 16, v209
	v_and_b32_e32 v209, 0xffff0000, v209
	v_lshlrev_b32_e32 v230, 16, v202
	v_and_b32_e32 v231, 0xffff0000, v202
	v_lshlrev_b32_e32 v202, 16, v203
	v_and_b32_e32 v203, 0xffff0000, v203
	v_lshlrev_b32_e32 v232, 16, v204
	v_and_b32_e32 v233, 0xffff0000, v204
	v_lshlrev_b32_e32 v204, 16, v205
	v_and_b32_e32 v205, 0xffff0000, v205
	v_add_u32_e32 v214, s20, v216
	v_ashrrev_i32_e32 v215, 31, v214
	v_lshlrev_b64 v[236:237], 11, v[214:215]
	s_lshl_b32 s4, s6, 2
	s_mov_b32 s11, 0
	s_ashr_i32 s5, s4, 31
	v_pk_mul_f32 v[128:129], v[128:129], v[176:177]
	v_pk_mul_f32 v[126:127], v[126:127], v[174:175]
	v_pk_mul_f32 v[120:121], v[120:121], v[168:169]
	v_pk_mul_f32 v[118:119], v[118:119], v[166:167]
	v_pk_mul_f32 v[124:125], v[124:125], v[180:181]
	v_pk_mul_f32 v[122:123], v[122:123], v[178:179]
	v_pk_mul_f32 v[116:117], v[116:117], v[164:165]
	v_pk_mul_f32 v[114:115], v[114:115], v[162:163]
	s_waitcnt lgkmcnt(0)
	v_pk_fma_f32 v[126:127], v[126:127], v[234:235], v[228:229] op_sel_hi:[1,0,1]
	v_pk_fma_f32 v[128:129], v[128:129], v[234:235], v[208:209] op_sel_hi:[1,0,1]
	v_pk_fma_f32 v[118:119], v[118:119], v[234:235], v[230:231] op_sel_hi:[1,0,1]
	v_pk_fma_f32 v[120:121], v[120:121], v[234:235], v[202:203] op_sel_hi:[1,0,1]
	v_pk_fma_f32 v[124:125], v[124:125], v[234:235], v[206:207] op_sel_hi:[1,0,1]
	v_pk_fma_f32 v[122:123], v[122:123], v[234:235], v[226:227] op_sel_hi:[1,0,1]
	v_pk_fma_f32 v[202:203], v[114:115], v[234:235], v[232:233] op_sel_hi:[1,0,1]
	v_pk_fma_f32 v[204:205], v[116:117], v[234:235], v[204:205] op_sel_hi:[1,0,1]
	v_mul_f32_e32 v206, v127, v127
	v_mul_f32_e32 v207, v129, v129
	v_mul_f32_e32 v208, v119, v119
	v_mul_f32_e32 v209, v121, v121
	v_mul_f32_e32 v226, v123, v123
	v_mul_f32_e32 v227, v125, v125
	v_cvt_pk_bf16_f32 v114, v122, v123
	v_cvt_pk_bf16_f32 v115, v124, v125
	v_mul_f32_e32 v123, v203, v203
	v_mul_f32_e32 v125, v205, v205
	v_fmac_f32_e32 v206, v126, v126
	v_fmac_f32_e32 v207, v128, v128
	v_fmac_f32_e32 v208, v118, v118
	v_fmac_f32_e32 v209, v120, v120
	v_fmac_f32_e32 v226, v122, v122
	v_fmac_f32_e32 v227, v124, v124
	v_fmac_f32_e32 v123, v202, v202
	v_fmac_f32_e32 v125, v204, v204
	v_cvt_pk_bf16_f32 v116, v126, v127
	v_add_f32_e32 v122, v206, v207
	v_add_f32_e32 v124, v208, v209
	v_add_f32_e32 v126, v226, v227
	v_add_f32_e32 v123, v123, v125
	v_add_f32_e32 v122, v126, v122
	v_add_f32_e32 v123, v124, v123
	v_add_f32_e32 v124, v122, v123
	ds_bpermute_b32 v125, v220, v124
	v_lshl_add_u64 v[122:123], s[62:63], 0, v[236:237]
	v_lshl_add_u64 v[122:123], v[210:211], 1, v[122:123]
	v_cvt_pk_bf16_f32 v117, v128, v129
	global_store_dwordx4 v[122:123], v[114:117], off sc1
	s_waitcnt lgkmcnt(0)
	s_nop 0
	v_add_f32_e32 v114, v124, v125
	ds_bpermute_b32 v115, v221, v114
	v_cvt_pk_bf16_f32 v116, v118, v119
	v_cvt_pk_bf16_f32 v117, v120, v121
	v_cvt_pk_bf16_f32 v118, v202, v203
	v_cvt_pk_bf16_f32 v119, v204, v205
	global_store_dwordx4 v[122:123], v[116:119], off offset:256 sc1
	s_and_saveexec_b64 s[6:7], s[0:1]
	s_cbranch_execz .LBB0_1648
	s_waitcnt lgkmcnt(0)
	v_add_f32_e32 v116, v114, v115
	v_lshlrev_b64 v[114:115], 6, v[214:215]
	v_lshl_add_u64 v[114:115], s[86:87], 0, v[114:115]
	v_lshl_add_u64 v[114:115], s[4:5], 2, v[114:115]
	v_lshl_add_u64 v[114:115], v[114:115], 0, s[10:11]
	global_store_dword v[114:115], v116, off sc1
.LBB0_1648:
	s_or_b64 exec, exec, s[6:7]
	ds_read_b32 v116, v225 offset:4160
	v_lshlrev_b32_e32 v120, 16, v198
	v_and_b32_e32 v121, 0xffff0000, v198
	v_lshlrev_b32_e32 v122, 16, v199
	v_and_b32_e32 v123, 0xffff0000, v199
	v_pk_mul_f32 v[112:113], v[112:113], v[180:181]
	v_pk_mul_f32 v[110:111], v[110:111], v[178:179]
	v_lshlrev_b32_e32 v124, 16, v200
	v_and_b32_e32 v125, 0xffff0000, v200
	v_lshlrev_b32_e32 v126, 16, v201
	v_and_b32_e32 v127, 0xffff0000, v201
	s_waitcnt lgkmcnt(0)
	v_pk_fma_f32 v[112:113], v[112:113], v[116:117], v[122:123] op_sel_hi:[1,0,1]
	v_pk_fma_f32 v[110:111], v[110:111], v[116:117], v[120:121] op_sel_hi:[1,0,1]
	v_pk_mul_f32 v[108:109], v[108:109], v[176:177]
	v_pk_mul_f32 v[106:107], v[106:107], v[174:175]
	v_pk_fma_f32 v[120:121], v[108:109], v[116:117], v[126:127] op_sel_hi:[1,0,1]
	v_pk_fma_f32 v[108:109], v[106:107], v[116:117], v[124:125] op_sel_hi:[1,0,1]
	v_mul_f32_e32 v106, v111, v111
	v_mul_f32_e32 v107, v113, v113
	v_fmac_f32_e32 v106, v110, v110
	v_fmac_f32_e32 v107, v112, v112
	v_add_f32_e32 v106, v106, v107
	v_mul_f32_e32 v107, v109, v109
	v_mul_f32_e32 v117, v121, v121
	v_fmac_f32_e32 v107, v108, v108
	v_fmac_f32_e32 v117, v120, v120
	v_add_f32_e32 v107, v107, v117
	v_add_f32_e32 v117, v106, v107
	v_cvt_pk_bf16_f32 v106, v110, v111
	v_cvt_pk_bf16_f32 v107, v112, v113
	v_lshlrev_b32_e32 v110, 16, v194
	v_and_b32_e32 v111, 0xffff0000, v194
	v_lshlrev_b32_e32 v112, 16, v195
	v_and_b32_e32 v113, 0xffff0000, v195
	v_pk_mul_f32 v[104:105], v[104:105], v[168:169]
	v_pk_mul_f32 v[102:103], v[102:103], v[166:167]
	v_cvt_pk_bf16_f32 v108, v108, v109
	v_cvt_pk_bf16_f32 v109, v120, v121
	v_lshlrev_b32_e32 v120, 16, v196
	v_and_b32_e32 v121, 0xffff0000, v196
	v_pk_fma_f32 v[104:105], v[104:105], v[116:117], v[112:113] op_sel_hi:[1,0,1]
	v_pk_fma_f32 v[102:103], v[102:103], v[116:117], v[110:111] op_sel_hi:[1,0,1]
	v_pk_mul_f32 v[98:99], v[98:99], v[162:163]
	v_lshlrev_b32_e32 v122, 16, v197
	v_and_b32_e32 v123, 0xffff0000, v197
	v_pk_mul_f32 v[100:101], v[100:101], v[164:165]
	v_pk_fma_f32 v[112:113], v[98:99], v[116:117], v[120:121] op_sel_hi:[1,0,1]
	v_mul_f32_e32 v98, v103, v103
	v_mul_f32_e32 v99, v105, v105
	v_pk_fma_f32 v[110:111], v[100:101], v[116:117], v[122:123] op_sel_hi:[1,0,1]
	v_fmac_f32_e32 v98, v102, v102
	v_fmac_f32_e32 v99, v104, v104
	v_add_f32_e32 v98, v98, v99
	v_mul_f32_e32 v99, v113, v113
	v_mul_f32_e32 v100, v111, v111
	v_fmac_f32_e32 v99, v112, v112
	v_fmac_f32_e32 v100, v110, v110
	v_add_f32_e32 v99, v99, v100
	v_add_f32_e32 v98, v98, v99
	v_add_f32_e32 v101, v117, v98
	ds_bpermute_b32 v120, v220, v101
	v_add3_u32 v114, s20, v216, 16
	v_ashrrev_i32_e32 v115, 31, v114
	v_lshlrev_b64 v[118:119], 11, v[114:115]
	v_lshl_add_u64 v[98:99], s[62:63], 0, v[118:119]
	v_lshl_add_u64 v[116:117], v[210:211], 1, v[98:99]
	s_waitcnt lgkmcnt(0)
	v_add_f32_e32 v98, v101, v120
	ds_bpermute_b32 v99, v221, v98
	global_store_dwordx4 v[116:117], v[106:109], off sc1
	v_cvt_pk_bf16_f32 v100, v102, v103
	v_cvt_pk_bf16_f32 v101, v104, v105
	v_cvt_pk_bf16_f32 v102, v112, v113
	v_cvt_pk_bf16_f32 v103, v110, v111
	global_store_dwordx4 v[116:117], v[100:103], off offset:256 sc1
	s_and_saveexec_b64 s[6:7], s[0:1]
	s_cbranch_execz .LBB0_1650
	s_waitcnt lgkmcnt(0)
	v_add_f32_e32 v100, v98, v99
	v_lshlrev_b64 v[98:99], 6, v[114:115]
	v_lshl_add_u64 v[98:99], s[86:87], 0, v[98:99]
	v_lshl_add_u64 v[98:99], s[4:5], 2, v[98:99]
	v_lshl_add_u64 v[98:99], v[98:99], 0, s[10:11]
	global_store_dword v[98:99], v100, off sc1
.LBB0_1650:
	s_or_b64 exec, exec, s[6:7]
	ds_read_b32 v100, v225 offset:4224
	v_lshlrev_b32_e32 v104, 16, v190
	v_and_b32_e32 v105, 0xffff0000, v190
	v_lshlrev_b32_e32 v106, 16, v191
	v_and_b32_e32 v107, 0xffff0000, v191
	v_pk_mul_f32 v[96:97], v[96:97], v[180:181]
	v_pk_mul_f32 v[94:95], v[94:95], v[178:179]
	v_lshlrev_b32_e32 v108, 16, v192
	v_and_b32_e32 v109, 0xffff0000, v192
	v_lshlrev_b32_e32 v110, 16, v193
	v_and_b32_e32 v111, 0xffff0000, v193
	s_waitcnt lgkmcnt(0)
	v_pk_fma_f32 v[96:97], v[96:97], v[100:101], v[106:107] op_sel_hi:[1,0,1]
	v_pk_fma_f32 v[94:95], v[94:95], v[100:101], v[104:105] op_sel_hi:[1,0,1]
	v_pk_mul_f32 v[92:93], v[92:93], v[176:177]
	v_pk_mul_f32 v[90:91], v[90:91], v[174:175]
	v_pk_fma_f32 v[104:105], v[92:93], v[100:101], v[110:111] op_sel_hi:[1,0,1]
	v_pk_fma_f32 v[92:93], v[90:91], v[100:101], v[108:109] op_sel_hi:[1,0,1]
	v_mul_f32_e32 v90, v95, v95
	v_mul_f32_e32 v91, v97, v97
	v_fmac_f32_e32 v90, v94, v94
	v_fmac_f32_e32 v91, v96, v96
	v_add_f32_e32 v90, v90, v91
	v_mul_f32_e32 v91, v93, v93
	v_mul_f32_e32 v101, v105, v105
	v_fmac_f32_e32 v91, v92, v92
	v_fmac_f32_e32 v101, v104, v104
	v_add_f32_e32 v91, v91, v101
	v_add_f32_e32 v101, v90, v91
	v_cvt_pk_bf16_f32 v90, v94, v95
	v_cvt_pk_bf16_f32 v91, v96, v97
	v_lshlrev_b32_e32 v94, 16, v186
	v_and_b32_e32 v95, 0xffff0000, v186
	v_lshlrev_b32_e32 v96, 16, v187
	v_and_b32_e32 v97, 0xffff0000, v187
	v_pk_mul_f32 v[88:89], v[88:89], v[168:169]
	v_pk_mul_f32 v[86:87], v[86:87], v[166:167]
	v_cvt_pk_bf16_f32 v92, v92, v93
	v_cvt_pk_bf16_f32 v93, v104, v105
	v_lshlrev_b32_e32 v104, 16, v188
	v_and_b32_e32 v105, 0xffff0000, v188
	v_pk_fma_f32 v[88:89], v[88:89], v[100:101], v[96:97] op_sel_hi:[1,0,1]
	v_pk_fma_f32 v[86:87], v[86:87], v[100:101], v[94:95] op_sel_hi:[1,0,1]
	v_pk_mul_f32 v[82:83], v[82:83], v[162:163]
	v_lshlrev_b32_e32 v106, 16, v189
	v_and_b32_e32 v107, 0xffff0000, v189
	v_pk_mul_f32 v[84:85], v[84:85], v[164:165]
	v_pk_fma_f32 v[96:97], v[82:83], v[100:101], v[104:105] op_sel_hi:[1,0,1]
	v_mul_f32_e32 v82, v87, v87
	v_mul_f32_e32 v83, v89, v89
	v_pk_fma_f32 v[94:95], v[84:85], v[100:101], v[106:107] op_sel_hi:[1,0,1]
	v_fmac_f32_e32 v82, v86, v86
	v_fmac_f32_e32 v83, v88, v88
	v_add_f32_e32 v82, v82, v83
	v_mul_f32_e32 v83, v97, v97
	v_mul_f32_e32 v84, v95, v95
	v_fmac_f32_e32 v83, v96, v96
	v_fmac_f32_e32 v84, v94, v94
	v_add_f32_e32 v83, v83, v84
	v_add_f32_e32 v82, v82, v83
	v_add_f32_e32 v85, v101, v82
	ds_bpermute_b32 v104, v220, v85
	v_add3_u32 v98, s20, v216, 32
	v_ashrrev_i32_e32 v99, 31, v98
	v_lshlrev_b64 v[102:103], 11, v[98:99]
	v_lshl_add_u64 v[82:83], s[62:63], 0, v[102:103]
	v_lshl_add_u64 v[100:101], v[210:211], 1, v[82:83]
	s_waitcnt lgkmcnt(0)
	v_add_f32_e32 v82, v85, v104
	ds_bpermute_b32 v83, v221, v82
	global_store_dwordx4 v[100:101], v[90:93], off sc1
	v_cvt_pk_bf16_f32 v84, v86, v87
	v_cvt_pk_bf16_f32 v85, v88, v89
	v_cvt_pk_bf16_f32 v86, v96, v97
	v_cvt_pk_bf16_f32 v87, v94, v95
	global_store_dwordx4 v[100:101], v[84:87], off offset:256 sc1
	s_and_saveexec_b64 s[6:7], s[0:1]
	s_cbranch_execz .LBB0_1652
	s_waitcnt lgkmcnt(0)
	v_add_f32_e32 v84, v82, v83
	v_lshlrev_b64 v[82:83], 6, v[98:99]
	v_lshl_add_u64 v[82:83], s[86:87], 0, v[82:83]
	v_lshl_add_u64 v[82:83], s[4:5], 2, v[82:83]
	v_lshl_add_u64 v[82:83], v[82:83], 0, s[10:11]
	global_store_dword v[82:83], v84, off sc1
.LBB0_1652:
	s_or_b64 exec, exec, s[6:7]
	ds_read_b32 v84, v225 offset:4288
	v_lshlrev_b32_e32 v88, 16, v182
	v_and_b32_e32 v89, 0xffff0000, v182
	v_lshlrev_b32_e32 v90, 16, v183
	v_and_b32_e32 v91, 0xffff0000, v183
	v_pk_mul_f32 v[80:81], v[80:81], v[180:181]
	v_pk_mul_f32 v[78:79], v[78:79], v[178:179]
	v_lshlrev_b32_e32 v92, 16, v184
	v_and_b32_e32 v93, 0xffff0000, v184
	v_lshlrev_b32_e32 v94, 16, v185
	v_and_b32_e32 v95, 0xffff0000, v185
	s_waitcnt lgkmcnt(0)
	v_pk_fma_f32 v[80:81], v[80:81], v[84:85], v[90:91] op_sel_hi:[1,0,1]
	v_pk_fma_f32 v[78:79], v[78:79], v[84:85], v[88:89] op_sel_hi:[1,0,1]
	v_pk_mul_f32 v[76:77], v[76:77], v[176:177]
	v_pk_mul_f32 v[74:75], v[74:75], v[174:175]
	v_pk_fma_f32 v[88:89], v[76:77], v[84:85], v[94:95] op_sel_hi:[1,0,1]
	v_pk_fma_f32 v[76:77], v[74:75], v[84:85], v[92:93] op_sel_hi:[1,0,1]
	v_mul_f32_e32 v74, v79, v79
	v_mul_f32_e32 v75, v81, v81
	v_fmac_f32_e32 v74, v78, v78
	v_fmac_f32_e32 v75, v80, v80
	v_add_f32_e32 v74, v74, v75
	v_mul_f32_e32 v75, v77, v77
	v_mul_f32_e32 v85, v89, v89
	v_fmac_f32_e32 v75, v76, v76
	v_fmac_f32_e32 v85, v88, v88
	v_add_f32_e32 v75, v75, v85
	v_add_f32_e32 v85, v74, v75
	v_cvt_pk_bf16_f32 v74, v78, v79
	v_cvt_pk_bf16_f32 v75, v80, v81
	v_lshlrev_b32_e32 v78, 16, v170
	v_and_b32_e32 v79, 0xffff0000, v170
	v_lshlrev_b32_e32 v80, 16, v171
	v_and_b32_e32 v81, 0xffff0000, v171
	v_pk_mul_f32 v[72:73], v[72:73], v[168:169]
	v_pk_mul_f32 v[70:71], v[70:71], v[166:167]
	v_cvt_pk_bf16_f32 v76, v76, v77
	v_cvt_pk_bf16_f32 v77, v88, v89
	v_lshlrev_b32_e32 v88, 16, v172
	v_and_b32_e32 v89, 0xffff0000, v172
	v_pk_fma_f32 v[72:73], v[72:73], v[84:85], v[80:81] op_sel_hi:[1,0,1]
	v_pk_fma_f32 v[70:71], v[70:71], v[84:85], v[78:79] op_sel_hi:[1,0,1]
	v_pk_mul_f32 v[66:67], v[66:67], v[162:163]
	v_lshlrev_b32_e32 v90, 16, v173
	v_and_b32_e32 v91, 0xffff0000, v173
	v_pk_mul_f32 v[68:69], v[68:69], v[164:165]
	v_pk_fma_f32 v[80:81], v[66:67], v[84:85], v[88:89] op_sel_hi:[1,0,1]
	v_mul_f32_e32 v66, v71, v71
	v_mul_f32_e32 v67, v73, v73
	v_pk_fma_f32 v[78:79], v[68:69], v[84:85], v[90:91] op_sel_hi:[1,0,1]
	v_fmac_f32_e32 v66, v70, v70
	v_fmac_f32_e32 v67, v72, v72
	v_add_f32_e32 v66, v66, v67
	v_mul_f32_e32 v67, v81, v81
	v_mul_f32_e32 v68, v79, v79
	v_fmac_f32_e32 v67, v80, v80
	v_fmac_f32_e32 v68, v78, v78
	v_add_f32_e32 v67, v67, v68
	v_add_f32_e32 v66, v66, v67
	v_add_f32_e32 v69, v85, v66
	ds_bpermute_b32 v88, v220, v69
	v_add3_u32 v82, s20, v216, 48
	v_ashrrev_i32_e32 v83, 31, v82
	v_lshlrev_b64 v[86:87], 11, v[82:83]
	v_lshl_add_u64 v[66:67], s[62:63], 0, v[86:87]
	v_lshl_add_u64 v[84:85], v[210:211], 1, v[66:67]
	s_waitcnt lgkmcnt(0)
	v_add_f32_e32 v66, v69, v88
	ds_bpermute_b32 v67, v221, v66
	global_store_dwordx4 v[84:85], v[74:77], off sc1
	v_cvt_pk_bf16_f32 v68, v70, v71
	v_cvt_pk_bf16_f32 v69, v72, v73
	v_cvt_pk_bf16_f32 v70, v80, v81
	v_cvt_pk_bf16_f32 v71, v78, v79
	global_store_dwordx4 v[84:85], v[68:71], off offset:256 sc1
	s_and_saveexec_b64 s[6:7], s[0:1]
	s_cbranch_execz .LBB0_1654
	s_waitcnt lgkmcnt(0)
	v_add_f32_e32 v68, v66, v67
	v_lshlrev_b64 v[66:67], 6, v[82:83]
	v_lshl_add_u64 v[66:67], s[86:87], 0, v[66:67]
	v_lshl_add_u64 v[66:67], s[4:5], 2, v[66:67]
	v_lshl_add_u64 v[66:67], v[66:67], 0, s[10:11]
	global_store_dword v[66:67], v68, off sc1
.LBB0_1654:
	s_or_b64 exec, exec, s[6:7]
	ds_read_b32 v68, v225 offset:4608
	v_lshlrev_b32_e32 v72, 16, v158
	v_and_b32_e32 v73, 0xffff0000, v158
	v_lshlrev_b32_e32 v74, 16, v159
	v_and_b32_e32 v75, 0xffff0000, v159
	v_pk_mul_f32 v[64:65], v[64:65], v[180:181]
	v_pk_mul_f32 v[62:63], v[62:63], v[178:179]
	v_lshlrev_b32_e32 v76, 16, v160
	v_and_b32_e32 v77, 0xffff0000, v160
	v_lshlrev_b32_e32 v78, 16, v161
	v_and_b32_e32 v79, 0xffff0000, v161
	s_waitcnt lgkmcnt(0)
	v_pk_fma_f32 v[64:65], v[64:65], v[68:69], v[74:75] op_sel_hi:[1,0,1]
	v_pk_fma_f32 v[62:63], v[62:63], v[68:69], v[72:73] op_sel_hi:[1,0,1]
	v_pk_mul_f32 v[60:61], v[60:61], v[176:177]
	v_pk_mul_f32 v[58:59], v[58:59], v[174:175]
	v_pk_fma_f32 v[72:73], v[60:61], v[68:69], v[78:79] op_sel_hi:[1,0,1]
	v_pk_fma_f32 v[60:61], v[58:59], v[68:69], v[76:77] op_sel_hi:[1,0,1]
	v_mul_f32_e32 v58, v63, v63
	v_mul_f32_e32 v59, v65, v65
	v_fmac_f32_e32 v58, v62, v62
	v_fmac_f32_e32 v59, v64, v64
	v_add_f32_e32 v58, v58, v59
	v_mul_f32_e32 v59, v61, v61
	v_mul_f32_e32 v69, v73, v73
	v_fmac_f32_e32 v59, v60, v60
	v_fmac_f32_e32 v69, v72, v72
	v_add_f32_e32 v59, v59, v69
	v_add_f32_e32 v69, v58, v59
	v_cvt_pk_bf16_f32 v58, v62, v63
	v_cvt_pk_bf16_f32 v59, v64, v65
	v_lshlrev_b32_e32 v62, 16, v154
	v_and_b32_e32 v63, 0xffff0000, v154
	v_lshlrev_b32_e32 v64, 16, v155
	v_and_b32_e32 v65, 0xffff0000, v155
	v_pk_mul_f32 v[56:57], v[56:57], v[168:169]
	v_pk_mul_f32 v[54:55], v[54:55], v[166:167]
	v_cvt_pk_bf16_f32 v60, v60, v61
	v_cvt_pk_bf16_f32 v61, v72, v73
	v_lshlrev_b32_e32 v72, 16, v156
	v_and_b32_e32 v73, 0xffff0000, v156
	v_pk_fma_f32 v[56:57], v[56:57], v[68:69], v[64:65] op_sel_hi:[1,0,1]
	v_pk_fma_f32 v[54:55], v[54:55], v[68:69], v[62:63] op_sel_hi:[1,0,1]
	v_pk_mul_f32 v[50:51], v[50:51], v[162:163]
	v_lshlrev_b32_e32 v74, 16, v157
	v_and_b32_e32 v75, 0xffff0000, v157
	v_pk_mul_f32 v[52:53], v[52:53], v[164:165]
	v_pk_fma_f32 v[64:65], v[50:51], v[68:69], v[72:73] op_sel_hi:[1,0,1]
	v_mul_f32_e32 v50, v55, v55
	v_mul_f32_e32 v51, v57, v57
	v_pk_fma_f32 v[62:63], v[52:53], v[68:69], v[74:75] op_sel_hi:[1,0,1]
	v_fmac_f32_e32 v50, v54, v54
	v_fmac_f32_e32 v51, v56, v56
	v_add_f32_e32 v50, v50, v51
	v_mul_f32_e32 v51, v65, v65
	v_mul_f32_e32 v52, v63, v63
	v_fmac_f32_e32 v51, v64, v64
	v_fmac_f32_e32 v52, v62, v62
	v_add_f32_e32 v51, v51, v52
	v_add_f32_e32 v50, v50, v51
	v_add_f32_e32 v53, v69, v50
	ds_bpermute_b32 v72, v220, v53
	v_add_u32_e32 v66, 0x80, v214
	v_ashrrev_i32_e32 v67, 31, v66
	v_lshlrev_b64 v[70:71], 11, v[66:67]
	v_lshl_add_u64 v[50:51], s[62:63], 0, v[70:71]
	v_lshl_add_u64 v[68:69], v[210:211], 1, v[50:51]
	s_waitcnt lgkmcnt(0)
	v_add_f32_e32 v50, v53, v72
	ds_bpermute_b32 v51, v221, v50
	global_store_dwordx4 v[68:69], v[58:61], off sc1
	v_cvt_pk_bf16_f32 v52, v54, v55
	v_cvt_pk_bf16_f32 v53, v56, v57
	v_cvt_pk_bf16_f32 v54, v64, v65
	v_cvt_pk_bf16_f32 v55, v62, v63
	global_store_dwordx4 v[68:69], v[52:55], off offset:256 sc1
	s_and_saveexec_b64 s[6:7], s[0:1]
	s_cbranch_execz .LBB0_1656
	s_waitcnt lgkmcnt(0)
	v_add_f32_e32 v52, v50, v51
	v_lshlrev_b64 v[50:51], 6, v[66:67]
	v_lshl_add_u64 v[50:51], s[86:87], 0, v[50:51]
	v_lshl_add_u64 v[50:51], s[4:5], 2, v[50:51]
	v_lshl_add_u64 v[50:51], v[50:51], 0, s[10:11]
	global_store_dword v[50:51], v52, off sc1
.LBB0_1656:
	s_or_b64 exec, exec, s[6:7]
	ds_read_b32 v52, v225 offset:4672
	v_lshlrev_b32_e32 v56, 16, v150
	v_and_b32_e32 v57, 0xffff0000, v150
	v_lshlrev_b32_e32 v58, 16, v151
	v_and_b32_e32 v59, 0xffff0000, v151
	v_pk_mul_f32 v[48:49], v[48:49], v[180:181]
	v_pk_mul_f32 v[46:47], v[46:47], v[178:179]
	v_lshlrev_b32_e32 v60, 16, v152
	v_and_b32_e32 v61, 0xffff0000, v152
	v_lshlrev_b32_e32 v62, 16, v153
	v_and_b32_e32 v63, 0xffff0000, v153
	s_waitcnt lgkmcnt(0)
	v_pk_fma_f32 v[48:49], v[48:49], v[52:53], v[58:59] op_sel_hi:[1,0,1]
	v_pk_fma_f32 v[46:47], v[46:47], v[52:53], v[56:57] op_sel_hi:[1,0,1]
	v_pk_mul_f32 v[44:45], v[44:45], v[176:177]
	v_pk_mul_f32 v[42:43], v[42:43], v[174:175]
	v_pk_fma_f32 v[56:57], v[44:45], v[52:53], v[62:63] op_sel_hi:[1,0,1]
	v_pk_fma_f32 v[44:45], v[42:43], v[52:53], v[60:61] op_sel_hi:[1,0,1]
	v_mul_f32_e32 v42, v47, v47
	v_mul_f32_e32 v43, v49, v49
	v_fmac_f32_e32 v42, v46, v46
	v_fmac_f32_e32 v43, v48, v48
	v_add_f32_e32 v42, v42, v43
	v_mul_f32_e32 v43, v45, v45
	v_mul_f32_e32 v53, v57, v57
	v_fmac_f32_e32 v43, v44, v44
	v_fmac_f32_e32 v53, v56, v56
	v_add_f32_e32 v43, v43, v53
	v_add_f32_e32 v53, v42, v43
	v_cvt_pk_bf16_f32 v42, v46, v47
	v_cvt_pk_bf16_f32 v43, v48, v49
	v_lshlrev_b32_e32 v46, 16, v146
	v_and_b32_e32 v47, 0xffff0000, v146
	v_lshlrev_b32_e32 v48, 16, v147
	v_and_b32_e32 v49, 0xffff0000, v147
	v_pk_mul_f32 v[40:41], v[40:41], v[168:169]
	v_pk_mul_f32 v[38:39], v[38:39], v[166:167]
	v_cvt_pk_bf16_f32 v44, v44, v45
	v_cvt_pk_bf16_f32 v45, v56, v57
	v_lshlrev_b32_e32 v56, 16, v148
	v_and_b32_e32 v57, 0xffff0000, v148
	v_pk_fma_f32 v[40:41], v[40:41], v[52:53], v[48:49] op_sel_hi:[1,0,1]
	v_pk_fma_f32 v[38:39], v[38:39], v[52:53], v[46:47] op_sel_hi:[1,0,1]
	v_pk_mul_f32 v[34:35], v[34:35], v[162:163]
	v_lshlrev_b32_e32 v58, 16, v149
	v_and_b32_e32 v59, 0xffff0000, v149
	v_pk_mul_f32 v[36:37], v[36:37], v[164:165]
	v_pk_fma_f32 v[48:49], v[34:35], v[52:53], v[56:57] op_sel_hi:[1,0,1]
	v_mul_f32_e32 v34, v39, v39
	v_mul_f32_e32 v35, v41, v41
	v_pk_fma_f32 v[46:47], v[36:37], v[52:53], v[58:59] op_sel_hi:[1,0,1]
	v_fmac_f32_e32 v34, v38, v38
	v_fmac_f32_e32 v35, v40, v40
	v_add_f32_e32 v34, v34, v35
	v_mul_f32_e32 v35, v49, v49
	v_mul_f32_e32 v36, v47, v47
	v_fmac_f32_e32 v35, v48, v48
	v_fmac_f32_e32 v36, v46, v46
	v_add_f32_e32 v35, v35, v36
	v_add_f32_e32 v34, v34, v35
	v_add_f32_e32 v37, v53, v34
	ds_bpermute_b32 v56, v220, v37
	v_add_u32_e32 v50, 0x90, v214
	v_ashrrev_i32_e32 v51, 31, v50
	v_lshlrev_b64 v[54:55], 11, v[50:51]
	v_lshl_add_u64 v[34:35], s[62:63], 0, v[54:55]
	v_lshl_add_u64 v[52:53], v[210:211], 1, v[34:35]
	s_waitcnt lgkmcnt(0)
	v_add_f32_e32 v34, v37, v56
	ds_bpermute_b32 v35, v221, v34
	global_store_dwordx4 v[52:53], v[42:45], off sc1
	v_cvt_pk_bf16_f32 v36, v38, v39
	v_cvt_pk_bf16_f32 v37, v40, v41
	v_cvt_pk_bf16_f32 v38, v48, v49
	v_cvt_pk_bf16_f32 v39, v46, v47
	global_store_dwordx4 v[52:53], v[36:39], off offset:256 sc1
	s_and_saveexec_b64 s[6:7], s[0:1]
	s_cbranch_execz .LBB0_1658
	s_waitcnt lgkmcnt(0)
	v_add_f32_e32 v36, v34, v35
	v_lshlrev_b64 v[34:35], 6, v[50:51]
	v_lshl_add_u64 v[34:35], s[86:87], 0, v[34:35]
	v_lshl_add_u64 v[34:35], s[4:5], 2, v[34:35]
	v_lshl_add_u64 v[34:35], v[34:35], 0, s[10:11]
	global_store_dword v[34:35], v36, off sc1
.LBB0_1658:
	s_or_b64 exec, exec, s[6:7]
	ds_read_b32 v36, v225 offset:4736
	v_lshlrev_b32_e32 v40, 16, v142
	v_and_b32_e32 v41, 0xffff0000, v142
	v_lshlrev_b32_e32 v42, 16, v143
	v_and_b32_e32 v43, 0xffff0000, v143
	v_pk_mul_f32 v[32:33], v[32:33], v[180:181]
	v_pk_mul_f32 v[30:31], v[30:31], v[178:179]
	v_lshlrev_b32_e32 v44, 16, v144
	v_and_b32_e32 v45, 0xffff0000, v144
	v_lshlrev_b32_e32 v46, 16, v145
	v_and_b32_e32 v47, 0xffff0000, v145
	s_waitcnt lgkmcnt(0)
	v_pk_fma_f32 v[32:33], v[32:33], v[36:37], v[42:43] op_sel_hi:[1,0,1]
	v_pk_fma_f32 v[30:31], v[30:31], v[36:37], v[40:41] op_sel_hi:[1,0,1]
	v_pk_mul_f32 v[28:29], v[28:29], v[176:177]
	v_pk_mul_f32 v[26:27], v[26:27], v[174:175]
	v_pk_fma_f32 v[40:41], v[28:29], v[36:37], v[46:47] op_sel_hi:[1,0,1]
	v_pk_fma_f32 v[28:29], v[26:27], v[36:37], v[44:45] op_sel_hi:[1,0,1]
	v_mul_f32_e32 v26, v31, v31
	v_mul_f32_e32 v27, v33, v33
	v_fmac_f32_e32 v26, v30, v30
	v_fmac_f32_e32 v27, v32, v32
	v_add_f32_e32 v26, v26, v27
	v_mul_f32_e32 v27, v29, v29
	v_mul_f32_e32 v37, v41, v41
	v_fmac_f32_e32 v27, v28, v28
	v_fmac_f32_e32 v37, v40, v40
	v_add_f32_e32 v27, v27, v37
	v_add_f32_e32 v37, v26, v27
	v_cvt_pk_bf16_f32 v26, v30, v31
	v_cvt_pk_bf16_f32 v27, v32, v33
	v_lshlrev_b32_e32 v30, 16, v138
	v_and_b32_e32 v31, 0xffff0000, v138
	v_lshlrev_b32_e32 v32, 16, v139
	v_and_b32_e32 v33, 0xffff0000, v139
	v_pk_mul_f32 v[24:25], v[24:25], v[168:169]
	v_pk_mul_f32 v[22:23], v[22:23], v[166:167]
	v_cvt_pk_bf16_f32 v28, v28, v29
	v_cvt_pk_bf16_f32 v29, v40, v41
	v_lshlrev_b32_e32 v40, 16, v140
	v_and_b32_e32 v41, 0xffff0000, v140
	v_pk_fma_f32 v[24:25], v[24:25], v[36:37], v[32:33] op_sel_hi:[1,0,1]
	v_pk_fma_f32 v[22:23], v[22:23], v[36:37], v[30:31] op_sel_hi:[1,0,1]
	v_pk_mul_f32 v[18:19], v[18:19], v[162:163]
	v_lshlrev_b32_e32 v42, 16, v141
	v_and_b32_e32 v43, 0xffff0000, v141
	v_pk_mul_f32 v[20:21], v[20:21], v[164:165]
	v_pk_fma_f32 v[32:33], v[18:19], v[36:37], v[40:41] op_sel_hi:[1,0,1]
	v_mul_f32_e32 v18, v23, v23
	v_mul_f32_e32 v19, v25, v25
	v_pk_fma_f32 v[30:31], v[20:21], v[36:37], v[42:43] op_sel_hi:[1,0,1]
	v_fmac_f32_e32 v18, v22, v22
	v_fmac_f32_e32 v19, v24, v24
	v_add_f32_e32 v18, v18, v19
	v_mul_f32_e32 v19, v33, v33
	v_mul_f32_e32 v20, v31, v31
	v_fmac_f32_e32 v19, v32, v32
	v_fmac_f32_e32 v20, v30, v30
	v_add_f32_e32 v19, v19, v20
	v_add_f32_e32 v18, v18, v19
	v_add_f32_e32 v21, v37, v18
	ds_bpermute_b32 v40, v220, v21
	v_add_u32_e32 v34, 0xa0, v214
	v_ashrrev_i32_e32 v35, 31, v34
	v_lshlrev_b64 v[38:39], 11, v[34:35]
	v_lshl_add_u64 v[18:19], s[62:63], 0, v[38:39]
	v_lshl_add_u64 v[36:37], v[210:211], 1, v[18:19]
	s_waitcnt lgkmcnt(0)
	v_add_f32_e32 v18, v21, v40
	ds_bpermute_b32 v19, v221, v18
	global_store_dwordx4 v[36:37], v[26:29], off sc1
	v_cvt_pk_bf16_f32 v20, v22, v23
	v_cvt_pk_bf16_f32 v21, v24, v25
	v_cvt_pk_bf16_f32 v22, v32, v33
	v_cvt_pk_bf16_f32 v23, v30, v31
	global_store_dwordx4 v[36:37], v[20:23], off offset:256 sc1
	s_and_saveexec_b64 s[6:7], s[0:1]
	s_cbranch_execz .LBB0_1660
	s_waitcnt lgkmcnt(0)
	v_add_f32_e32 v20, v18, v19
	v_lshlrev_b64 v[18:19], 6, v[34:35]
	v_lshl_add_u64 v[18:19], s[86:87], 0, v[18:19]
	v_lshl_add_u64 v[18:19], s[4:5], 2, v[18:19]
	v_lshl_add_u64 v[18:19], v[18:19], 0, s[10:11]
	global_store_dword v[18:19], v20, off sc1
.LBB0_1660:
	s_or_b64 exec, exec, s[6:7]
	ds_read_b32 v20, v225 offset:4800
	v_lshlrev_b32_e32 v24, 16, v134
	v_and_b32_e32 v25, 0xffff0000, v134
	v_lshlrev_b32_e32 v26, 16, v135
	v_and_b32_e32 v27, 0xffff0000, v135
	v_pk_mul_f32 v[16:17], v[16:17], v[180:181]
	v_pk_mul_f32 v[14:15], v[14:15], v[178:179]
	v_lshlrev_b32_e32 v28, 16, v136
	v_and_b32_e32 v29, 0xffff0000, v136
	v_lshlrev_b32_e32 v30, 16, v137
	v_and_b32_e32 v31, 0xffff0000, v137
	s_waitcnt lgkmcnt(0)
	v_pk_fma_f32 v[16:17], v[16:17], v[20:21], v[26:27] op_sel_hi:[1,0,1]
	v_pk_fma_f32 v[14:15], v[14:15], v[20:21], v[24:25] op_sel_hi:[1,0,1]
	v_pk_mul_f32 v[12:13], v[12:13], v[176:177]
	v_pk_mul_f32 v[10:11], v[10:11], v[174:175]
	v_pk_fma_f32 v[24:25], v[12:13], v[20:21], v[30:31] op_sel_hi:[1,0,1]
	v_pk_fma_f32 v[12:13], v[10:11], v[20:21], v[28:29] op_sel_hi:[1,0,1]
	v_mul_f32_e32 v10, v15, v15
	v_mul_f32_e32 v11, v17, v17
	v_fmac_f32_e32 v10, v14, v14
	v_fmac_f32_e32 v11, v16, v16
	v_add_f32_e32 v10, v10, v11
	v_mul_f32_e32 v11, v13, v13
	v_mul_f32_e32 v21, v25, v25
	v_fmac_f32_e32 v11, v12, v12
	v_fmac_f32_e32 v21, v24, v24
	v_add_f32_e32 v11, v11, v21
	v_add_f32_e32 v21, v10, v11
	v_cvt_pk_bf16_f32 v10, v14, v15
	v_cvt_pk_bf16_f32 v11, v16, v17
	v_lshlrev_b32_e32 v14, 16, v130
	v_and_b32_e32 v15, 0xffff0000, v130
	v_lshlrev_b32_e32 v16, 16, v131
	v_and_b32_e32 v17, 0xffff0000, v131
	v_pk_mul_f32 v[8:9], v[8:9], v[168:169]
	v_pk_mul_f32 v[6:7], v[6:7], v[166:167]
	v_cvt_pk_bf16_f32 v12, v12, v13
	v_cvt_pk_bf16_f32 v13, v24, v25
	v_lshlrev_b32_e32 v24, 16, v132
	v_and_b32_e32 v25, 0xffff0000, v132
	v_pk_fma_f32 v[8:9], v[8:9], v[20:21], v[16:17] op_sel_hi:[1,0,1]
	v_pk_fma_f32 v[6:7], v[6:7], v[20:21], v[14:15] op_sel_hi:[1,0,1]
	v_pk_mul_f32 v[2:3], v[2:3], v[162:163]
	v_lshlrev_b32_e32 v26, 16, v133
	v_and_b32_e32 v27, 0xffff0000, v133
	v_pk_mul_f32 v[4:5], v[4:5], v[164:165]
	v_pk_fma_f32 v[16:17], v[2:3], v[20:21], v[24:25] op_sel_hi:[1,0,1]
	v_mul_f32_e32 v2, v7, v7
	v_mul_f32_e32 v3, v9, v9
	v_pk_fma_f32 v[14:15], v[4:5], v[20:21], v[26:27] op_sel_hi:[1,0,1]
	v_fmac_f32_e32 v2, v6, v6
	v_fmac_f32_e32 v3, v8, v8
	v_add_f32_e32 v2, v2, v3
	v_mul_f32_e32 v3, v17, v17
	v_mul_f32_e32 v4, v15, v15
	v_fmac_f32_e32 v3, v16, v16
	v_fmac_f32_e32 v4, v14, v14
	v_add_f32_e32 v3, v3, v4
	v_add_f32_e32 v2, v2, v3
	v_add_f32_e32 v5, v21, v2
	ds_bpermute_b32 v24, v220, v5
	v_add_u32_e32 v18, 0xb0, v214
	v_ashrrev_i32_e32 v19, 31, v18
	v_lshlrev_b64 v[22:23], 11, v[18:19]
	v_lshl_add_u64 v[2:3], s[62:63], 0, v[22:23]
	v_lshl_add_u64 v[20:21], v[210:211], 1, v[2:3]
	s_waitcnt lgkmcnt(0)
	v_add_f32_e32 v2, v5, v24
	ds_bpermute_b32 v3, v221, v2
	global_store_dwordx4 v[20:21], v[10:13], off sc1
	v_cvt_pk_bf16_f32 v4, v6, v7
	v_cvt_pk_bf16_f32 v5, v8, v9
	v_cvt_pk_bf16_f32 v6, v16, v17
	v_cvt_pk_bf16_f32 v7, v14, v15
	global_store_dwordx4 v[20:21], v[4:7], off offset:256 sc1
	s_and_saveexec_b64 s[6:7], s[0:1]
	s_cbranch_execz .LBB0_1662
	s_waitcnt lgkmcnt(0)
	v_add_f32_e32 v4, v2, v3
	v_lshlrev_b64 v[2:3], 6, v[18:19]
	v_lshl_add_u64 v[2:3], s[86:87], 0, v[2:3]
	v_lshl_add_u64 v[2:3], s[4:5], 2, v[2:3]
	v_lshl_add_u64 v[2:3], v[2:3], 0, s[10:11]
	global_store_dword v[2:3], v4, off sc1

.LBB0_1696:
	s_andn2_saveexec_b64 s[8:9], s[8:9]
	s_cbranch_execz .LBB0_1716
	s_mov_b64 s[8:9], exec
	s_waitcnt lgkmcnt(0)
	s_waitcnt vmcnt(0)
	v_mbcnt_lo_u32_b32 v3, s8, 0
	v_mbcnt_hi_u32_b32 v3, s9, v3
	v_cmp_eq_u32_e32 vcc, 0, v3
	s_and_saveexec_b64 s[10:11], vcc
	s_cbranch_execz .LBB0_1699
	s_bcnt1_i32_b64 s3, s[8:9]
	v_mov_b32_e32 v4, 0x43000
	v_mov_b32_e32 v5, s3
	global_atomic_add v4, v4, v5, s[82:83] offset:1024 sc0

.LBB0_1720:
	v_lshlrev_b32_e32 v34, 14, v173
	v_lshlrev_b32_e32 v35, 12, v140
	v_add3_u32 v34, v168, v34, v35
	s_barrier
	s_nop 4
	ds_write2st64_b32 v34, v2, v3 offset1:1
	ds_write2st64_b32 v34, v4, v5 offset0:2 offset1:3
	ds_write2st64_b32 v34, v6, v7 offset0:4 offset1:5
	ds_write2st64_b32 v34, v8, v9 offset0:6 offset1:7
	ds_write2st64_b32 v34, v10, v11 offset0:8 offset1:9
	ds_write2st64_b32 v34, v12, v13 offset0:10 offset1:11
	ds_write2st64_b32 v34, v14, v15 offset0:12 offset1:13
	ds_write2st64_b32 v34, v16, v17 offset0:14 offset1:15
	ds_write2st64_b32 v34, v18, v19 offset0:16 offset1:17
	ds_write2st64_b32 v34, v20, v21 offset0:18 offset1:19
	ds_write2st64_b32 v34, v22, v23 offset0:20 offset1:21
	ds_write2st64_b32 v34, v24, v25 offset0:22 offset1:23
	ds_write2st64_b32 v34, v26, v27 offset0:24 offset1:25
	ds_write2st64_b32 v34, v28, v29 offset0:26 offset1:27
	ds_write2st64_b32 v34, v30, v31 offset0:28 offset1:29
	ds_write2st64_b32 v34, v32, v33 offset0:30 offset1:31
	v_lshrrev_b32_e32 v3, 3, v138
	v_lshlrev_b32_e32 v2, 3, v172
	v_and_b32_e32 v3, 0xfffff0, v3
	v_and_or_b32 v2, v2, 8, v3
	v_lshl_add_u32 v2, v2, 8, v168
	s_waitcnt lgkmcnt(0)
	s_barrier
	ds_read2st64_b32 v[34:35], v2 offset1:1
	ds_read2st64_b32 v[36:37], v2 offset0:2 offset1:3
	ds_read2st64_b32 v[38:39], v2 offset0:4 offset1:5
	ds_read2st64_b32 v[40:41], v2 offset0:6 offset1:7
	ds_read2st64_b32 v[42:43], v2 offset0:64 offset1:65
	ds_read2st64_b32 v[44:45], v2 offset0:66 offset1:67
	ds_read2st64_b32 v[46:47], v2 offset0:68 offset1:69
	ds_read2st64_b32 v[48:49], v2 offset0:70 offset1:71
	ds_read2st64_b32 v[50:51], v2 offset0:128 offset1:129
	ds_read2st64_b32 v[52:53], v2 offset0:130 offset1:131
	ds_read2st64_b32 v[54:55], v2 offset0:132 offset1:133
	ds_read2st64_b32 v[56:57], v2 offset0:134 offset1:135
	ds_read2st64_b32 v[58:59], v2 offset0:192 offset1:193
	ds_read2st64_b32 v[60:61], v2 offset0:194 offset1:195
	ds_read2st64_b32 v[62:63], v2 offset0:196 offset1:197
	ds_read2st64_b32 v[64:65], v2 offset0:198 offset1:199
	s_waitcnt lgkmcnt(0)
	s_barrier
	global_load_dwordx4 v[2:5], v[130:131], off
	global_load_dwordx4 v[6:9], v[130:131], off offset:16
	global_load_dwordx4 v[10:13], v[130:131], off offset:32
	global_load_dwordx4 v[14:17], v[130:131], off offset:48
	global_load_dwordx4 v[18:21], v[130:131], off offset:64
	global_load_dwordx4 v[22:25], v[130:131], off offset:80
	global_load_dwordx4 v[26:29], v[130:131], off offset:96
	global_load_dwordx4 v[30:33], v[130:131], off offset:112
	s_add_i32 s23, s23, s88
	s_add_i32 s16, s16, s17
	s_cmpk_gt_i32 s23, 0x7f
	s_waitcnt vmcnt(7)
	v_mov_b32_e32 v66, v2
	s_waitcnt vmcnt(6)
	v_mov_b32_e32 v67, v6
	v_mov_b32_e32 v6, v3
	v_mov_b32_e32 v2, v4
	v_mov_b32_e32 v3, v8
	v_mov_b32_e32 v8, v5
	s_waitcnt vmcnt(5)
	v_mov_b32_e32 v4, v11
	v_mov_b32_e32 v5, v12
	v_mov_b32_e32 v11, v13
	v_pk_add_f32 v[6:7], v[66:67], v[6:7]
	v_pk_add_f32 v[2:3], v[2:3], v[8:9]
	v_pk_add_f32 v[4:5], v[4:5], v[10:11]
	v_pk_add_f32 v[2:3], v[6:7], v[2:3]
	v_pk_add_f32 v[4:5], v[4:5], v[4:5] op_sel:[0,1] op_sel_hi:[1,0]
	v_add_f32_e32 v2, 0, v2
	s_waitcnt vmcnt(4)
	v_add_f32_e32 v12, v14, v15
	v_add_f32_e32 v14, v16, v17
	s_waitcnt vmcnt(3)
	v_mov_b32_e32 v17, v18
	v_mov_b32_e32 v13, v20
	v_mov_b32_e32 v15, v21
	v_mov_b32_e32 v5, v19
	v_add_f32_e32 v16, v2, v3
	s_waitcnt vmcnt(2)
	v_mov_b32_e32 v20, v23
	v_mov_b32_e32 v21, v24
	v_mov_b32_e32 v23, v25
	v_pk_add_f32 v[8:9], v[12:13], v[14:15]
	v_pk_add_f32 v[2:3], v[16:17], v[4:5]
	v_pk_add_f32 v[10:11], v[20:21], v[22:23]
	v_pk_add_f32 v[2:3], v[2:3], v[8:9]
	v_pk_add_f32 v[6:7], v[10:11], v[10:11] op_sel:[0,1] op_sel_hi:[1,0]
	v_pk_add_f32 v[2:3], v[2:3], v[2:3] op_sel:[0,1] op_sel_hi:[1,0]
	s_waitcnt vmcnt(1)
	v_add_f32_e32 v24, v26, v27
	v_add_f32_e32 v18, v28, v29
	s_waitcnt vmcnt(0)
	v_mov_b32_e32 v25, v32
	v_mov_b32_e32 v7, v31
	v_mov_b32_e32 v3, v30
	v_mov_b32_e32 v19, v33
	v_pk_add_f32 v[2:3], v[2:3], v[6:7]
	v_pk_add_f32 v[4:5], v[24:25], v[18:19]
	v_pk_add_f32 v[8:9], v[36:37], 0 op_sel_hi:[1,0]
	v_pk_add_f32 v[2:3], v[2:3], v[4:5]
	v_pk_add_f32 v[8:9], v[8:9], v[44:45]
	v_add_f32_e32 v2, v2, v3
	v_fmamk_f32 v2, v2, 0x3a800000, v170
	v_mul_f32_e32 v3, 0x4f800000, v2
	v_cmp_gt_f32_e32 vcc, s22, v2
	v_pk_add_f32 v[8:9], v[8:9], v[52:53]
	s_nop 0
	v_cndmask_b32_e32 v2, v2, v3, vcc
	v_sqrt_f32_e32 v3, v2
	v_pk_add_f32 v[8:9], v[8:9], v[60:61]
	v_add_u32_e32 v4, -1, v3
	v_fma_f32 v5, -v4, v3, v2
	v_cmp_ge_f32_e64 s[0:1], 0, v5
	v_add_u32_e32 v5, 1, v3
	v_max_f32_e32 v9, 0, v9
	v_cndmask_b32_e64 v4, v3, v4, s[0:1]
	v_fma_f32 v3, -v5, v3, v2
	v_cmp_lt_f32_e64 s[0:1], 0, v3
	v_max_f32_e32 v8, 0, v8
	s_nop 0
	v_cndmask_b32_e64 v3, v4, v5, s[0:1]
	v_mul_f32_e32 v4, 0x37800000, v3
	v_cndmask_b32_e32 v3, v3, v4, vcc
	v_cmp_class_f32_e32 vcc, v2, v171
	s_nop 1
	v_cndmask_b32_e32 v2, v3, v2, vcc
	v_div_scale_f32 v3, s[0:1], v2, v2, 1.0
	v_rcp_f32_e32 v4, v3
	s_nop 0
	v_fma_f32 v5, -v3, v4, 1.0
	v_fmac_f32_e32 v4, v5, v4
	v_div_scale_f32 v5, vcc, 1.0, v2, 1.0
	v_mul_f32_e32 v6, v5, v4
	v_fma_f32 v7, -v3, v6, v5
	v_fmac_f32_e32 v6, v7, v4
	v_fma_f32 v3, -v3, v6, v5
	v_div_fmas_f32 v3, v3, v4, v6
	v_pk_add_f32 v[6:7], v[34:35], 0 op_sel_hi:[1,0]
	v_div_fixup_f32 v2, v3, v2, 1.0
	v_pk_add_f32 v[6:7], v[6:7], v[42:43]
	v_or_b32_e32 v3, s24, v169
	v_pk_add_f32 v[6:7], v[6:7], v[50:51]
	v_ashrrev_i32_e32 v4, 4, v3
	v_pk_add_f32 v[6:7], v[6:7], v[58:59]
	v_ashrrev_i32_e32 v5, 31, v4
	v_max_f32_e32 v7, 0, v7
	v_max_f32_e32 v6, 0, v6
	v_pk_mul_f32 v[6:7], v[6:7], v[2:3] op_sel_hi:[1,0]
	v_pk_mul_f32 v[8:9], v[8:9], v[2:3] op_sel_hi:[1,0]
	v_pk_mul_f32 v[6:7], v[6:7], v[6:7]
	v_pk_mul_f32 v[8:9], v[8:9], v[8:9]
	v_lshlrev_b64 v[4:5], 10, v[4:5]
	v_cvt_pk_bf16_f32 v6, v6, v7
	v_cvt_pk_bf16_f32 v7, v8, v9
	v_lshl_add_u64 v[4:5], v[134:135], 0, v[4:5]
	global_store_dwordx2 v[4:5], v[6:7], off sc1
	v_pk_add_f32 v[6:7], v[38:39], 0 op_sel_hi:[1,0]
	v_pk_add_f32 v[8:9], v[40:41], 0 op_sel_hi:[1,0]
	v_pk_add_f32 v[6:7], v[6:7], v[46:47]
	v_pk_add_f32 v[8:9], v[8:9], v[48:49]
	v_pk_add_f32 v[6:7], v[6:7], v[54:55]
	v_pk_add_f32 v[8:9], v[8:9], v[56:57]
	v_pk_add_f32 v[6:7], v[6:7], v[62:63]
	v_pk_add_f32 v[8:9], v[8:9], v[64:65]
	v_max_f32_e32 v7, 0, v7
	v_max_f32_e32 v6, 0, v6
	v_max_f32_e32 v9, 0, v9
	v_max_f32_e32 v8, 0, v8
	v_pk_mul_f32 v[6:7], v[6:7], v[2:3] op_sel_hi:[1,0]
	v_pk_mul_f32 v[2:3], v[8:9], v[2:3] op_sel_hi:[1,0]
	v_pk_mul_f32 v[6:7], v[6:7], v[6:7]
	v_pk_mul_f32 v[2:3], v[2:3], v[2:3]
	v_cvt_pk_bf16_f32 v6, v6, v7
	v_cvt_pk_bf16_f32 v7, v2, v3
	global_store_dwordx2 v[4:5], v[6:7], off offset:512 sc1
	s_cbranch_scc1 .LBB0_1726
